# GEMM k-loops: complementary schedules for co-resident blocks (b<256: reads,DMA,ladder; b>=256: reads,ladder,DMA), role in new SGPR s100 (on v_m11)
# speedup vs baseline: 1.0061x; 1.0061x over previous
_Z4mega6Paramsii:
	s_load_dwordx4 s[60:63], s[0:1], 0xb0
	s_mov_b32 s88, s2
	s_lshr_b32 s100, s2, 8
	s_add_u32 s2, s0, 0xb8
	v_writelane_b32 v253, s0, 0
	s_addc_u32 s3, s1, 0
	s_nop 0
	v_writelane_b32 v253, s1, 1
	v_writelane_b32 v253, s2, 2
	s_waitcnt lgkmcnt(0)
	s_sub_i32 s0, s61, s60
	s_cmp_lt_i32 s0, 2
	v_writelane_b32 v253, s3, 3
	s_cbranch_scc1 .LBB0_7
	v_and_b32_e32 v1, 0x3ff, v0
	v_cmp_eq_u32_e32 vcc, 0, v1
	s_and_saveexec_b64 s[0:1], vcc
	s_cbranch_execz .LBB0_3
	v_mov_b32_e32 v2, 0
	v_mov_b32_e32 v3, v2
	v_mov_b32_e32 v4, v2
	v_mov_b32_e32 v5, v2
	v_mov_b32_e32 v1, 0x12000
	ds_write_b128 v1, v[2:5]

.LBB0_30:
	s_mul_i32 s44, s43, 0x6000
	s_add_i32 s45, s44, 0xffffa000
	s_cmp_gt_i32 s43, 0
	s_waitcnt vmcnt(6)
	s_cselect_b32 s45, s45, 0xc000
	s_waitcnt lgkmcnt(0)
	s_barrier
	s_setprio 2
	v_add3_u32 v0, s44, v177, v176
	v_add_u32_e32 v0, s55, v0
	v_add3_u32 v212, s44, v178, v176
	ds_read_b128 v[196:199], v212 offset:8192
	ds_read_b128 v[180:183], v0
	ds_read_b128 v[184:187], v0 offset:1024
	ds_read_b128 v[188:191], v0 offset:2048
	ds_read_b128 v[192:195], v0 offset:3072
	ds_read_b128 v[200:203], v212 offset:9216
	ds_read_b128 v[204:207], v212 offset:10240
	ds_read_b128 v[208:211], v212 offset:11264
	ds_read_b128 v[216:219], v212 offset:12288
	ds_read_b128 v[226:229], v212 offset:13312
	ds_read_b128 v[230:233], v212 offset:14336
	ds_read_b128 v[234:237], v212 offset:15360
	s_cmp_eq_u32 s100, 0
	s_cbranch_scc0 .Lmy_re_0
	v_lshl_add_u64 v[212:213], v[174:175], 0, s[12:13]
	v_lshl_add_u64 v[212:213], v[162:163], 1, v[212:213]
	s_add_i32 s68, s45, s42
	s_mov_b32 m0, s68
	s_nop 0
	global_load_lds_dwordx4 v[212:213], off
	v_lshl_add_u64 v[212:213], v[174:175], 0, s[12:13]
	v_lshl_add_u64 v[212:213], v[164:165], 1, v[212:213]
	s_add_i32 s68, s45, s40
	s_mov_b32 m0, s68
	s_nop 0
	global_load_lds_dwordx4 v[212:213], off
	s_add_i32 s45, s41, s45
	v_lshl_add_u64 v[212:213], v[172:173], 0, s[12:13]
	s_mov_b32 m0, s45
	s_nop 0
	global_load_lds_dwordx4 v[212:213], off
	v_lshl_add_u64 v[212:213], v[170:171], 0, s[12:13]
	s_add_i32 s68, s45, 0x400
	s_mov_b32 m0, s68
	s_nop 0
	global_load_lds_dwordx4 v[212:213], off
	v_lshl_add_u64 v[212:213], v[168:169], 0, s[12:13]
	s_add_i32 s68, s45, 0x800
	s_mov_b32 m0, s68
	s_nop 0
	global_load_lds_dwordx4 v[212:213], off
	s_addk_i32 s45, 0xc00
	v_lshl_add_u64 v[212:213], v[166:167], 0, s[12:13]
	s_mov_b32 m0, s45
	s_nop 0
	global_load_lds_dwordx4 v[212:213], off
.Lmy_re_0:
	s_setprio 0
	s_waitcnt lgkmcnt(10)
	v_mfma_f32_16x16x32_bf16 v[34:37], v[196:199], v[180:183], v[34:37]
	s_waitcnt lgkmcnt(9)
	v_mfma_f32_16x16x32_bf16 v[38:41], v[196:199], v[184:187], v[38:41]
	s_waitcnt lgkmcnt(8)
	v_mfma_f32_16x16x32_bf16 v[42:45], v[196:199], v[188:191], v[42:45]
	s_waitcnt lgkmcnt(7)
	v_mfma_f32_16x16x32_bf16 v[46:49], v[196:199], v[192:195], v[46:49]
	s_waitcnt lgkmcnt(6)
	v_mfma_f32_16x16x32_bf16 v[50:53], v[200:203], v[180:183], v[50:53]
	v_mfma_f32_16x16x32_bf16 v[54:57], v[200:203], v[184:187], v[54:57]
	v_mfma_f32_16x16x32_bf16 v[58:61], v[200:203], v[188:191], v[58:61]
	v_mfma_f32_16x16x32_bf16 v[62:65], v[200:203], v[192:195], v[62:65]
	s_waitcnt lgkmcnt(5)
	v_mfma_f32_16x16x32_bf16 v[66:69], v[204:207], v[180:183], v[66:69]
	v_mfma_f32_16x16x32_bf16 v[70:73], v[204:207], v[184:187], v[70:73]
	v_mfma_f32_16x16x32_bf16 v[74:77], v[204:207], v[188:191], v[74:77]
	v_mfma_f32_16x16x32_bf16 v[78:81], v[204:207], v[192:195], v[78:81]
	s_waitcnt lgkmcnt(4)
	v_mfma_f32_16x16x32_bf16 v[82:85], v[208:211], v[180:183], v[82:85]
	v_mfma_f32_16x16x32_bf16 v[86:89], v[208:211], v[184:187], v[86:89]
	v_mfma_f32_16x16x32_bf16 v[90:93], v[208:211], v[188:191], v[90:93]
	v_mfma_f32_16x16x32_bf16 v[94:97], v[208:211], v[192:195], v[94:97]
	s_waitcnt lgkmcnt(3)
	v_mfma_f32_16x16x32_bf16 v[98:101], v[216:219], v[180:183], v[98:101]
	v_mfma_f32_16x16x32_bf16 v[102:105], v[216:219], v[184:187], v[102:105]
	v_mfma_f32_16x16x32_bf16 v[106:109], v[216:219], v[188:191], v[106:109]
	v_mfma_f32_16x16x32_bf16 v[110:113], v[216:219], v[192:195], v[110:113]
	s_waitcnt lgkmcnt(2)
	v_mfma_f32_16x16x32_bf16 v[114:117], v[226:229], v[180:183], v[114:117]
	v_mfma_f32_16x16x32_bf16 v[118:121], v[226:229], v[184:187], v[118:121]
	v_mfma_f32_16x16x32_bf16 v[122:125], v[226:229], v[188:191], v[122:125]
	v_mfma_f32_16x16x32_bf16 v[126:129], v[226:229], v[192:195], v[126:129]
	s_waitcnt lgkmcnt(1)
	v_mfma_f32_16x16x32_bf16 v[130:133], v[230:233], v[180:183], v[130:133]
	v_mfma_f32_16x16x32_bf16 v[134:137], v[230:233], v[184:187], v[134:137]
	v_mfma_f32_16x16x32_bf16 v[138:141], v[230:233], v[188:191], v[138:141]
	v_mfma_f32_16x16x32_bf16 v[142:145], v[230:233], v[192:195], v[142:145]
	s_waitcnt lgkmcnt(0)
	v_mfma_f32_16x16x32_bf16 v[146:149], v[234:237], v[180:183], v[146:149]
	v_mfma_f32_16x16x32_bf16 v[150:153], v[234:237], v[184:187], v[150:153]
	v_mfma_f32_16x16x32_bf16 v[154:157], v[234:237], v[188:191], v[154:157]
	v_mfma_f32_16x16x32_bf16 v[158:161], v[234:237], v[192:195], v[158:161]
	s_cmp_eq_u32 s100, 0
	s_cbranch_scc1 .Lmy_rl_0
	s_setprio 2
	v_lshl_add_u64 v[212:213], v[174:175], 0, s[12:13]
	v_lshl_add_u64 v[212:213], v[162:163], 1, v[212:213]
	s_add_i32 s68, s45, s42
	s_mov_b32 m0, s68
	s_nop 0
	global_load_lds_dwordx4 v[212:213], off
	v_lshl_add_u64 v[212:213], v[174:175], 0, s[12:13]
	v_lshl_add_u64 v[212:213], v[164:165], 1, v[212:213]
	s_add_i32 s68, s45, s40
	s_mov_b32 m0, s68
	s_nop 0
	global_load_lds_dwordx4 v[212:213], off
	s_add_i32 s45, s41, s45
	v_lshl_add_u64 v[212:213], v[172:173], 0, s[12:13]
	s_mov_b32 m0, s45
	s_nop 0
	global_load_lds_dwordx4 v[212:213], off
	v_lshl_add_u64 v[212:213], v[170:171], 0, s[12:13]
	s_add_i32 s68, s45, 0x400
	s_mov_b32 m0, s68
	s_nop 0
	global_load_lds_dwordx4 v[212:213], off
	v_lshl_add_u64 v[212:213], v[168:169], 0, s[12:13]
	s_add_i32 s68, s45, 0x800
	s_mov_b32 m0, s68
	s_nop 0
	global_load_lds_dwordx4 v[212:213], off
	s_addk_i32 s45, 0xc00
	v_lshl_add_u64 v[212:213], v[166:167], 0, s[12:13]
	s_mov_b32 m0, s45
	s_nop 0
	global_load_lds_dwordx4 v[212:213], off
.Lmy_rl_0:
	s_add_i32 s44, s43, 1
	s_cmp_lg_u32 s43, 2
	s_cselect_b32 s43, s44, 0
	s_add_u32 s12, s12, 64
	s_addc_u32 s13, s13, 0
	s_cmpk_eq_i32 s12, 0x780
	s_cbranch_scc0 .LBB0_30
	s_waitcnt vmcnt(6)
	v_mov_b32_e32 v162, v23
	v_mov_b32_e32 v163, v24
	v_mov_b32_e32 v23, v25
	v_mov_b32_e32 v164, v7
	v_mov_b32_e32 v165, v8
	v_pk_add_f32 v[22:23], v[162:163], v[22:23]
	v_mov_b32_e32 v7, v9
	v_pk_add_f32 v[6:7], v[164:165], v[6:7]
	v_add_f32_e32 v0, v22, v23
	v_add_f32_e32 v0, v0, v6
	v_add_f32_e32 v0, v0, v7
	v_fmamk_f32 v0, v0, 0x3a800000, v250
	s_mov_b32 s12, 0x800000
	s_waitcnt vmcnt(4)
	v_mov_b32_e32 v166, v19
	v_mov_b32_e32 v167, v20
	v_mov_b32_e32 v168, v3
	v_mul_f32_e32 v3, 0x4b800000, v0
	v_cmp_gt_f32_e32 vcc, s12, v0
	v_mov_b32_e32 v19, v21
	v_mov_b32_e32 v169, v4
	v_cndmask_b32_e32 v0, v0, v3, vcc
	v_pk_add_f32 v[6:7], v[166:167], v[18:19]
	v_mov_b32_e32 v3, v5
	v_pk_add_f32 v[2:3], v[168:169], v[2:3]
	v_add_f32_e32 v4, v6, v7
	v_add_f32_e32 v2, v4, v2
	v_add_f32_e32 v2, v2, v3
	v_fmamk_f32 v2, v2, 0x3a800000, v250
	v_mul_f32_e32 v3, 0x4b800000, v2
	v_cmp_gt_f32_e64 s[40:41], s12, v2
	s_waitcnt vmcnt(2)
	v_mov_b32_e32 v170, v27
	v_mov_b32_e32 v171, v28
	v_cndmask_b32_e64 v2, v2, v3, s[40:41]
	v_mov_b32_e32 v27, v29
	v_mov_b32_e32 v172, v11
	v_mov_b32_e32 v173, v12
	v_rsq_f32_e32 v179, v2
	v_pk_add_f32 v[2:3], v[170:171], v[26:27]
	v_mov_b32_e32 v11, v13
	v_pk_add_f32 v[4:5], v[172:173], v[10:11]
	v_add_f32_e32 v2, v2, v3
	v_add_f32_e32 v2, v2, v4
	v_add_f32_e32 v2, v2, v5
	v_fmamk_f32 v2, v2, 0x3a800000, v250
	v_mul_f32_e32 v3, 0x4b800000, v2
	v_cmp_gt_f32_e64 s[42:43], s12, v2
	s_waitcnt vmcnt(0)
	v_mov_b32_e32 v174, v31
	v_mov_b32_e32 v175, v32
	v_cndmask_b32_e64 v2, v2, v3, s[42:43]
	v_mov_b32_e32 v31, v33
	v_mov_b32_e32 v180, v15
	v_mov_b32_e32 v181, v16
	v_rsq_f32_e32 v182, v2
	v_pk_add_f32 v[2:3], v[174:175], v[30:31]
	v_mov_b32_e32 v15, v17
	v_pk_add_f32 v[4:5], v[180:181], v[14:15]
	v_add_f32_e32 v2, v2, v3
	v_add_f32_e32 v2, v2, v4
	v_add_f32_e32 v2, v2, v5
	v_fmamk_f32 v2, v2, 0x3a800000, v250
	v_mul_f32_e32 v3, 0x4b800000, v2
	v_cmp_gt_f32_e64 s[44:45], s12, v2
	s_waitcnt vmcnt(6)
	v_add_u32_e32 v183, v178, v176
	s_waitcnt lgkmcnt(0)
	s_barrier
	v_cndmask_b32_e64 v2, v2, v3, s[44:45]
	v_rsq_f32_e32 v180, v2
	ds_read_b128 v[2:5], v183 offset:15360
	ds_read_b128 v[6:9], v183 offset:14336
	ds_read_b128 v[10:13], v183 offset:13312
	ds_read_b128 v[14:17], v183 offset:12288
	ds_read_b128 v[18:21], v183 offset:11264
	ds_read_b128 v[22:25], v183 offset:10240
	ds_read_b128 v[26:29], v183 offset:9216
	ds_read_b128 v[30:33], v183 offset:8192
	v_add3_u32 v178, s55, v177, v176
	ds_read_b128 v[162:165], v178 offset:3072
	ds_read_b128 v[166:169], v178 offset:2048
	ds_read_b128 v[170:173], v178 offset:1024
	ds_read_b128 v[174:177], v178
	v_rsq_f32_e32 v0, v0
	v_mul_f32_e32 v184, 0x45800000, v179
	v_mul_f32_e32 v185, 0x45800000, v182
	v_mul_f32_e32 v186, 0x45800000, v180
	v_mul_f32_e32 v181, 0x45800000, v0
	s_waitcnt lgkmcnt(0)
	v_mfma_f32_16x16x32_bf16 v[34:37], v[30:33], v[174:177], v[34:37]
	v_mfma_f32_16x16x32_bf16 v[38:41], v[30:33], v[170:173], v[38:41]
	v_mfma_f32_16x16x32_bf16 v[42:45], v[30:33], v[166:169], v[42:45]
	v_mfma_f32_16x16x32_bf16 v[30:33], v[30:33], v[162:165], v[46:49]
	v_mfma_f32_16x16x32_bf16 v[46:49], v[26:29], v[174:177], v[50:53]
	v_mfma_f32_16x16x32_bf16 v[50:53], v[26:29], v[170:173], v[54:57]
	v_mfma_f32_16x16x32_bf16 v[54:57], v[26:29], v[166:169], v[58:61]
	v_mfma_f32_16x16x32_bf16 v[58:61], v[26:29], v[162:165], v[62:65]
	v_mfma_f32_16x16x32_bf16 v[62:65], v[22:25], v[174:177], v[66:69]
	v_mfma_f32_16x16x32_bf16 v[66:69], v[22:25], v[170:173], v[70:73]
	v_mfma_f32_16x16x32_bf16 v[70:73], v[22:25], v[166:169], v[74:77]
	v_mfma_f32_16x16x32_bf16 v[74:77], v[22:25], v[162:165], v[78:81]
	v_mfma_f32_16x16x32_bf16 v[78:81], v[18:21], v[174:177], v[82:85]
	v_mfma_f32_16x16x32_bf16 v[82:85], v[18:21], v[170:173], v[86:89]
	v_mfma_f32_16x16x32_bf16 v[86:89], v[18:21], v[166:169], v[90:93]
	v_mfma_f32_16x16x32_bf16 v[18:21], v[18:21], v[162:165], v[94:97]
	v_mfma_f32_16x16x32_bf16 v[90:93], v[14:17], v[174:177], v[98:101]
	v_mfma_f32_16x16x32_bf16 v[94:97], v[14:17], v[170:173], v[102:105]
	v_mfma_f32_16x16x32_bf16 v[98:101], v[14:17], v[166:169], v[106:109]
	v_mfma_f32_16x16x32_bf16 v[14:17], v[14:17], v[162:165], v[110:113]
	v_mfma_f32_16x16x32_bf16 v[102:105], v[10:13], v[174:177], v[114:117]
	v_mfma_f32_16x16x32_bf16 v[106:109], v[10:13], v[170:173], v[118:121]
	v_mfma_f32_16x16x32_bf16 v[110:113], v[10:13], v[166:169], v[122:125]
	v_mfma_f32_16x16x32_bf16 v[10:13], v[10:13], v[162:165], v[126:129]
	v_mfma_f32_16x16x32_bf16 v[114:117], v[6:9], v[174:177], v[130:133]
	v_mfma_f32_16x16x32_bf16 v[118:121], v[6:9], v[170:173], v[134:137]
	v_mfma_f32_16x16x32_bf16 v[122:125], v[6:9], v[166:169], v[138:141]
	v_mfma_f32_16x16x32_bf16 v[6:9], v[6:9], v[162:165], v[142:145]
	v_mfma_f32_16x16x32_bf16 v[126:129], v[2:5], v[174:177], v[146:149]
	v_mfma_f32_16x16x32_bf16 v[130:133], v[2:5], v[170:173], v[150:153]
	v_mfma_f32_16x16x32_bf16 v[134:137], v[2:5], v[166:169], v[154:157]
	v_mfma_f32_16x16x32_bf16 v[2:5], v[2:5], v[162:165], v[158:161]
	s_waitcnt vmcnt(0)
	v_cndmask_b32_e32 v26, v0, v181, vcc
	v_cndmask_b32_e64 v24, v179, v184, s[40:41]
	v_cndmask_b32_e64 v22, v182, v185, s[42:43]
	v_cndmask_b32_e64 v0, v180, v186, s[44:45]
	s_waitcnt lgkmcnt(0)
	s_barrier
	ds_read_b128 v[138:141], v178 offset:24576
	ds_read_b128 v[142:145], v178 offset:25600
	ds_read_b128 v[146:149], v178 offset:26624
	ds_read_b128 v[150:153], v178 offset:27648
	ds_read_b128 v[154:157], v183 offset:32768
	ds_read_b128 v[158:161], v183 offset:33792
	ds_read_b128 v[162:165], v183 offset:34816
	ds_read_b128 v[166:169], v183 offset:35840
	ds_read_b128 v[170:173], v183 offset:36864
	ds_read_b128 v[174:177], v183 offset:37888
	ds_read_b128 v[178:181], v183 offset:38912
	ds_read_b128 v[182:185], v183 offset:39936
	s_waitcnt lgkmcnt(7)
	v_mfma_f32_16x16x32_bf16 v[34:37], v[154:157], v[138:141], v[34:37]
	v_mfma_f32_16x16x32_bf16 v[38:41], v[154:157], v[142:145], v[38:41]
	v_mfma_f32_16x16x32_bf16 v[42:45], v[154:157], v[146:149], v[42:45]
	v_mfma_f32_16x16x32_bf16 v[28:31], v[154:157], v[150:153], v[30:33]
	s_waitcnt lgkmcnt(6)
	v_mfma_f32_16x16x32_bf16 v[46:49], v[158:161], v[138:141], v[46:49]
	v_mfma_f32_16x16x32_bf16 v[50:53], v[158:161], v[142:145], v[50:53]
	v_mfma_f32_16x16x32_bf16 v[54:57], v[158:161], v[146:149], v[54:57]
	v_mfma_f32_16x16x32_bf16 v[58:61], v[158:161], v[150:153], v[58:61]
	s_waitcnt lgkmcnt(5)
	v_mfma_f32_16x16x32_bf16 v[62:65], v[162:165], v[138:141], v[62:65]
	v_mfma_f32_16x16x32_bf16 v[66:69], v[162:165], v[142:145], v[66:69]
	v_mfma_f32_16x16x32_bf16 v[70:73], v[162:165], v[146:149], v[70:73]
	v_mfma_f32_16x16x32_bf16 v[74:77], v[162:165], v[150:153], v[74:77]
	s_waitcnt lgkmcnt(4)
	v_mfma_f32_16x16x32_bf16 v[78:81], v[166:169], v[138:141], v[78:81]
	v_mfma_f32_16x16x32_bf16 v[82:85], v[166:169], v[142:145], v[82:85]
	v_mfma_f32_16x16x32_bf16 v[86:89], v[166:169], v[146:149], v[86:89]
	v_mfma_f32_16x16x32_bf16 v[154:157], v[166:169], v[150:153], v[18:21]
	s_waitcnt lgkmcnt(3)
	v_mfma_f32_16x16x32_bf16 v[90:93], v[170:173], v[138:141], v[90:93]
	v_mfma_f32_16x16x32_bf16 v[94:97], v[170:173], v[142:145], v[94:97]
	v_mfma_f32_16x16x32_bf16 v[98:101], v[170:173], v[146:149], v[98:101]
	v_mfma_f32_16x16x32_bf16 v[158:161], v[170:173], v[150:153], v[14:17]
	s_waitcnt lgkmcnt(2)
	v_mfma_f32_16x16x32_bf16 v[102:105], v[174:177], v[138:141], v[102:105]
	v_mfma_f32_16x16x32_bf16 v[106:109], v[174:177], v[142:145], v[106:109]
	v_mfma_f32_16x16x32_bf16 v[110:113], v[174:177], v[146:149], v[110:113]
	v_mfma_f32_16x16x32_bf16 v[162:165], v[174:177], v[150:153], v[10:13]
	s_waitcnt lgkmcnt(1)
	v_mfma_f32_16x16x32_bf16 v[114:117], v[178:181], v[138:141], v[114:117]
	v_mfma_f32_16x16x32_bf16 v[118:121], v[178:181], v[142:145], v[118:121]
	v_mfma_f32_16x16x32_bf16 v[122:125], v[178:181], v[146:149], v[122:125]
	v_mfma_f32_16x16x32_bf16 v[18:21], v[178:181], v[150:153], v[6:9]
	s_waitcnt lgkmcnt(0)
	v_mfma_f32_16x16x32_bf16 v[14:17], v[182:185], v[138:141], v[126:129]
	v_mfma_f32_16x16x32_bf16 v[10:13], v[182:185], v[142:145], v[130:133]
	v_mfma_f32_16x16x32_bf16 v[6:9], v[182:185], v[146:149], v[134:137]
	v_mfma_f32_16x16x32_bf16 v[2:5], v[182:185], v[150:153], v[2:5]
	v_mov_b32_e32 v23, v224
	s_movk_i32 s12, 0x210
	v_lshrrev_b32_e32 v32, 1, v23
	v_and_b32_e32 v27, 0x7fffff80, v23
	v_and_b32_e32 v32, 24, v32
	v_and_b32_e32 v25, 0x4f, v23
	v_lshl_or_b32 v27, v27, 1, v32
	v_pk_mul_f32 v[32:33], v[26:27], v[34:35] op_sel_hi:[0,1]
	v_pk_mul_f32 v[34:35], v[26:27], v[36:37] op_sel_hi:[0,1]
	v_mad_u32_u24 v25, v25, s12, v27
	v_cvt_pk_bf16_f32 v32, v32, v33
	v_cvt_pk_bf16_f32 v33, v34, v35
	v_pk_mul_f32 v[34:35], v[24:25], v[38:39] op_sel_hi:[0,1]
	v_pk_mul_f32 v[36:37], v[24:25], v[40:41] op_sel_hi:[0,1]
	v_cvt_pk_bf16_f32 v34, v34, v35
	v_cvt_pk_bf16_f32 v35, v36, v37
	v_pk_mul_f32 v[36:37], v[22:23], v[42:43] op_sel_hi:[0,1]
	v_pk_mul_f32 v[38:39], v[22:23], v[44:45] op_sel_hi:[0,1]
	v_pk_mul_f32 v[28:29], v[0:1], v[28:29] op_sel_hi:[0,1]
	v_pk_mul_f32 v[30:31], v[0:1], v[30:31] op_sel_hi:[0,1]
	v_cvt_pk_bf16_f32 v36, v36, v37
	v_cvt_pk_bf16_f32 v37, v38, v39
	v_cvt_pk_bf16_f32 v28, v28, v29
	v_cvt_pk_bf16_f32 v29, v30, v31
	v_pk_mul_f32 v[30:31], v[26:27], v[46:47] op_sel_hi:[0,1]
	v_pk_mul_f32 v[38:39], v[26:27], v[48:49] op_sel_hi:[0,1]
	v_cvt_pk_bf16_f32 v30, v30, v31
	v_cvt_pk_bf16_f32 v31, v38, v39
	s_barrier
	ds_write2_b64 v25, v[32:33], v[30:31] offset1:4
	v_pk_mul_f32 v[30:31], v[24:25], v[50:51] op_sel_hi:[0,1]
	v_pk_mul_f32 v[32:33], v[24:25], v[52:53] op_sel_hi:[0,1]
	v_cvt_pk_bf16_f32 v30, v30, v31
	v_cvt_pk_bf16_f32 v31, v32, v33
	v_add_u32_e32 v27, 0x2000, v25
	ds_write2_b64 v27, v[34:35], v[30:31] offset0:32 offset1:36
	v_pk_mul_f32 v[30:31], v[22:23], v[54:55] op_sel_hi:[0,1]
	v_pk_mul_f32 v[32:33], v[22:23], v[56:57] op_sel_hi:[0,1]
	v_cvt_pk_bf16_f32 v30, v30, v31
	v_cvt_pk_bf16_f32 v31, v32, v33
	v_add_u32_e32 v40, 0x4000, v25
	ds_write2_b64 v40, v[36:37], v[30:31] offset0:64 offset1:68
	v_pk_mul_f32 v[30:31], v[0:1], v[58:59] op_sel_hi:[0,1]
	v_pk_mul_f32 v[32:33], v[0:1], v[60:61] op_sel_hi:[0,1]
	v_cvt_pk_bf16_f32 v30, v30, v31
	v_cvt_pk_bf16_f32 v31, v32, v33
	v_add_u32_e32 v41, 0x6000, v25
	ds_write2_b64 v41, v[28:29], v[30:31] offset0:96 offset1:100
	v_pk_mul_f32 v[28:29], v[26:27], v[62:63] op_sel_hi:[0,1]
	v_pk_mul_f32 v[30:31], v[26:27], v[64:65] op_sel_hi:[0,1]
	v_cvt_pk_bf16_f32 v28, v28, v29
	v_cvt_pk_bf16_f32 v29, v30, v31
	v_pk_mul_f32 v[30:31], v[24:25], v[66:67] op_sel_hi:[0,1]
	v_pk_mul_f32 v[32:33], v[24:25], v[68:69] op_sel_hi:[0,1]
	v_cvt_pk_bf16_f32 v30, v30, v31
	v_cvt_pk_bf16_f32 v31, v32, v33
	v_pk_mul_f32 v[32:33], v[22:23], v[70:71] op_sel_hi:[0,1]
	v_pk_mul_f32 v[34:35], v[22:23], v[72:73] op_sel_hi:[0,1]
	v_cvt_pk_bf16_f32 v32, v32, v33
	v_cvt_pk_bf16_f32 v33, v34, v35
	v_pk_mul_f32 v[34:35], v[0:1], v[74:75] op_sel_hi:[0,1]
	v_pk_mul_f32 v[36:37], v[0:1], v[76:77] op_sel_hi:[0,1]
	v_cvt_pk_bf16_f32 v34, v34, v35
	v_cvt_pk_bf16_f32 v35, v36, v37
	v_pk_mul_f32 v[36:37], v[26:27], v[78:79] op_sel_hi:[0,1]
	v_pk_mul_f32 v[38:39], v[26:27], v[80:81] op_sel_hi:[0,1]
	v_cvt_pk_bf16_f32 v36, v36, v37
	v_cvt_pk_bf16_f32 v37, v38, v39
	ds_write2_b64 v25, v[28:29], v[36:37] offset0:8 offset1:12
	v_pk_mul_f32 v[28:29], v[24:25], v[82:83] op_sel_hi:[0,1]
	v_pk_mul_f32 v[36:37], v[24:25], v[84:85] op_sel_hi:[0,1]
	v_cvt_pk_bf16_f32 v28, v28, v29
	v_cvt_pk_bf16_f32 v29, v36, v37
	ds_write2_b64 v27, v[30:31], v[28:29] offset0:40 offset1:44
	v_pk_mul_f32 v[28:29], v[22:23], v[86:87] op_sel_hi:[0,1]
	v_pk_mul_f32 v[30:31], v[22:23], v[88:89] op_sel_hi:[0,1]
	v_cvt_pk_bf16_f32 v28, v28, v29
	v_cvt_pk_bf16_f32 v29, v30, v31
	ds_write2_b64 v40, v[32:33], v[28:29] offset0:72 offset1:76
	v_pk_mul_f32 v[28:29], v[0:1], v[154:155] op_sel_hi:[0,1]
	v_pk_mul_f32 v[30:31], v[0:1], v[156:157] op_sel_hi:[0,1]
	v_cvt_pk_bf16_f32 v28, v28, v29
	v_cvt_pk_bf16_f32 v29, v30, v31
	ds_write2_b64 v41, v[34:35], v[28:29] offset0:104 offset1:108
	v_pk_mul_f32 v[28:29], v[26:27], v[90:91] op_sel_hi:[0,1]
	v_pk_mul_f32 v[30:31], v[26:27], v[92:93] op_sel_hi:[0,1]
	v_cvt_pk_bf16_f32 v28, v28, v29
	v_cvt_pk_bf16_f32 v29, v30, v31
	v_pk_mul_f32 v[30:31], v[24:25], v[94:95] op_sel_hi:[0,1]
	v_pk_mul_f32 v[32:33], v[24:25], v[96:97] op_sel_hi:[0,1]
	v_cvt_pk_bf16_f32 v30, v30, v31
	v_cvt_pk_bf16_f32 v31, v32, v33
	v_pk_mul_f32 v[32:33], v[22:23], v[98:99] op_sel_hi:[0,1]
	v_pk_mul_f32 v[34:35], v[22:23], v[100:101] op_sel_hi:[0,1]
	v_cvt_pk_bf16_f32 v32, v32, v33
	v_cvt_pk_bf16_f32 v33, v34, v35
	v_pk_mul_f32 v[34:35], v[0:1], v[158:159] op_sel_hi:[0,1]
	v_pk_mul_f32 v[36:37], v[0:1], v[160:161] op_sel_hi:[0,1]
	v_cvt_pk_bf16_f32 v34, v34, v35
	v_cvt_pk_bf16_f32 v35, v36, v37
	v_pk_mul_f32 v[36:37], v[26:27], v[102:103] op_sel_hi:[0,1]
	v_pk_mul_f32 v[38:39], v[26:27], v[104:105] op_sel_hi:[0,1]
	v_cvt_pk_bf16_f32 v36, v36, v37
	v_cvt_pk_bf16_f32 v37, v38, v39
	ds_write2_b64 v25, v[28:29], v[36:37] offset0:16 offset1:20
	v_pk_mul_f32 v[28:29], v[24:25], v[106:107] op_sel_hi:[0,1]
	v_pk_mul_f32 v[36:37], v[24:25], v[108:109] op_sel_hi:[0,1]
	v_cvt_pk_bf16_f32 v28, v28, v29
	v_cvt_pk_bf16_f32 v29, v36, v37
	ds_write2_b64 v27, v[30:31], v[28:29] offset0:48 offset1:52
	v_pk_mul_f32 v[28:29], v[22:23], v[110:111] op_sel_hi:[0,1]
	v_pk_mul_f32 v[30:31], v[22:23], v[112:113] op_sel_hi:[0,1]
	v_cvt_pk_bf16_f32 v28, v28, v29
	v_cvt_pk_bf16_f32 v29, v30, v31
	ds_write2_b64 v40, v[32:33], v[28:29] offset0:80 offset1:84
	v_pk_mul_f32 v[28:29], v[0:1], v[162:163] op_sel_hi:[0,1]
	v_pk_mul_f32 v[30:31], v[0:1], v[164:165] op_sel_hi:[0,1]
	v_cvt_pk_bf16_f32 v28, v28, v29
	v_cvt_pk_bf16_f32 v29, v30, v31
	ds_write2_b64 v41, v[34:35], v[28:29] offset0:112 offset1:116
	v_pk_mul_f32 v[28:29], v[26:27], v[114:115] op_sel_hi:[0,1]
	v_pk_mul_f32 v[30:31], v[26:27], v[116:117] op_sel_hi:[0,1]
	v_pk_mul_f32 v[18:19], v[0:1], v[18:19] op_sel_hi:[0,1]
	v_pk_mul_f32 v[20:21], v[0:1], v[20:21] op_sel_hi:[0,1]
	v_pk_mul_f32 v[2:3], v[0:1], v[2:3] op_sel_hi:[0,1]
	v_pk_mul_f32 v[4:5], v[0:1], v[4:5] op_sel_hi:[0,1]
	v_lshlrev_b32_e32 v0, 3, v23
	v_cvt_pk_bf16_f32 v28, v28, v29
	v_cvt_pk_bf16_f32 v29, v30, v31
	v_pk_mul_f32 v[30:31], v[24:25], v[118:119] op_sel_hi:[0,1]
	v_pk_mul_f32 v[32:33], v[24:25], v[120:121] op_sel_hi:[0,1]
	v_cvt_pk_bf16_f32 v18, v18, v19
	v_cvt_pk_bf16_f32 v19, v20, v21
	v_cvt_pk_bf16_f32 v2, v2, v3
	v_cvt_pk_bf16_f32 v3, v4, v5
	v_and_b32_e32 v0, 0xf8, v0
	v_cvt_pk_bf16_f32 v30, v30, v31
	v_cvt_pk_bf16_f32 v31, v32, v33
	v_pk_mul_f32 v[32:33], v[22:23], v[122:123] op_sel_hi:[0,1]
	v_pk_mul_f32 v[34:35], v[22:23], v[124:125] op_sel_hi:[0,1]
	v_pk_mul_f32 v[14:15], v[26:27], v[14:15] op_sel_hi:[0,1]
	v_pk_mul_f32 v[16:17], v[26:27], v[16:17] op_sel_hi:[0,1]
	v_pk_mul_f32 v[10:11], v[24:25], v[10:11] op_sel_hi:[0,1]
	v_pk_mul_f32 v[12:13], v[24:25], v[12:13] op_sel_hi:[0,1]
	v_pk_mul_f32 v[6:7], v[22:23], v[6:7] op_sel_hi:[0,1]
	v_pk_mul_f32 v[8:9], v[22:23], v[8:9] op_sel_hi:[0,1]
	ds_write2_b64 v41, v[18:19], v[2:3] offset0:120 offset1:124
	v_or_b32_e32 v2, s54, v0
	s_movk_i32 s12, 0x400
	v_cvt_pk_bf16_f32 v32, v32, v33
	v_cvt_pk_bf16_f32 v33, v34, v35
	v_cvt_pk_bf16_f32 v14, v14, v15
	v_cvt_pk_bf16_f32 v15, v16, v17
	v_cvt_pk_bf16_f32 v10, v10, v11
	v_cvt_pk_bf16_f32 v11, v12, v13
	v_cvt_pk_bf16_f32 v6, v6, v7
	v_cvt_pk_bf16_f32 v7, v8, v9
	v_cmp_gt_i32_e32 vcc, s12, v2
	ds_write2_b64 v25, v[28:29], v[14:15] offset0:24 offset1:28
	ds_write2_b64 v27, v[30:31], v[10:11] offset0:56 offset1:60
	ds_write2_b64 v40, v[32:33], v[6:7] offset0:88 offset1:92
	s_waitcnt lgkmcnt(0)
	s_barrier
	s_and_saveexec_b64 s[12:13], vcc
	s_cbranch_execz .LBB0_28
	v_ashrrev_i32_e32 v8, 5, v23
	v_lshlrev_b32_e32 v0, 1, v0
	s_movk_i32 s40, 0x210
	v_mad_u64_u32 v[6:7], s[40:41], v8, s40, v[0:1]
	v_add_u32_e32 v8, s57, v8
	ds_read_b128 v[2:5], v6
	v_ashrrev_i32_e32 v9, 31, v8
	s_ashr_i32 s55, s54, 31
	v_lshlrev_b64 v[10:11], 11, v[8:9]
	v_lshl_add_u64 v[10:11], s[4:5], 0, v[10:11]
	s_lshl_b64 s[40:41], s[54:55], 1
	v_lshl_add_u64 v[10:11], v[10:11], 0, s[40:41]
	v_lshl_add_u64 v[10:11], v[10:11], 0, v[0:1]
	s_waitcnt lgkmcnt(0)
	global_store_dwordx4 v[10:11], v[2:5], off
	v_add_u32_e32 v10, 8, v8
	ds_read_b128 v[2:5], v6 offset:4224
	v_ashrrev_i32_e32 v11, 31, v10
	v_lshlrev_b64 v[10:11], 11, v[10:11]
	v_lshl_add_u64 v[10:11], s[4:5], 0, v[10:11]
	v_lshl_add_u64 v[10:11], v[10:11], 0, s[40:41]
	v_lshl_add_u64 v[10:11], v[10:11], 0, v[0:1]
	s_waitcnt lgkmcnt(0)
	global_store_dwordx4 v[10:11], v[2:5], off
	v_add_u32_e32 v10, 16, v8
	ds_read_b128 v[2:5], v6 offset:8448
	v_ashrrev_i32_e32 v11, 31, v10
	v_lshlrev_b64 v[10:11], 11, v[10:11]
	v_lshl_add_u64 v[10:11], s[4:5], 0, v[10:11]
	v_lshl_add_u64 v[10:11], v[10:11], 0, s[40:41]
	v_lshl_add_u64 v[10:11], v[10:11], 0, v[0:1]
	s_waitcnt lgkmcnt(0)
	global_store_dwordx4 v[10:11], v[2:5], off
	v_add_u32_e32 v10, 24, v8
	ds_read_b128 v[2:5], v6 offset:12672
	v_ashrrev_i32_e32 v11, 31, v10
	v_lshlrev_b64 v[10:11], 11, v[10:11]
	v_lshl_add_u64 v[10:11], s[4:5], 0, v[10:11]
	v_lshl_add_u64 v[10:11], v[10:11], 0, s[40:41]
	v_lshl_add_u64 v[10:11], v[10:11], 0, v[0:1]
	s_waitcnt lgkmcnt(0)
	global_store_dwordx4 v[10:11], v[2:5], off
	v_add_u32_e32 v10, 32, v8
	ds_read_b128 v[2:5], v6 offset:16896
	v_ashrrev_i32_e32 v11, 31, v10
	v_lshlrev_b64 v[10:11], 11, v[10:11]
	v_lshl_add_u64 v[10:11], s[4:5], 0, v[10:11]
	v_lshl_add_u64 v[10:11], v[10:11], 0, s[40:41]
	v_lshl_add_u64 v[10:11], v[10:11], 0, v[0:1]
	s_waitcnt lgkmcnt(0)
	global_store_dwordx4 v[10:11], v[2:5], off
	v_add_u32_e32 v10, 40, v8
	ds_read_b128 v[2:5], v6 offset:21120
	v_ashrrev_i32_e32 v11, 31, v10
	v_lshlrev_b64 v[10:11], 11, v[10:11]
	v_lshl_add_u64 v[10:11], s[4:5], 0, v[10:11]
	v_lshl_add_u64 v[10:11], v[10:11], 0, s[40:41]
	v_lshl_add_u64 v[10:11], v[10:11], 0, v[0:1]
	s_waitcnt lgkmcnt(0)
	global_store_dwordx4 v[10:11], v[2:5], off
	v_add_u32_e32 v10, 48, v8
	ds_read_b128 v[2:5], v6 offset:25344
	v_ashrrev_i32_e32 v11, 31, v10
	v_lshlrev_b64 v[10:11], 11, v[10:11]
	v_lshl_add_u64 v[10:11], s[4:5], 0, v[10:11]
	v_lshl_add_u64 v[10:11], v[10:11], 0, s[40:41]
	v_lshl_add_u64 v[10:11], v[10:11], 0, v[0:1]
	s_waitcnt lgkmcnt(0)
	global_store_dwordx4 v[10:11], v[2:5], off
	v_add_u32_e32 v10, 56, v8
	ds_read_b128 v[2:5], v6 offset:29568
	v_ashrrev_i32_e32 v11, 31, v10
	v_lshlrev_b64 v[10:11], 11, v[10:11]
	v_lshl_add_u64 v[10:11], s[4:5], 0, v[10:11]
	v_lshl_add_u64 v[10:11], v[10:11], 0, s[40:41]
	v_lshl_add_u64 v[10:11], v[10:11], 0, v[0:1]
	s_waitcnt lgkmcnt(0)
	global_store_dwordx4 v[10:11], v[2:5], off
	v_add_u32_e32 v10, 64, v8
	ds_read_b128 v[2:5], v6 offset:33792
	v_ashrrev_i32_e32 v11, 31, v10
	v_lshlrev_b64 v[10:11], 11, v[10:11]
	v_lshl_add_u64 v[10:11], s[4:5], 0, v[10:11]
	v_lshl_add_u64 v[10:11], v[10:11], 0, s[40:41]
	v_lshl_add_u64 v[10:11], v[10:11], 0, v[0:1]
	s_waitcnt lgkmcnt(0)
	global_store_dwordx4 v[10:11], v[2:5], off
	v_add_u32_e32 v10, 0x48, v8
	ds_read_b128 v[2:5], v6 offset:38016
	v_ashrrev_i32_e32 v11, 31, v10
	v_lshlrev_b64 v[10:11], 11, v[10:11]
	v_lshl_add_u64 v[10:11], s[4:5], 0, v[10:11]
	v_lshl_add_u64 v[10:11], v[10:11], 0, s[40:41]
	v_lshl_add_u64 v[10:11], v[10:11], 0, v[0:1]
	s_waitcnt lgkmcnt(0)
	global_store_dwordx4 v[10:11], v[2:5], off
	v_add_u32_e32 v10, 0x50, v8
	ds_read_b128 v[2:5], v6 offset:42240
	v_ashrrev_i32_e32 v11, 31, v10
	v_lshlrev_b64 v[10:11], 11, v[10:11]
	v_lshl_add_u64 v[10:11], s[4:5], 0, v[10:11]
	v_lshl_add_u64 v[10:11], v[10:11], 0, s[40:41]
	v_lshl_add_u64 v[10:11], v[10:11], 0, v[0:1]
	s_waitcnt lgkmcnt(0)
	global_store_dwordx4 v[10:11], v[2:5], off
	v_add_u32_e32 v10, 0x58, v8
	ds_read_b128 v[2:5], v6 offset:46464
	v_ashrrev_i32_e32 v11, 31, v10
	v_lshlrev_b64 v[10:11], 11, v[10:11]
	v_lshl_add_u64 v[10:11], s[4:5], 0, v[10:11]
	v_lshl_add_u64 v[10:11], v[10:11], 0, s[40:41]
	v_lshl_add_u64 v[10:11], v[10:11], 0, v[0:1]
	s_waitcnt lgkmcnt(0)
	global_store_dwordx4 v[10:11], v[2:5], off
	v_add_u32_e32 v10, 0x60, v8
	ds_read_b128 v[2:5], v6 offset:50688
	v_ashrrev_i32_e32 v11, 31, v10
	v_lshlrev_b64 v[10:11], 11, v[10:11]
	v_lshl_add_u64 v[10:11], s[4:5], 0, v[10:11]
	v_lshl_add_u64 v[10:11], v[10:11], 0, s[40:41]
	v_lshl_add_u64 v[10:11], v[10:11], 0, v[0:1]
	s_waitcnt lgkmcnt(0)
	global_store_dwordx4 v[10:11], v[2:5], off
	v_add_u32_e32 v10, 0x68, v8
	ds_read_b128 v[2:5], v6 offset:54912
	v_ashrrev_i32_e32 v11, 31, v10
	v_lshlrev_b64 v[10:11], 11, v[10:11]
	v_lshl_add_u64 v[10:11], s[4:5], 0, v[10:11]
	v_lshl_add_u64 v[10:11], v[10:11], 0, s[40:41]
	v_lshl_add_u64 v[10:11], v[10:11], 0, v[0:1]
	s_waitcnt lgkmcnt(0)
	global_store_dwordx4 v[10:11], v[2:5], off
	v_add_u32_e32 v10, 0x70, v8
	ds_read_b128 v[2:5], v6 offset:59136
	v_ashrrev_i32_e32 v11, 31, v10
	v_lshlrev_b64 v[10:11], 11, v[10:11]
	v_lshl_add_u64 v[10:11], s[4:5], 0, v[10:11]
	v_lshl_add_u64 v[10:11], v[10:11], 0, s[40:41]
	v_lshl_add_u64 v[10:11], v[10:11], 0, v[0:1]
	s_waitcnt lgkmcnt(0)
	global_store_dwordx4 v[10:11], v[2:5], off
	ds_read_b128 v[2:5], v6 offset:63360
	v_add_u32_e32 v6, 0x78, v8
	v_ashrrev_i32_e32 v7, 31, v6
	v_lshlrev_b64 v[6:7], 11, v[6:7]
	v_lshl_add_u64 v[6:7], s[4:5], 0, v[6:7]
	v_lshl_add_u64 v[6:7], v[6:7], 0, s[40:41]
	v_lshl_add_u64 v[6:7], v[6:7], 0, v[0:1]
	s_waitcnt lgkmcnt(0)
	global_store_dwordx4 v[6:7], v[2:5], off
	s_branch .LBB0_28

.LBB0_72:
	s_mul_i32 s42, s1, 0x6000
	s_add_i32 s43, s42, 0xffffa000
	s_cmp_gt_i32 s1, 0
	s_waitcnt vmcnt(6)
	s_cselect_b32 s43, s43, 0xc000
	s_waitcnt lgkmcnt(0)
	s_barrier
	s_setprio 2
	v_add3_u32 v0, s42, v177, v176
	v_add_u32_e32 v0, s14, v0
	v_add3_u32 v212, s42, v178, v176
	ds_read_b128 v[196:199], v212 offset:8192
	ds_read_b128 v[180:183], v0
	ds_read_b128 v[184:187], v0 offset:1024
	ds_read_b128 v[188:191], v0 offset:2048
	ds_read_b128 v[192:195], v0 offset:3072
	ds_read_b128 v[200:203], v212 offset:9216
	ds_read_b128 v[204:207], v212 offset:10240
	ds_read_b128 v[208:211], v212 offset:11264
	ds_read_b128 v[216:219], v212 offset:12288
	ds_read_b128 v[226:229], v212 offset:13312
	ds_read_b128 v[230:233], v212 offset:14336
	ds_read_b128 v[234:237], v212 offset:15360
	s_cmp_eq_u32 s100, 0
	s_cbranch_scc0 .Lmy_re_1
	v_lshl_add_u64 v[212:213], v[174:175], 0, s[12:13]
	v_lshl_add_u64 v[212:213], v[162:163], 1, v[212:213]
	s_add_i32 s44, s43, s41
	s_mov_b32 m0, s44
	s_nop 0
	global_load_lds_dwordx4 v[212:213], off
	v_lshl_add_u64 v[212:213], v[174:175], 0, s[12:13]
	v_lshl_add_u64 v[212:213], v[164:165], 1, v[212:213]
	s_add_i32 s44, s43, s15
	s_mov_b32 m0, s44
	s_nop 0
	global_load_lds_dwordx4 v[212:213], off
	s_add_i32 s43, s40, s43
	v_lshl_add_u64 v[212:213], v[172:173], 0, s[12:13]
	s_mov_b32 m0, s43
	s_nop 0
	global_load_lds_dwordx4 v[212:213], off
	v_lshl_add_u64 v[212:213], v[170:171], 0, s[12:13]
	s_add_i32 s44, s43, 0x400
	s_mov_b32 m0, s44
	s_nop 0
	global_load_lds_dwordx4 v[212:213], off
	v_lshl_add_u64 v[212:213], v[168:169], 0, s[12:13]
	s_add_i32 s44, s43, 0x800
	s_mov_b32 m0, s44
	s_nop 0
	global_load_lds_dwordx4 v[212:213], off
	s_addk_i32 s43, 0xc00
	v_lshl_add_u64 v[212:213], v[166:167], 0, s[12:13]
	s_mov_b32 m0, s43
	s_nop 0
	global_load_lds_dwordx4 v[212:213], off
.Lmy_re_1:
	s_setprio 0
	s_waitcnt lgkmcnt(10)
	v_mfma_f32_16x16x32_bf16 v[34:37], v[196:199], v[180:183], v[34:37]
	s_waitcnt lgkmcnt(9)
	v_mfma_f32_16x16x32_bf16 v[38:41], v[196:199], v[184:187], v[38:41]
	s_waitcnt lgkmcnt(8)
	v_mfma_f32_16x16x32_bf16 v[42:45], v[196:199], v[188:191], v[42:45]
	s_waitcnt lgkmcnt(7)
	v_mfma_f32_16x16x32_bf16 v[46:49], v[196:199], v[192:195], v[46:49]
	s_waitcnt lgkmcnt(6)
	v_mfma_f32_16x16x32_bf16 v[50:53], v[200:203], v[180:183], v[50:53]
	v_mfma_f32_16x16x32_bf16 v[54:57], v[200:203], v[184:187], v[54:57]
	v_mfma_f32_16x16x32_bf16 v[58:61], v[200:203], v[188:191], v[58:61]
	v_mfma_f32_16x16x32_bf16 v[62:65], v[200:203], v[192:195], v[62:65]
	s_waitcnt lgkmcnt(5)
	v_mfma_f32_16x16x32_bf16 v[66:69], v[204:207], v[180:183], v[66:69]
	v_mfma_f32_16x16x32_bf16 v[70:73], v[204:207], v[184:187], v[70:73]
	v_mfma_f32_16x16x32_bf16 v[74:77], v[204:207], v[188:191], v[74:77]
	v_mfma_f32_16x16x32_bf16 v[78:81], v[204:207], v[192:195], v[78:81]
	s_waitcnt lgkmcnt(4)
	v_mfma_f32_16x16x32_bf16 v[82:85], v[208:211], v[180:183], v[82:85]
	v_mfma_f32_16x16x32_bf16 v[86:89], v[208:211], v[184:187], v[86:89]
	v_mfma_f32_16x16x32_bf16 v[90:93], v[208:211], v[188:191], v[90:93]
	v_mfma_f32_16x16x32_bf16 v[94:97], v[208:211], v[192:195], v[94:97]
	s_waitcnt lgkmcnt(3)
	v_mfma_f32_16x16x32_bf16 v[98:101], v[216:219], v[180:183], v[98:101]
	v_mfma_f32_16x16x32_bf16 v[102:105], v[216:219], v[184:187], v[102:105]
	v_mfma_f32_16x16x32_bf16 v[106:109], v[216:219], v[188:191], v[106:109]
	v_mfma_f32_16x16x32_bf16 v[110:113], v[216:219], v[192:195], v[110:113]
	s_waitcnt lgkmcnt(2)
	v_mfma_f32_16x16x32_bf16 v[114:117], v[226:229], v[180:183], v[114:117]
	v_mfma_f32_16x16x32_bf16 v[118:121], v[226:229], v[184:187], v[118:121]
	v_mfma_f32_16x16x32_bf16 v[122:125], v[226:229], v[188:191], v[122:125]
	v_mfma_f32_16x16x32_bf16 v[126:129], v[226:229], v[192:195], v[126:129]
	s_waitcnt lgkmcnt(1)
	v_mfma_f32_16x16x32_bf16 v[130:133], v[230:233], v[180:183], v[130:133]
	v_mfma_f32_16x16x32_bf16 v[134:137], v[230:233], v[184:187], v[134:137]
	v_mfma_f32_16x16x32_bf16 v[138:141], v[230:233], v[188:191], v[138:141]
	v_mfma_f32_16x16x32_bf16 v[142:145], v[230:233], v[192:195], v[142:145]
	s_waitcnt lgkmcnt(0)
	v_mfma_f32_16x16x32_bf16 v[146:149], v[234:237], v[180:183], v[146:149]
	v_mfma_f32_16x16x32_bf16 v[150:153], v[234:237], v[184:187], v[150:153]
	v_mfma_f32_16x16x32_bf16 v[154:157], v[234:237], v[188:191], v[154:157]
	v_mfma_f32_16x16x32_bf16 v[158:161], v[234:237], v[192:195], v[158:161]
	s_cmp_eq_u32 s100, 0
	s_cbranch_scc1 .Lmy_rl_1
	s_setprio 2
	v_lshl_add_u64 v[212:213], v[174:175], 0, s[12:13]
	v_lshl_add_u64 v[212:213], v[162:163], 1, v[212:213]
	s_add_i32 s44, s43, s41
	s_mov_b32 m0, s44
	s_nop 0
	global_load_lds_dwordx4 v[212:213], off
	v_lshl_add_u64 v[212:213], v[174:175], 0, s[12:13]
	v_lshl_add_u64 v[212:213], v[164:165], 1, v[212:213]
	s_add_i32 s44, s43, s15
	s_mov_b32 m0, s44
	s_nop 0
	global_load_lds_dwordx4 v[212:213], off
	s_add_i32 s43, s40, s43
	v_lshl_add_u64 v[212:213], v[172:173], 0, s[12:13]
	s_mov_b32 m0, s43
	s_nop 0
	global_load_lds_dwordx4 v[212:213], off
	v_lshl_add_u64 v[212:213], v[170:171], 0, s[12:13]
	s_add_i32 s44, s43, 0x400
	s_mov_b32 m0, s44
	s_nop 0
	global_load_lds_dwordx4 v[212:213], off
	v_lshl_add_u64 v[212:213], v[168:169], 0, s[12:13]
	s_add_i32 s44, s43, 0x800
	s_mov_b32 m0, s44
	s_nop 0
	global_load_lds_dwordx4 v[212:213], off
	s_addk_i32 s43, 0xc00
	v_lshl_add_u64 v[212:213], v[166:167], 0, s[12:13]
	s_mov_b32 m0, s43
	s_nop 0
	global_load_lds_dwordx4 v[212:213], off
.Lmy_rl_1:
	s_add_i32 s42, s1, 1
	s_cmp_lg_u32 s1, 2
	s_cselect_b32 s1, s42, 0
	s_add_u32 s12, s12, 64
	s_addc_u32 s13, s13, 0
	s_cmpk_eq_i32 s12, 0x780
	s_cbranch_scc0 .LBB0_72
	s_waitcnt vmcnt(6)
	v_mov_b32_e32 v162, v31
	v_mov_b32_e32 v163, v32
	v_mov_b32_e32 v31, v33
	v_mov_b32_e32 v164, v15
	v_mov_b32_e32 v165, v16
	v_pk_add_f32 v[30:31], v[162:163], v[30:31]
	v_mov_b32_e32 v15, v17
	v_pk_add_f32 v[14:15], v[164:165], v[14:15]
	v_add_f32_e32 v0, v30, v31
	v_add_f32_e32 v0, v0, v14
	v_add_f32_e32 v0, v0, v15
	s_waitcnt vmcnt(4)
	v_mov_b32_e32 v166, v27
	v_mov_b32_e32 v167, v28
	v_fmamk_f32 v0, v0, 0x3a800000, v250
	s_mov_b32 s1, 0x800000
	v_mov_b32_e32 v27, v29
	v_mov_b32_e32 v168, v11
	v_mov_b32_e32 v169, v12
	s_waitcnt vmcnt(1)
	v_mov_b32_e32 v180, v3
	v_mul_f32_e32 v3, 0x4b800000, v0
	v_cmp_gt_f32_e32 vcc, s1, v0
	v_pk_add_f32 v[14:15], v[166:167], v[26:27]
	v_mov_b32_e32 v11, v13
	v_cndmask_b32_e32 v0, v0, v3, vcc
	v_pk_add_f32 v[10:11], v[168:169], v[10:11]
	v_add_f32_e32 v3, v14, v15
	v_add_f32_e32 v3, v3, v10
	v_add_f32_e32 v3, v3, v11
	v_fmamk_f32 v3, v3, 0x3a800000, v250
	v_mov_b32_e32 v170, v23
	v_mov_b32_e32 v171, v24
	v_mov_b32_e32 v181, v4
	v_mul_f32_e32 v4, 0x4b800000, v3
	v_cmp_gt_f32_e64 s[40:41], s1, v3
	v_mov_b32_e32 v23, v25
	v_mov_b32_e32 v172, v7
	v_mov_b32_e32 v173, v8
	v_cndmask_b32_e64 v3, v3, v4, s[40:41]
	v_pk_add_f32 v[10:11], v[170:171], v[22:23]
	v_mov_b32_e32 v7, v9
	v_rsq_f32_e32 v179, v3
	v_pk_add_f32 v[6:7], v[172:173], v[6:7]
	v_add_f32_e32 v3, v10, v11
	v_add_f32_e32 v3, v3, v6
	v_add_f32_e32 v3, v3, v7
	v_fmamk_f32 v3, v3, 0x3a800000, v250
	v_mul_f32_e32 v4, 0x4b800000, v3
	v_cmp_gt_f32_e64 s[42:43], s1, v3
	s_waitcnt vmcnt(0)
	v_mov_b32_e32 v174, v19
	v_mov_b32_e32 v175, v20
	v_cndmask_b32_e64 v3, v3, v4, s[42:43]
	v_mov_b32_e32 v19, v21
	v_rsq_f32_e32 v182, v3
	v_pk_add_f32 v[6:7], v[174:175], v[18:19]
	v_mov_b32_e32 v3, v5
	v_pk_add_f32 v[2:3], v[180:181], v[2:3]
	v_add_f32_e32 v4, v6, v7
	v_add_f32_e32 v2, v4, v2
	v_add_f32_e32 v2, v2, v3
	v_fmamk_f32 v2, v2, 0x3a800000, v250
	v_mul_f32_e32 v3, 0x4b800000, v2
	v_cmp_gt_f32_e64 s[44:45], s1, v2
	s_waitcnt vmcnt(6)
	v_add_u32_e32 v183, v178, v176
	s_waitcnt lgkmcnt(0)
	s_barrier
	v_cndmask_b32_e64 v2, v2, v3, s[44:45]
	v_rsq_f32_e32 v180, v2
	ds_read_b128 v[2:5], v183 offset:15360
	ds_read_b128 v[6:9], v183 offset:14336
	ds_read_b128 v[10:13], v183 offset:13312
	ds_read_b128 v[14:17], v183 offset:12288
	ds_read_b128 v[18:21], v183 offset:11264
	ds_read_b128 v[22:25], v183 offset:10240
	ds_read_b128 v[26:29], v183 offset:9216
	ds_read_b128 v[30:33], v183 offset:8192
	v_add3_u32 v178, s14, v177, v176
	ds_read_b128 v[162:165], v178 offset:3072
	ds_read_b128 v[166:169], v178 offset:2048
	ds_read_b128 v[170:173], v178 offset:1024
	ds_read_b128 v[174:177], v178
	v_rsq_f32_e32 v0, v0
	v_mul_f32_e32 v184, 0x45800000, v179
	v_mul_f32_e32 v185, 0x45800000, v182
	v_mul_f32_e32 v186, 0x45800000, v180
	v_mul_f32_e32 v181, 0x45800000, v0
	s_waitcnt lgkmcnt(0)
	v_mfma_f32_16x16x32_bf16 v[34:37], v[30:33], v[174:177], v[34:37]
	v_mfma_f32_16x16x32_bf16 v[38:41], v[30:33], v[170:173], v[38:41]
	v_mfma_f32_16x16x32_bf16 v[42:45], v[30:33], v[166:169], v[42:45]
	v_mfma_f32_16x16x32_bf16 v[46:49], v[30:33], v[162:165], v[46:49]
	v_mfma_f32_16x16x32_bf16 v[50:53], v[26:29], v[174:177], v[50:53]
	v_mfma_f32_16x16x32_bf16 v[54:57], v[26:29], v[170:173], v[54:57]
	v_mfma_f32_16x16x32_bf16 v[58:61], v[26:29], v[166:169], v[58:61]
	v_mfma_f32_16x16x32_bf16 v[62:65], v[26:29], v[162:165], v[62:65]
	v_mfma_f32_16x16x32_bf16 v[66:69], v[22:25], v[174:177], v[66:69]
	v_mfma_f32_16x16x32_bf16 v[70:73], v[22:25], v[170:173], v[70:73]
	v_mfma_f32_16x16x32_bf16 v[74:77], v[22:25], v[166:169], v[74:77]
	v_mfma_f32_16x16x32_bf16 v[22:25], v[22:25], v[162:165], v[78:81]
	v_mfma_f32_16x16x32_bf16 v[78:81], v[18:21], v[174:177], v[82:85]
	v_mfma_f32_16x16x32_bf16 v[82:85], v[18:21], v[170:173], v[86:89]
	v_mfma_f32_16x16x32_bf16 v[86:89], v[18:21], v[166:169], v[90:93]
	v_mfma_f32_16x16x32_bf16 v[18:21], v[18:21], v[162:165], v[94:97]
	v_mfma_f32_16x16x32_bf16 v[90:93], v[14:17], v[174:177], v[98:101]
	v_mfma_f32_16x16x32_bf16 v[94:97], v[14:17], v[170:173], v[102:105]
	v_mfma_f32_16x16x32_bf16 v[98:101], v[14:17], v[166:169], v[106:109]
	v_mfma_f32_16x16x32_bf16 v[14:17], v[14:17], v[162:165], v[110:113]
	v_mfma_f32_16x16x32_bf16 v[102:105], v[10:13], v[174:177], v[114:117]
	v_mfma_f32_16x16x32_bf16 v[106:109], v[10:13], v[170:173], v[118:121]
	v_mfma_f32_16x16x32_bf16 v[110:113], v[10:13], v[166:169], v[122:125]
	v_mfma_f32_16x16x32_bf16 v[10:13], v[10:13], v[162:165], v[126:129]
	v_mfma_f32_16x16x32_bf16 v[114:117], v[6:9], v[174:177], v[130:133]
	v_mfma_f32_16x16x32_bf16 v[118:121], v[6:9], v[170:173], v[134:137]
	v_mfma_f32_16x16x32_bf16 v[122:125], v[6:9], v[166:169], v[138:141]
	v_mfma_f32_16x16x32_bf16 v[6:9], v[6:9], v[162:165], v[142:145]
	v_mfma_f32_16x16x32_bf16 v[126:129], v[2:5], v[174:177], v[146:149]
	v_mfma_f32_16x16x32_bf16 v[130:133], v[2:5], v[170:173], v[150:153]
	v_mfma_f32_16x16x32_bf16 v[134:137], v[2:5], v[166:169], v[154:157]
	v_mfma_f32_16x16x32_bf16 v[2:5], v[2:5], v[162:165], v[158:161]
	s_waitcnt vmcnt(0)
	v_cndmask_b32_e32 v30, v0, v181, vcc
	v_cndmask_b32_e64 v28, v179, v184, s[40:41]
	v_cndmask_b32_e64 v26, v182, v185, s[42:43]
	v_cndmask_b32_e64 v0, v180, v186, s[44:45]
	s_waitcnt lgkmcnt(0)
	s_barrier
	ds_read_b128 v[138:141], v178 offset:24576
	ds_read_b128 v[142:145], v178 offset:25600
	ds_read_b128 v[146:149], v178 offset:26624
	ds_read_b128 v[150:153], v178 offset:27648
	ds_read_b128 v[154:157], v183 offset:32768
	ds_read_b128 v[158:161], v183 offset:33792
	ds_read_b128 v[162:165], v183 offset:34816
	ds_read_b128 v[166:169], v183 offset:35840
	ds_read_b128 v[170:173], v183 offset:36864
	ds_read_b128 v[174:177], v183 offset:37888
	ds_read_b128 v[178:181], v183 offset:38912
	ds_read_b128 v[182:185], v183 offset:39936
	s_waitcnt lgkmcnt(7)
	v_mfma_f32_16x16x32_bf16 v[32:35], v[154:157], v[138:141], v[34:37]
	v_mfma_f32_16x16x32_bf16 v[36:39], v[154:157], v[142:145], v[38:41]
	v_mfma_f32_16x16x32_bf16 v[40:43], v[154:157], v[146:149], v[42:45]
	v_mfma_f32_16x16x32_bf16 v[44:47], v[154:157], v[150:153], v[46:49]
	s_waitcnt lgkmcnt(6)
	v_mfma_f32_16x16x32_bf16 v[48:51], v[158:161], v[138:141], v[50:53]
	v_mfma_f32_16x16x32_bf16 v[52:55], v[158:161], v[142:145], v[54:57]
	v_mfma_f32_16x16x32_bf16 v[56:59], v[158:161], v[146:149], v[58:61]
	v_mfma_f32_16x16x32_bf16 v[60:63], v[158:161], v[150:153], v[62:65]
	s_waitcnt lgkmcnt(5)
	v_mfma_f32_16x16x32_bf16 v[64:67], v[162:165], v[138:141], v[66:69]
	v_mfma_f32_16x16x32_bf16 v[68:71], v[162:165], v[142:145], v[70:73]
	v_mfma_f32_16x16x32_bf16 v[72:75], v[162:165], v[146:149], v[74:77]
	v_mfma_f32_16x16x32_bf16 v[154:157], v[162:165], v[150:153], v[22:25]
	s_waitcnt lgkmcnt(4)
	v_mfma_f32_16x16x32_bf16 v[76:79], v[166:169], v[138:141], v[78:81]
	v_mfma_f32_16x16x32_bf16 v[80:83], v[166:169], v[142:145], v[82:85]
	v_mfma_f32_16x16x32_bf16 v[84:87], v[166:169], v[146:149], v[86:89]
	v_mfma_f32_16x16x32_bf16 v[158:161], v[166:169], v[150:153], v[18:21]
	s_waitcnt lgkmcnt(3)
	v_mfma_f32_16x16x32_bf16 v[88:91], v[170:173], v[138:141], v[90:93]
	v_mfma_f32_16x16x32_bf16 v[92:95], v[170:173], v[142:145], v[94:97]
	v_mfma_f32_16x16x32_bf16 v[96:99], v[170:173], v[146:149], v[98:101]
	v_mfma_f32_16x16x32_bf16 v[162:165], v[170:173], v[150:153], v[14:17]
	s_waitcnt lgkmcnt(2)
	v_mfma_f32_16x16x32_bf16 v[100:103], v[174:177], v[138:141], v[102:105]
	v_mfma_f32_16x16x32_bf16 v[104:107], v[174:177], v[142:145], v[106:109]
	v_mfma_f32_16x16x32_bf16 v[108:111], v[174:177], v[146:149], v[110:113]
	v_mfma_f32_16x16x32_bf16 v[166:169], v[174:177], v[150:153], v[10:13]
	s_waitcnt lgkmcnt(1)
	v_mfma_f32_16x16x32_bf16 v[112:115], v[178:181], v[138:141], v[114:117]
	v_mfma_f32_16x16x32_bf16 v[116:119], v[178:181], v[142:145], v[118:121]
	v_mfma_f32_16x16x32_bf16 v[22:25], v[178:181], v[146:149], v[122:125]
	v_mfma_f32_16x16x32_bf16 v[18:21], v[178:181], v[150:153], v[6:9]
	s_waitcnt lgkmcnt(0)
	v_mfma_f32_16x16x32_bf16 v[14:17], v[182:185], v[138:141], v[126:129]
	v_mfma_f32_16x16x32_bf16 v[10:13], v[182:185], v[142:145], v[130:133]
	v_mfma_f32_16x16x32_bf16 v[6:9], v[182:185], v[146:149], v[134:137]
	v_mfma_f32_16x16x32_bf16 v[2:5], v[182:185], v[150:153], v[2:5]
	v_mov_b32_e32 v27, v224
	s_movk_i32 s1, 0x210
	v_lshrrev_b32_e32 v120, 1, v27
	v_and_b32_e32 v31, 0x7fffff80, v27
	v_and_b32_e32 v120, 24, v120
	v_and_b32_e32 v29, 0x4f, v27
	v_lshl_or_b32 v31, v31, 1, v120
	v_pk_mul_f32 v[32:33], v[30:31], v[32:33] op_sel_hi:[0,1]
	v_pk_mul_f32 v[34:35], v[30:31], v[34:35] op_sel_hi:[0,1]
	v_mad_u32_u24 v29, v29, s1, v31
	v_cvt_pk_bf16_f32 v32, v32, v33
	v_cvt_pk_bf16_f32 v33, v34, v35
	v_pk_mul_f32 v[34:35], v[28:29], v[36:37] op_sel_hi:[0,1]
	v_pk_mul_f32 v[36:37], v[28:29], v[38:39] op_sel_hi:[0,1]
	v_cvt_pk_bf16_f32 v34, v34, v35
	v_cvt_pk_bf16_f32 v35, v36, v37
	v_pk_mul_f32 v[36:37], v[26:27], v[40:41] op_sel_hi:[0,1]
	v_pk_mul_f32 v[38:39], v[26:27], v[42:43] op_sel_hi:[0,1]
	v_cvt_pk_bf16_f32 v36, v36, v37
	v_cvt_pk_bf16_f32 v37, v38, v39
	v_pk_mul_f32 v[38:39], v[0:1], v[44:45] op_sel_hi:[0,1]
	v_pk_mul_f32 v[40:41], v[0:1], v[46:47] op_sel_hi:[0,1]
	v_cvt_pk_bf16_f32 v38, v38, v39
	v_cvt_pk_bf16_f32 v39, v40, v41
	v_pk_mul_f32 v[40:41], v[30:31], v[48:49] op_sel_hi:[0,1]
	v_pk_mul_f32 v[42:43], v[30:31], v[50:51] op_sel_hi:[0,1]
	v_cvt_pk_bf16_f32 v40, v40, v41
	v_cvt_pk_bf16_f32 v41, v42, v43
	s_barrier
	ds_write2_b64 v29, v[32:33], v[40:41] offset1:4
	v_pk_mul_f32 v[32:33], v[28:29], v[52:53] op_sel_hi:[0,1]
	v_pk_mul_f32 v[40:41], v[28:29], v[54:55] op_sel_hi:[0,1]
	v_cvt_pk_bf16_f32 v32, v32, v33
	v_cvt_pk_bf16_f32 v33, v40, v41
	v_add_u32_e32 v31, 0x2000, v29
	ds_write2_b64 v31, v[34:35], v[32:33] offset0:32 offset1:36
	v_pk_mul_f32 v[32:33], v[26:27], v[56:57] op_sel_hi:[0,1]
	v_pk_mul_f32 v[34:35], v[26:27], v[58:59] op_sel_hi:[0,1]
	v_cvt_pk_bf16_f32 v32, v32, v33
	v_cvt_pk_bf16_f32 v33, v34, v35
	v_add_u32_e32 v44, 0x4000, v29
	ds_write2_b64 v44, v[36:37], v[32:33] offset0:64 offset1:68
	v_pk_mul_f32 v[32:33], v[0:1], v[60:61] op_sel_hi:[0,1]
	v_pk_mul_f32 v[34:35], v[0:1], v[62:63] op_sel_hi:[0,1]
	v_cvt_pk_bf16_f32 v32, v32, v33
	v_cvt_pk_bf16_f32 v33, v34, v35
	v_add_u32_e32 v45, 0x6000, v29
	ds_write2_b64 v45, v[38:39], v[32:33] offset0:96 offset1:100
	v_pk_mul_f32 v[32:33], v[30:31], v[64:65] op_sel_hi:[0,1]
	v_pk_mul_f32 v[34:35], v[30:31], v[66:67] op_sel_hi:[0,1]
	v_cvt_pk_bf16_f32 v32, v32, v33
	v_cvt_pk_bf16_f32 v33, v34, v35
	v_pk_mul_f32 v[34:35], v[28:29], v[68:69] op_sel_hi:[0,1]
	v_pk_mul_f32 v[36:37], v[28:29], v[70:71] op_sel_hi:[0,1]
	v_cvt_pk_bf16_f32 v34, v34, v35
	v_cvt_pk_bf16_f32 v35, v36, v37
	v_pk_mul_f32 v[36:37], v[26:27], v[72:73] op_sel_hi:[0,1]
	v_pk_mul_f32 v[38:39], v[26:27], v[74:75] op_sel_hi:[0,1]
	v_cvt_pk_bf16_f32 v36, v36, v37
	v_cvt_pk_bf16_f32 v37, v38, v39
	v_pk_mul_f32 v[38:39], v[0:1], v[154:155] op_sel_hi:[0,1]
	v_pk_mul_f32 v[40:41], v[0:1], v[156:157] op_sel_hi:[0,1]
	v_cvt_pk_bf16_f32 v38, v38, v39
	v_cvt_pk_bf16_f32 v39, v40, v41
	v_pk_mul_f32 v[40:41], v[30:31], v[76:77] op_sel_hi:[0,1]
	v_pk_mul_f32 v[42:43], v[30:31], v[78:79] op_sel_hi:[0,1]
	v_cvt_pk_bf16_f32 v40, v40, v41
	v_cvt_pk_bf16_f32 v41, v42, v43
	ds_write2_b64 v29, v[32:33], v[40:41] offset0:8 offset1:12
	v_pk_mul_f32 v[32:33], v[28:29], v[80:81] op_sel_hi:[0,1]
	v_pk_mul_f32 v[40:41], v[28:29], v[82:83] op_sel_hi:[0,1]
	v_cvt_pk_bf16_f32 v32, v32, v33
	v_cvt_pk_bf16_f32 v33, v40, v41
	ds_write2_b64 v31, v[34:35], v[32:33] offset0:40 offset1:44
	v_pk_mul_f32 v[32:33], v[26:27], v[84:85] op_sel_hi:[0,1]
	v_pk_mul_f32 v[34:35], v[26:27], v[86:87] op_sel_hi:[0,1]
	v_cvt_pk_bf16_f32 v32, v32, v33
	v_cvt_pk_bf16_f32 v33, v34, v35
	ds_write2_b64 v44, v[36:37], v[32:33] offset0:72 offset1:76
	v_pk_mul_f32 v[32:33], v[0:1], v[158:159] op_sel_hi:[0,1]
	v_pk_mul_f32 v[34:35], v[0:1], v[160:161] op_sel_hi:[0,1]
	v_cvt_pk_bf16_f32 v32, v32, v33
	v_cvt_pk_bf16_f32 v33, v34, v35
	ds_write2_b64 v45, v[38:39], v[32:33] offset0:104 offset1:108
	v_pk_mul_f32 v[32:33], v[30:31], v[88:89] op_sel_hi:[0,1]
	v_pk_mul_f32 v[34:35], v[30:31], v[90:91] op_sel_hi:[0,1]
	v_cvt_pk_bf16_f32 v32, v32, v33
	v_cvt_pk_bf16_f32 v33, v34, v35
	v_pk_mul_f32 v[34:35], v[28:29], v[92:93] op_sel_hi:[0,1]
	v_pk_mul_f32 v[36:37], v[28:29], v[94:95] op_sel_hi:[0,1]
	v_cvt_pk_bf16_f32 v34, v34, v35
	v_cvt_pk_bf16_f32 v35, v36, v37
	v_pk_mul_f32 v[36:37], v[26:27], v[96:97] op_sel_hi:[0,1]
	v_pk_mul_f32 v[38:39], v[26:27], v[98:99] op_sel_hi:[0,1]
	v_cvt_pk_bf16_f32 v36, v36, v37
	v_cvt_pk_bf16_f32 v37, v38, v39
	v_pk_mul_f32 v[38:39], v[0:1], v[162:163] op_sel_hi:[0,1]
	v_pk_mul_f32 v[40:41], v[0:1], v[164:165] op_sel_hi:[0,1]
	v_cvt_pk_bf16_f32 v38, v38, v39
	v_cvt_pk_bf16_f32 v39, v40, v41
	v_pk_mul_f32 v[40:41], v[30:31], v[100:101] op_sel_hi:[0,1]
	v_pk_mul_f32 v[42:43], v[30:31], v[102:103] op_sel_hi:[0,1]
	v_cvt_pk_bf16_f32 v40, v40, v41
	v_cvt_pk_bf16_f32 v41, v42, v43
	ds_write2_b64 v29, v[32:33], v[40:41] offset0:16 offset1:20
	v_pk_mul_f32 v[32:33], v[28:29], v[104:105] op_sel_hi:[0,1]
	v_pk_mul_f32 v[40:41], v[28:29], v[106:107] op_sel_hi:[0,1]
	v_cvt_pk_bf16_f32 v32, v32, v33
	v_cvt_pk_bf16_f32 v33, v40, v41
	ds_write2_b64 v31, v[34:35], v[32:33] offset0:48 offset1:52
	v_pk_mul_f32 v[32:33], v[26:27], v[108:109] op_sel_hi:[0,1]
	v_pk_mul_f32 v[34:35], v[26:27], v[110:111] op_sel_hi:[0,1]
	v_cvt_pk_bf16_f32 v32, v32, v33
	v_cvt_pk_bf16_f32 v33, v34, v35
	ds_write2_b64 v44, v[36:37], v[32:33] offset0:80 offset1:84
	v_pk_mul_f32 v[32:33], v[0:1], v[166:167] op_sel_hi:[0,1]
	v_pk_mul_f32 v[34:35], v[0:1], v[168:169] op_sel_hi:[0,1]
	v_cvt_pk_bf16_f32 v32, v32, v33
	v_cvt_pk_bf16_f32 v33, v34, v35
	v_pk_mul_f32 v[18:19], v[0:1], v[18:19] op_sel_hi:[0,1]
	v_pk_mul_f32 v[20:21], v[0:1], v[20:21] op_sel_hi:[0,1]
	v_pk_mul_f32 v[2:3], v[0:1], v[2:3] op_sel_hi:[0,1]
	v_pk_mul_f32 v[4:5], v[0:1], v[4:5] op_sel_hi:[0,1]
	v_lshlrev_b32_e32 v0, 3, v27
	ds_write2_b64 v45, v[38:39], v[32:33] offset0:112 offset1:116
	v_pk_mul_f32 v[32:33], v[30:31], v[112:113] op_sel_hi:[0,1]
	v_pk_mul_f32 v[34:35], v[30:31], v[114:115] op_sel_hi:[0,1]
	v_cvt_pk_bf16_f32 v18, v18, v19
	v_cvt_pk_bf16_f32 v19, v20, v21
	v_cvt_pk_bf16_f32 v2, v2, v3
	v_cvt_pk_bf16_f32 v3, v4, v5
	v_and_b32_e32 v0, 0xf8, v0
	v_cvt_pk_bf16_f32 v32, v32, v33
	v_cvt_pk_bf16_f32 v33, v34, v35
	v_pk_mul_f32 v[34:35], v[28:29], v[116:117] op_sel_hi:[0,1]
	v_pk_mul_f32 v[36:37], v[28:29], v[118:119] op_sel_hi:[0,1]
	v_pk_mul_f32 v[22:23], v[26:27], v[22:23] op_sel_hi:[0,1]
	v_pk_mul_f32 v[24:25], v[26:27], v[24:25] op_sel_hi:[0,1]
	v_pk_mul_f32 v[14:15], v[30:31], v[14:15] op_sel_hi:[0,1]
	v_pk_mul_f32 v[16:17], v[30:31], v[16:17] op_sel_hi:[0,1]
	v_pk_mul_f32 v[10:11], v[28:29], v[10:11] op_sel_hi:[0,1]
	v_pk_mul_f32 v[12:13], v[28:29], v[12:13] op_sel_hi:[0,1]
	v_pk_mul_f32 v[6:7], v[26:27], v[6:7] op_sel_hi:[0,1]
	v_pk_mul_f32 v[8:9], v[26:27], v[8:9] op_sel_hi:[0,1]
	ds_write2_b64 v45, v[18:19], v[2:3] offset0:120 offset1:124
	v_or_b32_e32 v2, s0, v0
	s_movk_i32 s1, 0x400
	v_cvt_pk_bf16_f32 v34, v34, v35
	v_cvt_pk_bf16_f32 v35, v36, v37
	v_cvt_pk_bf16_f32 v22, v22, v23
	v_cvt_pk_bf16_f32 v23, v24, v25
	v_cvt_pk_bf16_f32 v14, v14, v15
	v_cvt_pk_bf16_f32 v15, v16, v17
	v_cvt_pk_bf16_f32 v10, v10, v11
	v_cvt_pk_bf16_f32 v11, v12, v13
	v_cvt_pk_bf16_f32 v6, v6, v7
	v_cvt_pk_bf16_f32 v7, v8, v9
	v_cmp_gt_i32_e64 s[44:45], s1, v2
	ds_write2_b64 v29, v[32:33], v[14:15] offset0:24 offset1:28
	ds_write2_b64 v31, v[34:35], v[10:11] offset0:56 offset1:60
	ds_write2_b64 v44, v[22:23], v[6:7] offset0:88 offset1:92
	s_waitcnt lgkmcnt(0)
	s_barrier
	s_mov_b64 s[12:13], 11
	s_mov_b64 s[40:41], s[46:47]
	s_branch .LBB0_78

.LBB0_76:
	s_mul_i32 s41, s12, 0x6000
	s_add_i32 s42, s41, 0xffffa000
	s_cmp_gt_i32 s12, 0
	s_waitcnt vmcnt(6)
	s_cselect_b32 s42, s42, 0xc000
	s_waitcnt lgkmcnt(0)
	s_barrier
	s_setprio 2
	v_add3_u32 v0, s41, v177, v176
	v_add_u32_e32 v0, s13, v0
	v_add3_u32 v212, s41, v178, v176
	ds_read_b128 v[196:199], v212 offset:8192
	ds_read_b128 v[180:183], v0
	ds_read_b128 v[184:187], v0 offset:1024
	ds_read_b128 v[188:191], v0 offset:2048
	ds_read_b128 v[192:195], v0 offset:3072
	ds_read_b128 v[200:203], v212 offset:9216
	ds_read_b128 v[204:207], v212 offset:10240
	ds_read_b128 v[208:211], v212 offset:11264
	ds_read_b128 v[216:219], v212 offset:12288
	ds_read_b128 v[226:229], v212 offset:13312
	ds_read_b128 v[230:233], v212 offset:14336
	ds_read_b128 v[234:237], v212 offset:15360
	s_cmp_eq_u32 s100, 0
	s_cbranch_scc0 .Lmy_re_2
	v_lshl_add_u64 v[212:213], v[174:175], 0, s[0:1]
	v_lshl_add_u64 v[212:213], v[162:163], 1, v[212:213]
	s_add_i32 s43, s42, s40
	s_mov_b32 m0, s43
	s_nop 0
	global_load_lds_dwordx4 v[212:213], off
	v_lshl_add_u64 v[212:213], v[174:175], 0, s[0:1]
	v_lshl_add_u64 v[212:213], v[164:165], 1, v[212:213]
	s_add_i32 s43, s42, s14
	s_mov_b32 m0, s43
	s_nop 0
	global_load_lds_dwordx4 v[212:213], off
	s_add_i32 s42, s15, s42
	v_lshl_add_u64 v[212:213], v[172:173], 0, s[0:1]
	s_mov_b32 m0, s42
	s_nop 0
	global_load_lds_dwordx4 v[212:213], off
	v_lshl_add_u64 v[212:213], v[170:171], 0, s[0:1]
	s_add_i32 s43, s42, 0x400
	s_mov_b32 m0, s43
	s_nop 0
	global_load_lds_dwordx4 v[212:213], off
	v_lshl_add_u64 v[212:213], v[168:169], 0, s[0:1]
	s_add_i32 s43, s42, 0x800
	s_mov_b32 m0, s43
	s_nop 0
	global_load_lds_dwordx4 v[212:213], off
	s_addk_i32 s42, 0xc00
	v_lshl_add_u64 v[212:213], v[166:167], 0, s[0:1]
	s_mov_b32 m0, s42
	s_nop 0
	global_load_lds_dwordx4 v[212:213], off
.Lmy_re_2:
	s_setprio 0
	s_waitcnt lgkmcnt(10)
	v_mfma_f32_16x16x32_bf16 v[34:37], v[196:199], v[180:183], v[34:37]
	s_waitcnt lgkmcnt(9)
	v_mfma_f32_16x16x32_bf16 v[38:41], v[196:199], v[184:187], v[38:41]
	s_waitcnt lgkmcnt(8)
	v_mfma_f32_16x16x32_bf16 v[42:45], v[196:199], v[188:191], v[42:45]
	s_waitcnt lgkmcnt(7)
	v_mfma_f32_16x16x32_bf16 v[46:49], v[196:199], v[192:195], v[46:49]
	s_waitcnt lgkmcnt(6)
	v_mfma_f32_16x16x32_bf16 v[50:53], v[200:203], v[180:183], v[50:53]
	v_mfma_f32_16x16x32_bf16 v[54:57], v[200:203], v[184:187], v[54:57]
	v_mfma_f32_16x16x32_bf16 v[58:61], v[200:203], v[188:191], v[58:61]
	v_mfma_f32_16x16x32_bf16 v[62:65], v[200:203], v[192:195], v[62:65]
	s_waitcnt lgkmcnt(5)
	v_mfma_f32_16x16x32_bf16 v[66:69], v[204:207], v[180:183], v[66:69]
	v_mfma_f32_16x16x32_bf16 v[70:73], v[204:207], v[184:187], v[70:73]
	v_mfma_f32_16x16x32_bf16 v[74:77], v[204:207], v[188:191], v[74:77]
	v_mfma_f32_16x16x32_bf16 v[78:81], v[204:207], v[192:195], v[78:81]
	s_waitcnt lgkmcnt(4)
	v_mfma_f32_16x16x32_bf16 v[82:85], v[208:211], v[180:183], v[82:85]
	v_mfma_f32_16x16x32_bf16 v[86:89], v[208:211], v[184:187], v[86:89]
	v_mfma_f32_16x16x32_bf16 v[90:93], v[208:211], v[188:191], v[90:93]
	v_mfma_f32_16x16x32_bf16 v[94:97], v[208:211], v[192:195], v[94:97]
	s_waitcnt lgkmcnt(3)
	v_mfma_f32_16x16x32_bf16 v[98:101], v[216:219], v[180:183], v[98:101]
	v_mfma_f32_16x16x32_bf16 v[102:105], v[216:219], v[184:187], v[102:105]
	v_mfma_f32_16x16x32_bf16 v[106:109], v[216:219], v[188:191], v[106:109]
	v_mfma_f32_16x16x32_bf16 v[110:113], v[216:219], v[192:195], v[110:113]
	s_waitcnt lgkmcnt(2)
	v_mfma_f32_16x16x32_bf16 v[114:117], v[226:229], v[180:183], v[114:117]
	v_mfma_f32_16x16x32_bf16 v[118:121], v[226:229], v[184:187], v[118:121]
	v_mfma_f32_16x16x32_bf16 v[122:125], v[226:229], v[188:191], v[122:125]
	v_mfma_f32_16x16x32_bf16 v[126:129], v[226:229], v[192:195], v[126:129]
	s_waitcnt lgkmcnt(1)
	v_mfma_f32_16x16x32_bf16 v[130:133], v[230:233], v[180:183], v[130:133]
	v_mfma_f32_16x16x32_bf16 v[134:137], v[230:233], v[184:187], v[134:137]
	v_mfma_f32_16x16x32_bf16 v[138:141], v[230:233], v[188:191], v[138:141]
	v_mfma_f32_16x16x32_bf16 v[142:145], v[230:233], v[192:195], v[142:145]
	s_waitcnt lgkmcnt(0)
	v_mfma_f32_16x16x32_bf16 v[146:149], v[234:237], v[180:183], v[146:149]
	v_mfma_f32_16x16x32_bf16 v[150:153], v[234:237], v[184:187], v[150:153]
	v_mfma_f32_16x16x32_bf16 v[154:157], v[234:237], v[188:191], v[154:157]
	v_mfma_f32_16x16x32_bf16 v[158:161], v[234:237], v[192:195], v[158:161]
	s_cmp_eq_u32 s100, 0
	s_cbranch_scc1 .Lmy_rl_2
	s_setprio 2
	v_lshl_add_u64 v[212:213], v[174:175], 0, s[0:1]
	v_lshl_add_u64 v[212:213], v[162:163], 1, v[212:213]
	s_add_i32 s43, s42, s40
	s_mov_b32 m0, s43
	s_nop 0
	global_load_lds_dwordx4 v[212:213], off
	v_lshl_add_u64 v[212:213], v[174:175], 0, s[0:1]
	v_lshl_add_u64 v[212:213], v[164:165], 1, v[212:213]
	s_add_i32 s43, s42, s14
	s_mov_b32 m0, s43
	s_nop 0
	global_load_lds_dwordx4 v[212:213], off
	s_add_i32 s42, s15, s42
	v_lshl_add_u64 v[212:213], v[172:173], 0, s[0:1]
	s_mov_b32 m0, s42
	s_nop 0
	global_load_lds_dwordx4 v[212:213], off
	v_lshl_add_u64 v[212:213], v[170:171], 0, s[0:1]
	s_add_i32 s43, s42, 0x400
	s_mov_b32 m0, s43
	s_nop 0
	global_load_lds_dwordx4 v[212:213], off
	v_lshl_add_u64 v[212:213], v[168:169], 0, s[0:1]
	s_add_i32 s43, s42, 0x800
	s_mov_b32 m0, s43
	s_nop 0
	global_load_lds_dwordx4 v[212:213], off
	s_addk_i32 s42, 0xc00
	v_lshl_add_u64 v[212:213], v[166:167], 0, s[0:1]
	s_mov_b32 m0, s42
	s_nop 0
	global_load_lds_dwordx4 v[212:213], off
.Lmy_rl_2:
	s_add_i32 s41, s12, 1
	s_cmp_lg_u32 s12, 2
	s_cselect_b32 s12, s41, 0
	s_add_u32 s0, s0, 64
	s_addc_u32 s1, s1, 0
	s_cmpk_eq_i32 s0, 0x780
	s_cbranch_scc0 .LBB0_76
	s_waitcnt vmcnt(6)
	v_mov_b32_e32 v162, v23
	v_mov_b32_e32 v163, v24
	v_mov_b32_e32 v23, v25
	v_mov_b32_e32 v164, v7
	v_mov_b32_e32 v165, v8
	v_pk_add_f32 v[22:23], v[162:163], v[22:23]
	v_mov_b32_e32 v7, v9
	v_pk_add_f32 v[6:7], v[164:165], v[6:7]
	v_add_f32_e32 v0, v22, v23
	v_add_f32_e32 v0, v0, v6
	v_add_f32_e32 v0, v0, v7
	v_fmamk_f32 v0, v0, 0x3a800000, v250
	s_mov_b32 s0, 0x800000
	s_waitcnt vmcnt(4)
	v_mov_b32_e32 v166, v19
	v_mov_b32_e32 v167, v20
	v_mov_b32_e32 v168, v3
	v_mul_f32_e32 v3, 0x4b800000, v0
	v_cmp_gt_f32_e32 vcc, s0, v0
	v_mov_b32_e32 v19, v21
	v_mov_b32_e32 v169, v4
	v_cndmask_b32_e32 v0, v0, v3, vcc
	v_pk_add_f32 v[6:7], v[166:167], v[18:19]
	v_mov_b32_e32 v3, v5
	v_pk_add_f32 v[2:3], v[168:169], v[2:3]
	v_add_f32_e32 v4, v6, v7
	v_add_f32_e32 v2, v4, v2
	v_add_f32_e32 v2, v2, v3
	v_fmamk_f32 v2, v2, 0x3a800000, v250
	v_mul_f32_e32 v3, 0x4b800000, v2
	v_cmp_gt_f32_e64 s[40:41], s0, v2
	s_waitcnt vmcnt(2)
	v_mov_b32_e32 v170, v27
	v_mov_b32_e32 v171, v28
	v_cndmask_b32_e64 v2, v2, v3, s[40:41]
	v_mov_b32_e32 v27, v29
	v_mov_b32_e32 v172, v11
	v_mov_b32_e32 v173, v12
	v_rsq_f32_e32 v179, v2
	v_pk_add_f32 v[2:3], v[170:171], v[26:27]
	v_mov_b32_e32 v11, v13
	v_pk_add_f32 v[4:5], v[172:173], v[10:11]
	v_add_f32_e32 v2, v2, v3
	v_add_f32_e32 v2, v2, v4
	v_add_f32_e32 v2, v2, v5
	v_fmamk_f32 v2, v2, 0x3a800000, v250
	v_mul_f32_e32 v3, 0x4b800000, v2
	v_cmp_gt_f32_e64 s[42:43], s0, v2
	s_waitcnt vmcnt(0)
	v_mov_b32_e32 v174, v31
	v_mov_b32_e32 v175, v32
	v_cndmask_b32_e64 v2, v2, v3, s[42:43]
	v_mov_b32_e32 v31, v33
	v_mov_b32_e32 v180, v15
	v_mov_b32_e32 v181, v16
	v_rsq_f32_e32 v182, v2
	v_pk_add_f32 v[2:3], v[174:175], v[30:31]
	v_mov_b32_e32 v15, v17
	v_pk_add_f32 v[4:5], v[180:181], v[14:15]
	v_add_f32_e32 v2, v2, v3
	v_add_f32_e32 v2, v2, v4
	v_add_f32_e32 v2, v2, v5
	v_fmamk_f32 v2, v2, 0x3a800000, v250
	v_mul_f32_e32 v3, 0x4b800000, v2
	v_cmp_gt_f32_e64 s[44:45], s0, v2
	s_waitcnt vmcnt(6)
	v_add_u32_e32 v183, v178, v176
	s_waitcnt lgkmcnt(0)
	s_barrier
	v_cndmask_b32_e64 v2, v2, v3, s[44:45]
	v_rsq_f32_e32 v180, v2
	ds_read_b128 v[2:5], v183 offset:15360
	ds_read_b128 v[6:9], v183 offset:14336
	ds_read_b128 v[10:13], v183 offset:13312
	ds_read_b128 v[14:17], v183 offset:12288
	ds_read_b128 v[18:21], v183 offset:11264
	ds_read_b128 v[22:25], v183 offset:10240
	ds_read_b128 v[26:29], v183 offset:9216
	ds_read_b128 v[30:33], v183 offset:8192
	v_add3_u32 v178, s13, v177, v176
	ds_read_b128 v[162:165], v178 offset:3072
	ds_read_b128 v[166:169], v178 offset:2048
	ds_read_b128 v[170:173], v178 offset:1024
	ds_read_b128 v[174:177], v178
	v_rsq_f32_e32 v0, v0
	v_mul_f32_e32 v184, 0x45800000, v179
	v_mul_f32_e32 v185, 0x45800000, v182
	v_mul_f32_e32 v186, 0x45800000, v180
	v_mul_f32_e32 v181, 0x45800000, v0
	s_waitcnt lgkmcnt(0)
	v_mfma_f32_16x16x32_bf16 v[34:37], v[30:33], v[174:177], v[34:37]
	v_mfma_f32_16x16x32_bf16 v[38:41], v[30:33], v[170:173], v[38:41]
	v_mfma_f32_16x16x32_bf16 v[42:45], v[30:33], v[166:169], v[42:45]
	v_mfma_f32_16x16x32_bf16 v[46:49], v[30:33], v[162:165], v[46:49]
	v_mfma_f32_16x16x32_bf16 v[50:53], v[26:29], v[174:177], v[50:53]
	v_mfma_f32_16x16x32_bf16 v[54:57], v[26:29], v[170:173], v[54:57]
	v_mfma_f32_16x16x32_bf16 v[58:61], v[26:29], v[166:169], v[58:61]
	v_mfma_f32_16x16x32_bf16 v[62:65], v[26:29], v[162:165], v[62:65]
	v_mfma_f32_16x16x32_bf16 v[66:69], v[22:25], v[174:177], v[66:69]
	v_mfma_f32_16x16x32_bf16 v[70:73], v[22:25], v[170:173], v[70:73]
	v_mfma_f32_16x16x32_bf16 v[74:77], v[22:25], v[166:169], v[74:77]
	v_mfma_f32_16x16x32_bf16 v[22:25], v[22:25], v[162:165], v[78:81]
	v_mfma_f32_16x16x32_bf16 v[78:81], v[18:21], v[174:177], v[82:85]
	v_mfma_f32_16x16x32_bf16 v[82:85], v[18:21], v[170:173], v[86:89]
	v_mfma_f32_16x16x32_bf16 v[86:89], v[18:21], v[166:169], v[90:93]
	v_mfma_f32_16x16x32_bf16 v[18:21], v[18:21], v[162:165], v[94:97]
	v_mfma_f32_16x16x32_bf16 v[90:93], v[14:17], v[174:177], v[98:101]
	v_mfma_f32_16x16x32_bf16 v[94:97], v[14:17], v[170:173], v[102:105]
	v_mfma_f32_16x16x32_bf16 v[98:101], v[14:17], v[166:169], v[106:109]
	v_mfma_f32_16x16x32_bf16 v[14:17], v[14:17], v[162:165], v[110:113]
	v_mfma_f32_16x16x32_bf16 v[102:105], v[10:13], v[174:177], v[114:117]
	v_mfma_f32_16x16x32_bf16 v[106:109], v[10:13], v[170:173], v[118:121]
	v_mfma_f32_16x16x32_bf16 v[110:113], v[10:13], v[166:169], v[122:125]
	v_mfma_f32_16x16x32_bf16 v[10:13], v[10:13], v[162:165], v[126:129]
	v_mfma_f32_16x16x32_bf16 v[114:117], v[6:9], v[174:177], v[130:133]
	v_mfma_f32_16x16x32_bf16 v[118:121], v[6:9], v[170:173], v[134:137]
	v_mfma_f32_16x16x32_bf16 v[122:125], v[6:9], v[166:169], v[138:141]
	v_mfma_f32_16x16x32_bf16 v[6:9], v[6:9], v[162:165], v[142:145]
	v_mfma_f32_16x16x32_bf16 v[126:129], v[2:5], v[174:177], v[146:149]
	v_mfma_f32_16x16x32_bf16 v[130:133], v[2:5], v[170:173], v[150:153]
	v_mfma_f32_16x16x32_bf16 v[134:137], v[2:5], v[166:169], v[154:157]
	v_mfma_f32_16x16x32_bf16 v[2:5], v[2:5], v[162:165], v[158:161]
	s_waitcnt vmcnt(0)
	v_cndmask_b32_e32 v30, v0, v181, vcc
	v_cndmask_b32_e64 v28, v179, v184, s[40:41]
	v_cndmask_b32_e64 v26, v182, v185, s[42:43]
	v_cndmask_b32_e64 v0, v180, v186, s[44:45]
	s_waitcnt lgkmcnt(0)
	s_barrier
	ds_read_b128 v[138:141], v178 offset:24576
	ds_read_b128 v[142:145], v178 offset:25600
	ds_read_b128 v[146:149], v178 offset:26624
	ds_read_b128 v[150:153], v178 offset:27648
	ds_read_b128 v[154:157], v183 offset:32768
	ds_read_b128 v[158:161], v183 offset:33792
	ds_read_b128 v[162:165], v183 offset:34816
	ds_read_b128 v[166:169], v183 offset:35840
	ds_read_b128 v[170:173], v183 offset:36864
	ds_read_b128 v[174:177], v183 offset:37888
	ds_read_b128 v[178:181], v183 offset:38912
	ds_read_b128 v[182:185], v183 offset:39936
	s_waitcnt lgkmcnt(7)
	v_mfma_f32_16x16x32_bf16 v[32:35], v[154:157], v[138:141], v[34:37]
	v_mfma_f32_16x16x32_bf16 v[36:39], v[154:157], v[142:145], v[38:41]
	v_mfma_f32_16x16x32_bf16 v[40:43], v[154:157], v[146:149], v[42:45]
	v_mfma_f32_16x16x32_bf16 v[44:47], v[154:157], v[150:153], v[46:49]
	s_waitcnt lgkmcnt(6)
	v_mfma_f32_16x16x32_bf16 v[48:51], v[158:161], v[138:141], v[50:53]
	v_mfma_f32_16x16x32_bf16 v[52:55], v[158:161], v[142:145], v[54:57]
	v_mfma_f32_16x16x32_bf16 v[56:59], v[158:161], v[146:149], v[58:61]
	v_mfma_f32_16x16x32_bf16 v[60:63], v[158:161], v[150:153], v[62:65]
	s_waitcnt lgkmcnt(5)
	v_mfma_f32_16x16x32_bf16 v[64:67], v[162:165], v[138:141], v[66:69]
	v_mfma_f32_16x16x32_bf16 v[68:71], v[162:165], v[142:145], v[70:73]
	v_mfma_f32_16x16x32_bf16 v[72:75], v[162:165], v[146:149], v[74:77]
	v_mfma_f32_16x16x32_bf16 v[154:157], v[162:165], v[150:153], v[22:25]
	s_waitcnt lgkmcnt(4)
	v_mfma_f32_16x16x32_bf16 v[76:79], v[166:169], v[138:141], v[78:81]
	v_mfma_f32_16x16x32_bf16 v[80:83], v[166:169], v[142:145], v[82:85]
	v_mfma_f32_16x16x32_bf16 v[84:87], v[166:169], v[146:149], v[86:89]
	v_mfma_f32_16x16x32_bf16 v[158:161], v[166:169], v[150:153], v[18:21]
	s_waitcnt lgkmcnt(3)
	v_mfma_f32_16x16x32_bf16 v[88:91], v[170:173], v[138:141], v[90:93]
	v_mfma_f32_16x16x32_bf16 v[92:95], v[170:173], v[142:145], v[94:97]
	v_mfma_f32_16x16x32_bf16 v[96:99], v[170:173], v[146:149], v[98:101]
	v_mfma_f32_16x16x32_bf16 v[162:165], v[170:173], v[150:153], v[14:17]
	s_waitcnt lgkmcnt(2)
	v_mfma_f32_16x16x32_bf16 v[100:103], v[174:177], v[138:141], v[102:105]
	v_mfma_f32_16x16x32_bf16 v[104:107], v[174:177], v[142:145], v[106:109]
	v_mfma_f32_16x16x32_bf16 v[108:111], v[174:177], v[146:149], v[110:113]
	v_mfma_f32_16x16x32_bf16 v[166:169], v[174:177], v[150:153], v[10:13]
	s_waitcnt lgkmcnt(1)
	v_mfma_f32_16x16x32_bf16 v[112:115], v[178:181], v[138:141], v[114:117]
	v_mfma_f32_16x16x32_bf16 v[116:119], v[178:181], v[142:145], v[118:121]
	v_mfma_f32_16x16x32_bf16 v[22:25], v[178:181], v[146:149], v[122:125]
	v_mfma_f32_16x16x32_bf16 v[18:21], v[178:181], v[150:153], v[6:9]
	s_waitcnt lgkmcnt(0)
	v_mfma_f32_16x16x32_bf16 v[14:17], v[182:185], v[138:141], v[126:129]
	v_mfma_f32_16x16x32_bf16 v[10:13], v[182:185], v[142:145], v[130:133]
	v_mfma_f32_16x16x32_bf16 v[6:9], v[182:185], v[146:149], v[134:137]
	v_mfma_f32_16x16x32_bf16 v[2:5], v[182:185], v[150:153], v[2:5]
	v_mov_b32_e32 v27, v224
	s_movk_i32 s0, 0x210
	v_lshrrev_b32_e32 v120, 1, v27
	v_and_b32_e32 v31, 0x7fffff80, v27
	v_and_b32_e32 v120, 24, v120
	v_and_b32_e32 v29, 0x4f, v27
	v_lshl_or_b32 v31, v31, 1, v120
	v_pk_mul_f32 v[32:33], v[30:31], v[32:33] op_sel_hi:[0,1]
	v_pk_mul_f32 v[34:35], v[30:31], v[34:35] op_sel_hi:[0,1]
	v_mad_u32_u24 v29, v29, s0, v31
	v_cvt_pk_bf16_f32 v32, v32, v33
	v_cvt_pk_bf16_f32 v33, v34, v35
	v_pk_mul_f32 v[34:35], v[28:29], v[36:37] op_sel_hi:[0,1]
	v_pk_mul_f32 v[36:37], v[28:29], v[38:39] op_sel_hi:[0,1]
	v_cvt_pk_bf16_f32 v34, v34, v35
	v_cvt_pk_bf16_f32 v35, v36, v37
	v_pk_mul_f32 v[36:37], v[26:27], v[40:41] op_sel_hi:[0,1]
	v_pk_mul_f32 v[38:39], v[26:27], v[42:43] op_sel_hi:[0,1]
	v_cvt_pk_bf16_f32 v36, v36, v37
	v_cvt_pk_bf16_f32 v37, v38, v39
	v_pk_mul_f32 v[38:39], v[0:1], v[44:45] op_sel_hi:[0,1]
	v_pk_mul_f32 v[40:41], v[0:1], v[46:47] op_sel_hi:[0,1]
	v_cvt_pk_bf16_f32 v38, v38, v39
	v_cvt_pk_bf16_f32 v39, v40, v41
	v_pk_mul_f32 v[40:41], v[30:31], v[48:49] op_sel_hi:[0,1]
	v_pk_mul_f32 v[42:43], v[30:31], v[50:51] op_sel_hi:[0,1]
	v_cvt_pk_bf16_f32 v40, v40, v41
	v_cvt_pk_bf16_f32 v41, v42, v43
	s_barrier
	ds_write2_b64 v29, v[32:33], v[40:41] offset1:4
	v_pk_mul_f32 v[32:33], v[28:29], v[52:53] op_sel_hi:[0,1]
	v_pk_mul_f32 v[40:41], v[28:29], v[54:55] op_sel_hi:[0,1]
	v_cvt_pk_bf16_f32 v32, v32, v33
	v_cvt_pk_bf16_f32 v33, v40, v41
	v_add_u32_e32 v31, 0x2000, v29
	ds_write2_b64 v31, v[34:35], v[32:33] offset0:32 offset1:36
	v_pk_mul_f32 v[32:33], v[26:27], v[56:57] op_sel_hi:[0,1]
	v_pk_mul_f32 v[34:35], v[26:27], v[58:59] op_sel_hi:[0,1]
	v_cvt_pk_bf16_f32 v32, v32, v33
	v_cvt_pk_bf16_f32 v33, v34, v35
	v_add_u32_e32 v44, 0x4000, v29
	ds_write2_b64 v44, v[36:37], v[32:33] offset0:64 offset1:68
	v_pk_mul_f32 v[32:33], v[0:1], v[60:61] op_sel_hi:[0,1]
	v_pk_mul_f32 v[34:35], v[0:1], v[62:63] op_sel_hi:[0,1]
	v_cvt_pk_bf16_f32 v32, v32, v33
	v_cvt_pk_bf16_f32 v33, v34, v35
	v_add_u32_e32 v45, 0x6000, v29
	ds_write2_b64 v45, v[38:39], v[32:33] offset0:96 offset1:100
	v_pk_mul_f32 v[32:33], v[30:31], v[64:65] op_sel_hi:[0,1]
	v_pk_mul_f32 v[34:35], v[30:31], v[66:67] op_sel_hi:[0,1]
	v_cvt_pk_bf16_f32 v32, v32, v33
	v_cvt_pk_bf16_f32 v33, v34, v35
	v_pk_mul_f32 v[34:35], v[28:29], v[68:69] op_sel_hi:[0,1]
	v_pk_mul_f32 v[36:37], v[28:29], v[70:71] op_sel_hi:[0,1]
	v_cvt_pk_bf16_f32 v34, v34, v35
	v_cvt_pk_bf16_f32 v35, v36, v37
	v_pk_mul_f32 v[36:37], v[26:27], v[72:73] op_sel_hi:[0,1]
	v_pk_mul_f32 v[38:39], v[26:27], v[74:75] op_sel_hi:[0,1]
	v_cvt_pk_bf16_f32 v36, v36, v37
	v_cvt_pk_bf16_f32 v37, v38, v39
	v_pk_mul_f32 v[38:39], v[0:1], v[154:155] op_sel_hi:[0,1]
	v_pk_mul_f32 v[40:41], v[0:1], v[156:157] op_sel_hi:[0,1]
	v_cvt_pk_bf16_f32 v38, v38, v39
	v_cvt_pk_bf16_f32 v39, v40, v41
	v_pk_mul_f32 v[40:41], v[30:31], v[76:77] op_sel_hi:[0,1]
	v_pk_mul_f32 v[42:43], v[30:31], v[78:79] op_sel_hi:[0,1]
	v_cvt_pk_bf16_f32 v40, v40, v41
	v_cvt_pk_bf16_f32 v41, v42, v43
	ds_write2_b64 v29, v[32:33], v[40:41] offset0:8 offset1:12
	v_pk_mul_f32 v[32:33], v[28:29], v[80:81] op_sel_hi:[0,1]
	v_pk_mul_f32 v[40:41], v[28:29], v[82:83] op_sel_hi:[0,1]
	v_cvt_pk_bf16_f32 v32, v32, v33
	v_cvt_pk_bf16_f32 v33, v40, v41
	ds_write2_b64 v31, v[34:35], v[32:33] offset0:40 offset1:44
	v_pk_mul_f32 v[32:33], v[26:27], v[84:85] op_sel_hi:[0,1]
	v_pk_mul_f32 v[34:35], v[26:27], v[86:87] op_sel_hi:[0,1]
	v_cvt_pk_bf16_f32 v32, v32, v33
	v_cvt_pk_bf16_f32 v33, v34, v35
	ds_write2_b64 v44, v[36:37], v[32:33] offset0:72 offset1:76
	v_pk_mul_f32 v[32:33], v[0:1], v[158:159] op_sel_hi:[0,1]
	v_pk_mul_f32 v[34:35], v[0:1], v[160:161] op_sel_hi:[0,1]
	v_cvt_pk_bf16_f32 v32, v32, v33
	v_cvt_pk_bf16_f32 v33, v34, v35
	ds_write2_b64 v45, v[38:39], v[32:33] offset0:104 offset1:108
	v_pk_mul_f32 v[32:33], v[30:31], v[88:89] op_sel_hi:[0,1]
	v_pk_mul_f32 v[34:35], v[30:31], v[90:91] op_sel_hi:[0,1]
	v_cvt_pk_bf16_f32 v32, v32, v33
	v_cvt_pk_bf16_f32 v33, v34, v35
	v_pk_mul_f32 v[34:35], v[28:29], v[92:93] op_sel_hi:[0,1]
	v_pk_mul_f32 v[36:37], v[28:29], v[94:95] op_sel_hi:[0,1]
	v_cvt_pk_bf16_f32 v34, v34, v35
	v_cvt_pk_bf16_f32 v35, v36, v37
	v_pk_mul_f32 v[36:37], v[26:27], v[96:97] op_sel_hi:[0,1]
	v_pk_mul_f32 v[38:39], v[26:27], v[98:99] op_sel_hi:[0,1]
	v_cvt_pk_bf16_f32 v36, v36, v37
	v_cvt_pk_bf16_f32 v37, v38, v39
	v_pk_mul_f32 v[38:39], v[0:1], v[162:163] op_sel_hi:[0,1]
	v_pk_mul_f32 v[40:41], v[0:1], v[164:165] op_sel_hi:[0,1]
	v_cvt_pk_bf16_f32 v38, v38, v39
	v_cvt_pk_bf16_f32 v39, v40, v41
	v_pk_mul_f32 v[40:41], v[30:31], v[100:101] op_sel_hi:[0,1]
	v_pk_mul_f32 v[42:43], v[30:31], v[102:103] op_sel_hi:[0,1]
	v_cvt_pk_bf16_f32 v40, v40, v41
	v_cvt_pk_bf16_f32 v41, v42, v43
	ds_write2_b64 v29, v[32:33], v[40:41] offset0:16 offset1:20
	v_pk_mul_f32 v[32:33], v[28:29], v[104:105] op_sel_hi:[0,1]
	v_pk_mul_f32 v[40:41], v[28:29], v[106:107] op_sel_hi:[0,1]
	v_cvt_pk_bf16_f32 v32, v32, v33
	v_cvt_pk_bf16_f32 v33, v40, v41
	ds_write2_b64 v31, v[34:35], v[32:33] offset0:48 offset1:52
	v_pk_mul_f32 v[32:33], v[26:27], v[108:109] op_sel_hi:[0,1]
	v_pk_mul_f32 v[34:35], v[26:27], v[110:111] op_sel_hi:[0,1]
	v_cvt_pk_bf16_f32 v32, v32, v33
	v_cvt_pk_bf16_f32 v33, v34, v35
	ds_write2_b64 v44, v[36:37], v[32:33] offset0:80 offset1:84
	v_pk_mul_f32 v[32:33], v[0:1], v[166:167] op_sel_hi:[0,1]
	v_pk_mul_f32 v[34:35], v[0:1], v[168:169] op_sel_hi:[0,1]
	v_cvt_pk_bf16_f32 v32, v32, v33
	v_cvt_pk_bf16_f32 v33, v34, v35
	v_pk_mul_f32 v[18:19], v[0:1], v[18:19] op_sel_hi:[0,1]
	v_pk_mul_f32 v[20:21], v[0:1], v[20:21] op_sel_hi:[0,1]
	v_pk_mul_f32 v[2:3], v[0:1], v[2:3] op_sel_hi:[0,1]
	v_pk_mul_f32 v[4:5], v[0:1], v[4:5] op_sel_hi:[0,1]
	v_lshlrev_b32_e32 v0, 3, v27
	ds_write2_b64 v45, v[38:39], v[32:33] offset0:112 offset1:116
	v_pk_mul_f32 v[32:33], v[30:31], v[112:113] op_sel_hi:[0,1]
	v_pk_mul_f32 v[34:35], v[30:31], v[114:115] op_sel_hi:[0,1]
	v_cvt_pk_bf16_f32 v18, v18, v19
	v_cvt_pk_bf16_f32 v19, v20, v21
	v_cvt_pk_bf16_f32 v2, v2, v3
	v_cvt_pk_bf16_f32 v3, v4, v5
	v_and_b32_e32 v0, 0xf8, v0
	v_cvt_pk_bf16_f32 v32, v32, v33
	v_cvt_pk_bf16_f32 v33, v34, v35
	v_pk_mul_f32 v[34:35], v[28:29], v[116:117] op_sel_hi:[0,1]
	v_pk_mul_f32 v[36:37], v[28:29], v[118:119] op_sel_hi:[0,1]
	v_pk_mul_f32 v[22:23], v[26:27], v[22:23] op_sel_hi:[0,1]
	v_pk_mul_f32 v[24:25], v[26:27], v[24:25] op_sel_hi:[0,1]
	v_pk_mul_f32 v[14:15], v[30:31], v[14:15] op_sel_hi:[0,1]
	v_pk_mul_f32 v[16:17], v[30:31], v[16:17] op_sel_hi:[0,1]
	v_pk_mul_f32 v[10:11], v[28:29], v[10:11] op_sel_hi:[0,1]
	v_pk_mul_f32 v[12:13], v[28:29], v[12:13] op_sel_hi:[0,1]
	v_pk_mul_f32 v[6:7], v[26:27], v[6:7] op_sel_hi:[0,1]
	v_pk_mul_f32 v[8:9], v[26:27], v[8:9] op_sel_hi:[0,1]
	ds_write2_b64 v45, v[18:19], v[2:3] offset0:120 offset1:124
	v_or_b32_e32 v2, s82, v0
	s_movk_i32 s0, 0x800
	v_cvt_pk_bf16_f32 v34, v34, v35
	v_cvt_pk_bf16_f32 v35, v36, v37
	v_cvt_pk_bf16_f32 v22, v22, v23
	v_cvt_pk_bf16_f32 v23, v24, v25
	v_cvt_pk_bf16_f32 v14, v14, v15
	v_cvt_pk_bf16_f32 v15, v16, v17
	v_cvt_pk_bf16_f32 v10, v10, v11
	v_cvt_pk_bf16_f32 v11, v12, v13
	v_cvt_pk_bf16_f32 v6, v6, v7
	v_cvt_pk_bf16_f32 v7, v8, v9
	v_cmp_gt_i32_e64 s[44:45], s0, v2
	s_mov_b64 s[12:13], 12
	s_mov_b64 s[40:41], s[54:55]
	s_mov_b32 s0, s82
	ds_write2_b64 v29, v[32:33], v[14:15] offset0:24 offset1:28
	ds_write2_b64 v31, v[34:35], v[10:11] offset0:56 offset1:60
	ds_write2_b64 v44, v[22:23], v[6:7] offset0:88 offset1:92
	s_waitcnt lgkmcnt(0)
	s_barrier

.LBB0_119:
	s_mul_i32 s68, s1, 0x6000
	s_add_i32 s69, s68, 0xffffa000
	s_cmp_gt_i32 s1, 0
	s_waitcnt vmcnt(6)
	s_cselect_b32 s69, s69, 0xc000
	s_waitcnt lgkmcnt(0)
	s_barrier
	s_setprio 2
	v_or_b32_e32 v0, s68, v146
	v_add_u32_e32 v0, v0, v144
	v_add3_u32 v212, s68, v145, v144
	ds_read_b128 v[164:167], v212 offset:8192
	ds_read_b128 v[148:151], v0
	ds_read_b128 v[152:155], v0 offset:1024
	ds_read_b128 v[156:159], v0 offset:2048
	ds_read_b128 v[160:163], v0 offset:3072
	ds_read_b128 v[168:171], v212 offset:9216
	ds_read_b128 v[172:175], v212 offset:10240
	ds_read_b128 v[176:179], v212 offset:11264
	ds_read_b128 v[180:183], v212 offset:12288
	ds_read_b128 v[184:187], v212 offset:13312
	ds_read_b128 v[188:191], v212 offset:14336
	ds_read_b128 v[192:195], v212 offset:15360
	s_cmp_eq_u32 s100, 0
	s_cbranch_scc0 .Lmy_re_3
	v_lshl_add_u64 v[212:213], v[142:143], 0, s[42:43]
	v_lshl_add_u64 v[212:213], v[130:131], 1, v[212:213]
	s_add_i32 s70, s69, s15
	s_mov_b32 m0, s70
	s_nop 0
	global_load_lds_dwordx4 v[212:213], off
	v_lshl_add_u64 v[212:213], v[142:143], 0, s[42:43]
	v_lshl_add_u64 v[212:213], v[132:133], 1, v[212:213]
	s_add_i32 s70, s69, s13
	s_mov_b32 m0, s70
	s_nop 0
	global_load_lds_dwordx4 v[212:213], off
	s_add_i32 s69, s14, s69
	v_lshl_add_u64 v[212:213], v[140:141], 0, s[42:43]
	s_mov_b32 m0, s69
	s_nop 0
	global_load_lds_dwordx4 v[212:213], off
	v_lshl_add_u64 v[212:213], v[138:139], 0, s[42:43]
	s_add_i32 s70, s69, 0x400
	s_mov_b32 m0, s70
	s_nop 0
	global_load_lds_dwordx4 v[212:213], off
	v_lshl_add_u64 v[212:213], v[136:137], 0, s[42:43]
	s_add_i32 s70, s69, 0x800
	s_mov_b32 m0, s70
	s_nop 0
	global_load_lds_dwordx4 v[212:213], off
	v_lshl_add_u64 v[212:213], v[134:135], 0, s[42:43]
	s_addk_i32 s69, 0xc00
	s_mov_b32 m0, s69
	s_nop 0
	global_load_lds_dwordx4 v[212:213], off
.Lmy_re_3:
	s_setprio 0
	s_waitcnt lgkmcnt(10)
	v_mfma_f32_16x16x32_bf16 v[126:129], v[164:167], v[148:151], v[126:129]
	s_waitcnt lgkmcnt(9)
	v_mfma_f32_16x16x32_bf16 v[122:125], v[164:167], v[152:155], v[122:125]
	s_waitcnt lgkmcnt(8)
	v_mfma_f32_16x16x32_bf16 v[118:121], v[164:167], v[156:159], v[118:121]
	s_waitcnt lgkmcnt(7)
	v_mfma_f32_16x16x32_bf16 v[114:117], v[164:167], v[160:163], v[114:117]
	s_waitcnt lgkmcnt(6)
	v_mfma_f32_16x16x32_bf16 v[110:113], v[168:171], v[148:151], v[110:113]
	v_mfma_f32_16x16x32_bf16 v[106:109], v[168:171], v[152:155], v[106:109]
	v_mfma_f32_16x16x32_bf16 v[102:105], v[168:171], v[156:159], v[102:105]
	v_mfma_f32_16x16x32_bf16 v[98:101], v[168:171], v[160:163], v[98:101]
	s_waitcnt lgkmcnt(5)
	v_mfma_f32_16x16x32_bf16 v[94:97], v[172:175], v[148:151], v[94:97]
	v_mfma_f32_16x16x32_bf16 v[90:93], v[172:175], v[152:155], v[90:93]
	v_mfma_f32_16x16x32_bf16 v[86:89], v[172:175], v[156:159], v[86:89]
	v_mfma_f32_16x16x32_bf16 v[82:85], v[172:175], v[160:163], v[82:85]
	s_waitcnt lgkmcnt(4)
	v_mfma_f32_16x16x32_bf16 v[78:81], v[176:179], v[148:151], v[78:81]
	v_mfma_f32_16x16x32_bf16 v[74:77], v[176:179], v[152:155], v[74:77]
	v_mfma_f32_16x16x32_bf16 v[70:73], v[176:179], v[156:159], v[70:73]
	v_mfma_f32_16x16x32_bf16 v[66:69], v[176:179], v[160:163], v[66:69]
	s_waitcnt lgkmcnt(3)
	v_mfma_f32_16x16x32_bf16 v[62:65], v[180:183], v[148:151], v[62:65]
	v_mfma_f32_16x16x32_bf16 v[58:61], v[180:183], v[152:155], v[58:61]
	v_mfma_f32_16x16x32_bf16 v[54:57], v[180:183], v[156:159], v[54:57]
	v_mfma_f32_16x16x32_bf16 v[50:53], v[180:183], v[160:163], v[50:53]
	s_waitcnt lgkmcnt(2)
	v_mfma_f32_16x16x32_bf16 v[46:49], v[184:187], v[148:151], v[46:49]
	v_mfma_f32_16x16x32_bf16 v[42:45], v[184:187], v[152:155], v[42:45]
	v_mfma_f32_16x16x32_bf16 v[38:41], v[184:187], v[156:159], v[38:41]
	v_mfma_f32_16x16x32_bf16 v[34:37], v[184:187], v[160:163], v[34:37]
	s_waitcnt lgkmcnt(1)
	v_mfma_f32_16x16x32_bf16 v[30:33], v[188:191], v[148:151], v[30:33]
	v_mfma_f32_16x16x32_bf16 v[26:29], v[188:191], v[152:155], v[26:29]
	v_mfma_f32_16x16x32_bf16 v[22:25], v[188:191], v[156:159], v[22:25]
	v_mfma_f32_16x16x32_bf16 v[18:21], v[188:191], v[160:163], v[18:21]
	s_waitcnt lgkmcnt(0)
	v_mfma_f32_16x16x32_bf16 v[14:17], v[192:195], v[148:151], v[14:17]
	v_mfma_f32_16x16x32_bf16 v[10:13], v[192:195], v[152:155], v[10:13]
	v_mfma_f32_16x16x32_bf16 v[6:9], v[192:195], v[156:159], v[6:9]
	v_mfma_f32_16x16x32_bf16 v[2:5], v[192:195], v[160:163], v[2:5]
	s_cmp_eq_u32 s100, 0
	s_cbranch_scc1 .Lmy_rl_3
	s_setprio 2
	v_lshl_add_u64 v[212:213], v[142:143], 0, s[42:43]
	v_lshl_add_u64 v[212:213], v[130:131], 1, v[212:213]
	s_add_i32 s70, s69, s15
	s_mov_b32 m0, s70
	s_nop 0
	global_load_lds_dwordx4 v[212:213], off
	v_lshl_add_u64 v[212:213], v[142:143], 0, s[42:43]
	v_lshl_add_u64 v[212:213], v[132:133], 1, v[212:213]
	s_add_i32 s70, s69, s13
	s_mov_b32 m0, s70
	s_nop 0
	global_load_lds_dwordx4 v[212:213], off
	s_add_i32 s69, s14, s69
	v_lshl_add_u64 v[212:213], v[140:141], 0, s[42:43]
	s_mov_b32 m0, s69
	s_nop 0
	global_load_lds_dwordx4 v[212:213], off
	v_lshl_add_u64 v[212:213], v[138:139], 0, s[42:43]
	s_add_i32 s70, s69, 0x400
	s_mov_b32 m0, s70
	s_nop 0
	global_load_lds_dwordx4 v[212:213], off
	v_lshl_add_u64 v[212:213], v[136:137], 0, s[42:43]
	s_add_i32 s70, s69, 0x800
	s_mov_b32 m0, s70
	s_nop 0
	global_load_lds_dwordx4 v[212:213], off
	v_lshl_add_u64 v[212:213], v[134:135], 0, s[42:43]
	s_addk_i32 s69, 0xc00
	s_mov_b32 m0, s69
	s_nop 0
	global_load_lds_dwordx4 v[212:213], off
.Lmy_rl_3:
	s_add_i32 s68, s1, 1
	s_cmp_lg_u32 s1, 2
	s_cselect_b32 s1, s68, 0
	s_add_u32 s42, s42, 64
	s_addc_u32 s43, s43, 0
	s_cmpk_eq_i32 s42, 0x1500
	s_cbranch_scc0 .LBB0_119
	s_waitcnt vmcnt(6)
	v_add_u32_e32 v0, v146, v144
	v_add_u32_e32 v221, v145, v144
	s_waitcnt lgkmcnt(0)
	s_barrier
	ds_read_b128 v[130:133], v0
	ds_read_b128 v[134:137], v0 offset:1024
	ds_read_b128 v[138:141], v0 offset:2048
	ds_read_b128 v[146:149], v0 offset:3072
	ds_read_b128 v[142:145], v221 offset:8192
	ds_read_b128 v[150:153], v221 offset:9216
	ds_read_b128 v[154:157], v221 offset:10240
	ds_read_b128 v[158:161], v221 offset:11264
	ds_read_b128 v[162:165], v221 offset:12288
	ds_read_b128 v[166:169], v221 offset:13312
	ds_read_b128 v[170:173], v221 offset:14336
	ds_read_b128 v[174:177], v221 offset:15360
	s_waitcnt lgkmcnt(7)
	v_mfma_f32_16x16x32_bf16 v[126:129], v[142:145], v[130:133], v[126:129]
	v_mfma_f32_16x16x32_bf16 v[122:125], v[142:145], v[134:137], v[122:125]
	v_mfma_f32_16x16x32_bf16 v[118:121], v[142:145], v[138:141], v[118:121]
	v_mfma_f32_16x16x32_bf16 v[114:117], v[142:145], v[146:149], v[114:117]
	s_waitcnt lgkmcnt(6)
	v_mfma_f32_16x16x32_bf16 v[110:113], v[150:153], v[130:133], v[110:113]
	v_mfma_f32_16x16x32_bf16 v[106:109], v[150:153], v[134:137], v[106:109]
	v_mfma_f32_16x16x32_bf16 v[102:105], v[150:153], v[138:141], v[102:105]
	v_mfma_f32_16x16x32_bf16 v[98:101], v[150:153], v[146:149], v[98:101]
	s_waitcnt lgkmcnt(5)
	v_mfma_f32_16x16x32_bf16 v[94:97], v[154:157], v[130:133], v[94:97]
	v_mfma_f32_16x16x32_bf16 v[90:93], v[154:157], v[134:137], v[90:93]
	v_mfma_f32_16x16x32_bf16 v[86:89], v[154:157], v[138:141], v[86:89]
	v_mfma_f32_16x16x32_bf16 v[82:85], v[154:157], v[146:149], v[82:85]
	s_waitcnt lgkmcnt(4)
	v_mfma_f32_16x16x32_bf16 v[78:81], v[158:161], v[130:133], v[78:81]
	v_mfma_f32_16x16x32_bf16 v[74:77], v[158:161], v[134:137], v[74:77]
	v_mfma_f32_16x16x32_bf16 v[70:73], v[158:161], v[138:141], v[70:73]
	v_mfma_f32_16x16x32_bf16 v[66:69], v[158:161], v[146:149], v[66:69]
	s_waitcnt lgkmcnt(3)
	v_mfma_f32_16x16x32_bf16 v[142:145], v[162:165], v[130:133], v[62:65]
	v_mfma_f32_16x16x32_bf16 v[150:153], v[162:165], v[134:137], v[58:61]
	v_mfma_f32_16x16x32_bf16 v[154:157], v[162:165], v[138:141], v[54:57]
	v_mfma_f32_16x16x32_bf16 v[158:161], v[162:165], v[146:149], v[50:53]
	s_waitcnt lgkmcnt(2)
	v_mfma_f32_16x16x32_bf16 v[162:165], v[166:169], v[130:133], v[46:49]
	v_mfma_f32_16x16x32_bf16 v[178:181], v[166:169], v[134:137], v[42:45]
	v_mfma_f32_16x16x32_bf16 v[182:185], v[166:169], v[138:141], v[38:41]
	v_mfma_f32_16x16x32_bf16 v[166:169], v[166:169], v[146:149], v[34:37]
	s_waitcnt lgkmcnt(1)
	v_mfma_f32_16x16x32_bf16 v[186:189], v[170:173], v[130:133], v[30:33]
	v_mfma_f32_16x16x32_bf16 v[190:193], v[170:173], v[134:137], v[26:29]
	v_mfma_f32_16x16x32_bf16 v[194:197], v[170:173], v[138:141], v[22:25]
	v_mfma_f32_16x16x32_bf16 v[170:173], v[170:173], v[146:149], v[18:21]
	s_waitcnt lgkmcnt(0)
	v_mfma_f32_16x16x32_bf16 v[130:133], v[174:177], v[130:133], v[14:17]
	v_mfma_f32_16x16x32_bf16 v[134:137], v[174:177], v[134:137], v[10:13]
	v_mfma_f32_16x16x32_bf16 v[138:141], v[174:177], v[138:141], v[6:9]
	v_mfma_f32_16x16x32_bf16 v[146:149], v[174:177], v[146:149], v[2:5]
	s_waitcnt vmcnt(0)
	s_waitcnt lgkmcnt(0)
	s_barrier
	ds_read_b128 v[174:177], v0 offset:24576
	ds_read_b128 v[198:201], v0 offset:25600
	ds_read_b128 v[202:205], v0 offset:26624
	ds_read_b128 v[206:209], v0 offset:27648
	ds_read_b128 v[14:17], v221 offset:32768
	ds_read_b128 v[30:33], v221 offset:33792
	ds_read_b128 v[46:49], v221 offset:34816
	ds_read_b128 v[62:65], v221 offset:35840
	ds_read_b128 v[210:213], v221 offset:36864
	ds_read_b128 v[216:219], v221 offset:37888
	ds_read_b128 v[226:229], v221 offset:38912
	ds_read_b128 v[230:233], v221 offset:39936
	s_waitcnt lgkmcnt(7)
	v_mfma_f32_16x16x32_bf16 v[2:5], v[14:17], v[174:177], v[126:129]
	v_mfma_f32_16x16x32_bf16 v[6:9], v[14:17], v[198:201], v[122:125]
	v_mfma_f32_16x16x32_bf16 v[10:13], v[14:17], v[202:205], v[118:121]
	v_mfma_f32_16x16x32_bf16 v[14:17], v[14:17], v[206:209], v[114:117]
	s_waitcnt lgkmcnt(6)
	v_mfma_f32_16x16x32_bf16 v[18:21], v[30:33], v[174:177], v[110:113]
	v_mfma_f32_16x16x32_bf16 v[22:25], v[30:33], v[198:201], v[106:109]
	v_mfma_f32_16x16x32_bf16 v[26:29], v[30:33], v[202:205], v[102:105]
	v_mfma_f32_16x16x32_bf16 v[30:33], v[30:33], v[206:209], v[98:101]
	s_waitcnt lgkmcnt(5)
	v_mfma_f32_16x16x32_bf16 v[34:37], v[46:49], v[174:177], v[94:97]
	v_mfma_f32_16x16x32_bf16 v[38:41], v[46:49], v[198:201], v[90:93]
	v_mfma_f32_16x16x32_bf16 v[42:45], v[46:49], v[202:205], v[86:89]
	v_mfma_f32_16x16x32_bf16 v[46:49], v[46:49], v[206:209], v[82:85]
	s_waitcnt lgkmcnt(4)
	v_mfma_f32_16x16x32_bf16 v[50:53], v[62:65], v[174:177], v[78:81]
	v_mfma_f32_16x16x32_bf16 v[54:57], v[62:65], v[198:201], v[74:77]
	v_mfma_f32_16x16x32_bf16 v[58:61], v[62:65], v[202:205], v[70:73]
	v_mfma_f32_16x16x32_bf16 v[62:65], v[62:65], v[206:209], v[66:69]
	s_waitcnt lgkmcnt(3)
	v_mfma_f32_16x16x32_bf16 v[66:69], v[210:213], v[174:177], v[142:145]
	v_mfma_f32_16x16x32_bf16 v[70:73], v[210:213], v[198:201], v[150:153]
	v_mfma_f32_16x16x32_bf16 v[74:77], v[210:213], v[202:205], v[154:157]
	v_mfma_f32_16x16x32_bf16 v[78:81], v[210:213], v[206:209], v[158:161]
	s_waitcnt lgkmcnt(2)
	v_mfma_f32_16x16x32_bf16 v[82:85], v[216:219], v[174:177], v[162:165]
	v_mfma_f32_16x16x32_bf16 v[86:89], v[216:219], v[198:201], v[178:181]
	v_mfma_f32_16x16x32_bf16 v[90:93], v[216:219], v[202:205], v[182:185]
	v_mfma_f32_16x16x32_bf16 v[94:97], v[216:219], v[206:209], v[166:169]
	s_waitcnt lgkmcnt(1)
	v_mfma_f32_16x16x32_bf16 v[98:101], v[226:229], v[174:177], v[186:189]
	v_mfma_f32_16x16x32_bf16 v[102:105], v[226:229], v[198:201], v[190:193]
	v_mfma_f32_16x16x32_bf16 v[106:109], v[226:229], v[202:205], v[194:197]
	v_mfma_f32_16x16x32_bf16 v[110:113], v[226:229], v[206:209], v[170:173]
	s_waitcnt lgkmcnt(0)
	v_mfma_f32_16x16x32_bf16 v[114:117], v[230:233], v[174:177], v[130:133]
	v_mfma_f32_16x16x32_bf16 v[118:121], v[230:233], v[198:201], v[134:137]
	v_mfma_f32_16x16x32_bf16 v[122:125], v[230:233], v[202:205], v[138:141]
	v_mfma_f32_16x16x32_bf16 v[126:129], v[230:233], v[206:209], v[146:149]
	v_mov_b32_e32 v130, v224
	s_ashr_i32 s13, s12, 31
	v_and_b32_e32 v131, 31, v130
	v_ashrrev_i32_e32 v197, 7, v130
	v_ashrrev_i32_e32 v132, 5, v130
	v_lshlrev_b32_e32 v0, 2, v131
	s_lshl_b64 s[68:69], s[12:13], 11
	v_lshlrev_b32_e32 v164, 4, v131
	v_cmp_eq_u32_e64 s[42:43], 0, v131
	v_and_b32_e32 v131, 0x4f, v130
	v_and_b32_e32 v130, 48, v130
	s_movk_i32 s13, 0x210
	v_cmp_lt_i32_e32 vcc, v247, v214
	v_mad_u32_u24 v202, v131, s13, v130
	s_ashr_i32 s1, s0, 31
	v_cndmask_b32_e32 v130, v225, v247, vcc
	v_cmp_lt_i32_e32 vcc, v248, v214
	v_lshlrev_b32_e32 v203, 2, v130
	s_lshl_b32 s70, s87, 1
	v_cndmask_b32_e32 v130, v225, v248, vcc
	v_cmp_lt_i32_e32 vcc, v249, v214
	v_lshlrev_b32_e32 v204, 2, v130
	v_lshl_or_b32 v0, v132, 10, v0
	v_cndmask_b32_e32 v130, v225, v249, vcc
	v_cmp_lt_i32_e32 vcc, v223, v214
	v_lshlrev_b32_e32 v205, 2, v130
	v_mul_lo_u32 v165, v132, s13
	v_cndmask_b32_e32 v130, v225, v223, vcc
	v_cmp_lt_i32_e32 vcc, v252, v214
	v_lshlrev_b32_e32 v206, 2, v130
	s_mov_b32 s14, 0
	v_cndmask_b32_e32 v130, v225, v252, vcc
	v_lshlrev_b32_e32 v207, 2, v130
	v_add_u32_e32 v130, s12, v132
	v_ashrrev_i32_e32 v131, 31, v130
	s_add_u32 s12, s74, s68
	v_lshlrev_b64 v[132:133], 5, v[130:131]
	v_add_u32_e32 v134, 8, v130
	v_add_u32_e32 v136, 16, v130
	v_add_u32_e32 v138, 24, v130
	v_add_u32_e32 v140, 32, v130
	v_add_u32_e32 v142, 40, v130
	v_add_u32_e32 v144, 48, v130
	v_add_u32_e32 v146, 56, v130
	v_add_u32_e32 v148, 64, v130
	v_add_u32_e32 v150, 0x48, v130
	v_add_u32_e32 v152, 0x50, v130
	v_add_u32_e32 v154, 0x58, v130
	v_add_u32_e32 v156, 0x60, v130
	v_add_u32_e32 v158, 0x68, v130
	v_add_u32_e32 v160, 0x70, v130
	v_add_u32_e32 v130, 0x78, v130
	s_addc_u32 s13, s75, s69
	s_lshl_b64 s[0:1], s[0:1], 1
	v_ashrrev_i32_e32 v135, 31, v134
	v_ashrrev_i32_e32 v137, 31, v136
	v_ashrrev_i32_e32 v139, 31, v138
	v_ashrrev_i32_e32 v141, 31, v140
	v_ashrrev_i32_e32 v143, 31, v142
	v_ashrrev_i32_e32 v145, 31, v144
	v_ashrrev_i32_e32 v147, 31, v146
	v_ashrrev_i32_e32 v149, 31, v148
	v_ashrrev_i32_e32 v151, 31, v150
	v_ashrrev_i32_e32 v153, 31, v152
	v_ashrrev_i32_e32 v155, 31, v154
	v_ashrrev_i32_e32 v157, 31, v156
	v_ashrrev_i32_e32 v159, 31, v158
	v_ashrrev_i32_e32 v161, 31, v160
	v_ashrrev_i32_e32 v131, 31, v130
	s_add_u32 s0, s12, s0
	v_lshlrev_b64 v[134:135], 5, v[134:135]
	v_lshlrev_b64 v[136:137], 5, v[136:137]
	v_lshlrev_b64 v[138:139], 5, v[138:139]
	v_lshlrev_b64 v[140:141], 5, v[140:141]
	v_lshlrev_b64 v[142:143], 5, v[142:143]
	v_lshlrev_b64 v[144:145], 5, v[144:145]
	v_lshlrev_b64 v[146:147], 5, v[146:147]
	v_lshlrev_b64 v[148:149], 5, v[148:149]
	v_lshlrev_b64 v[150:151], 5, v[150:151]
	v_lshlrev_b64 v[152:153], 5, v[152:153]
	v_lshlrev_b64 v[154:155], 5, v[154:155]
	v_lshlrev_b64 v[156:157], 5, v[156:157]
	v_lshlrev_b64 v[158:159], 5, v[158:159]
	v_lshlrev_b64 v[160:161], 5, v[160:161]
	v_lshlrev_b64 v[162:163], 5, v[130:131]
	s_addc_u32 s1, s13, s1
	v_lshl_add_u64 v[130:131], v[0:1], 1, s[0:1]
	v_lshl_add_u64 v[132:133], s[44:45], 0, v[132:133]
	v_lshl_add_u64 v[134:135], s[44:45], 0, v[134:135]
	v_lshl_add_u64 v[136:137], s[44:45], 0, v[136:137]
	v_lshl_add_u64 v[138:139], s[44:45], 0, v[138:139]
	v_lshl_add_u64 v[140:141], s[44:45], 0, v[140:141]
	v_lshl_add_u64 v[142:143], s[44:45], 0, v[142:143]
	v_lshl_add_u64 v[144:145], s[44:45], 0, v[144:145]
	v_lshl_add_u64 v[146:147], s[44:45], 0, v[146:147]
	v_lshl_add_u64 v[148:149], s[44:45], 0, v[148:149]
	v_lshl_add_u64 v[150:151], s[44:45], 0, v[150:151]
	v_lshl_add_u64 v[152:153], s[44:45], 0, v[152:153]
	v_lshl_add_u64 v[154:155], s[44:45], 0, v[154:155]
	v_lshl_add_u64 v[156:157], s[44:45], 0, v[156:157]
	v_lshl_add_u64 v[158:159], s[44:45], 0, v[158:159]
	v_lshl_add_u64 v[160:161], s[44:45], 0, v[160:161]
	v_lshl_add_u64 v[162:163], s[44:45], 0, v[162:163]
	s_mov_b64 s[0:1], -1
	v_add_u32_e32 v0, v164, v165
	s_branch .LBB0_122

.LBB0_167:
	s_mul_i32 s4, s43, 0x6000
	s_add_i32 s5, s4, 0xffffa000
	s_cmp_gt_i32 s43, 0
	s_waitcnt vmcnt(6)
	s_cselect_b32 s5, s5, 0xc000
	s_waitcnt lgkmcnt(0)
	s_barrier
	s_setprio 2
	v_add3_u32 v0, s4, v177, v176
	v_add_u32_e32 v0, s47, v0
	v_add3_u32 v212, s4, v178, v176
	ds_read_b128 v[196:199], v212 offset:8192
	ds_read_b128 v[180:183], v0
	ds_read_b128 v[184:187], v0 offset:1024
	ds_read_b128 v[188:191], v0 offset:2048
	ds_read_b128 v[192:195], v0 offset:3072
	ds_read_b128 v[200:203], v212 offset:9216
	ds_read_b128 v[204:207], v212 offset:10240
	ds_read_b128 v[208:211], v212 offset:11264
	ds_read_b128 v[216:219], v212 offset:12288
	ds_read_b128 v[226:229], v212 offset:13312
	ds_read_b128 v[230:233], v212 offset:14336
	ds_read_b128 v[234:237], v212 offset:15360
	s_cmp_eq_u32 s100, 0
	s_cbranch_scc0 .Lmy_re_4
	v_lshl_add_u64 v[212:213], v[174:175], 0, s[12:13]
	v_lshl_add_u64 v[212:213], v[162:163], 1, v[212:213]
	s_add_i32 s44, s5, s42
	s_mov_b32 m0, s44
	s_nop 0
	global_load_lds_dwordx4 v[212:213], off
	v_lshl_add_u64 v[212:213], v[174:175], 0, s[12:13]
	v_lshl_add_u64 v[212:213], v[164:165], 1, v[212:213]
	s_add_i32 s44, s5, s40
	s_mov_b32 m0, s44
	s_nop 0
	global_load_lds_dwordx4 v[212:213], off
	s_add_i32 s5, s41, s5
	v_lshl_add_u64 v[212:213], v[172:173], 0, s[12:13]
	s_mov_b32 m0, s5
	s_nop 0
	global_load_lds_dwordx4 v[212:213], off
	v_lshl_add_u64 v[212:213], v[170:171], 0, s[12:13]
	s_add_i32 s44, s5, 0x400
	s_mov_b32 m0, s44
	s_nop 0
	global_load_lds_dwordx4 v[212:213], off
	v_lshl_add_u64 v[212:213], v[168:169], 0, s[12:13]
	s_add_i32 s44, s5, 0x800
	s_mov_b32 m0, s44
	s_nop 0
	global_load_lds_dwordx4 v[212:213], off
	s_addk_i32 s5, 0xc00
	v_lshl_add_u64 v[212:213], v[166:167], 0, s[12:13]
	s_mov_b32 m0, s5
	s_nop 0
	global_load_lds_dwordx4 v[212:213], off
.Lmy_re_4:
	s_setprio 0
	s_waitcnt lgkmcnt(10)
	v_mfma_f32_16x16x32_bf16 v[34:37], v[196:199], v[180:183], v[34:37]
	s_waitcnt lgkmcnt(9)
	v_mfma_f32_16x16x32_bf16 v[38:41], v[196:199], v[184:187], v[38:41]
	s_waitcnt lgkmcnt(8)
	v_mfma_f32_16x16x32_bf16 v[42:45], v[196:199], v[188:191], v[42:45]
	s_waitcnt lgkmcnt(7)
	v_mfma_f32_16x16x32_bf16 v[46:49], v[196:199], v[192:195], v[46:49]
	s_waitcnt lgkmcnt(6)
	v_mfma_f32_16x16x32_bf16 v[50:53], v[200:203], v[180:183], v[50:53]
	v_mfma_f32_16x16x32_bf16 v[54:57], v[200:203], v[184:187], v[54:57]
	v_mfma_f32_16x16x32_bf16 v[58:61], v[200:203], v[188:191], v[58:61]
	v_mfma_f32_16x16x32_bf16 v[62:65], v[200:203], v[192:195], v[62:65]
	s_waitcnt lgkmcnt(5)
	v_mfma_f32_16x16x32_bf16 v[66:69], v[204:207], v[180:183], v[66:69]
	v_mfma_f32_16x16x32_bf16 v[70:73], v[204:207], v[184:187], v[70:73]
	v_mfma_f32_16x16x32_bf16 v[74:77], v[204:207], v[188:191], v[74:77]
	v_mfma_f32_16x16x32_bf16 v[78:81], v[204:207], v[192:195], v[78:81]
	s_waitcnt lgkmcnt(4)
	v_mfma_f32_16x16x32_bf16 v[82:85], v[208:211], v[180:183], v[82:85]
	v_mfma_f32_16x16x32_bf16 v[86:89], v[208:211], v[184:187], v[86:89]
	v_mfma_f32_16x16x32_bf16 v[90:93], v[208:211], v[188:191], v[90:93]
	v_mfma_f32_16x16x32_bf16 v[94:97], v[208:211], v[192:195], v[94:97]
	s_waitcnt lgkmcnt(3)
	v_mfma_f32_16x16x32_bf16 v[98:101], v[216:219], v[180:183], v[98:101]
	v_mfma_f32_16x16x32_bf16 v[102:105], v[216:219], v[184:187], v[102:105]
	v_mfma_f32_16x16x32_bf16 v[106:109], v[216:219], v[188:191], v[106:109]
	v_mfma_f32_16x16x32_bf16 v[110:113], v[216:219], v[192:195], v[110:113]
	s_waitcnt lgkmcnt(2)
	v_mfma_f32_16x16x32_bf16 v[114:117], v[226:229], v[180:183], v[114:117]
	v_mfma_f32_16x16x32_bf16 v[118:121], v[226:229], v[184:187], v[118:121]
	v_mfma_f32_16x16x32_bf16 v[122:125], v[226:229], v[188:191], v[122:125]
	v_mfma_f32_16x16x32_bf16 v[126:129], v[226:229], v[192:195], v[126:129]
	s_waitcnt lgkmcnt(1)
	v_mfma_f32_16x16x32_bf16 v[130:133], v[230:233], v[180:183], v[130:133]
	v_mfma_f32_16x16x32_bf16 v[134:137], v[230:233], v[184:187], v[134:137]
	v_mfma_f32_16x16x32_bf16 v[138:141], v[230:233], v[188:191], v[138:141]
	v_mfma_f32_16x16x32_bf16 v[142:145], v[230:233], v[192:195], v[142:145]
	s_waitcnt lgkmcnt(0)
	v_mfma_f32_16x16x32_bf16 v[146:149], v[234:237], v[180:183], v[146:149]
	v_mfma_f32_16x16x32_bf16 v[150:153], v[234:237], v[184:187], v[150:153]
	v_mfma_f32_16x16x32_bf16 v[154:157], v[234:237], v[188:191], v[154:157]
	v_mfma_f32_16x16x32_bf16 v[158:161], v[234:237], v[192:195], v[158:161]
	s_cmp_eq_u32 s100, 0
	s_cbranch_scc1 .Lmy_rl_4
	s_setprio 2
	v_lshl_add_u64 v[212:213], v[174:175], 0, s[12:13]
	v_lshl_add_u64 v[212:213], v[162:163], 1, v[212:213]
	s_add_i32 s44, s5, s42
	s_mov_b32 m0, s44
	s_nop 0
	global_load_lds_dwordx4 v[212:213], off
	v_lshl_add_u64 v[212:213], v[174:175], 0, s[12:13]
	v_lshl_add_u64 v[212:213], v[164:165], 1, v[212:213]
	s_add_i32 s44, s5, s40
	s_mov_b32 m0, s44
	s_nop 0
	global_load_lds_dwordx4 v[212:213], off
	s_add_i32 s5, s41, s5
	v_lshl_add_u64 v[212:213], v[172:173], 0, s[12:13]
	s_mov_b32 m0, s5
	s_nop 0
	global_load_lds_dwordx4 v[212:213], off
	v_lshl_add_u64 v[212:213], v[170:171], 0, s[12:13]
	s_add_i32 s44, s5, 0x400
	s_mov_b32 m0, s44
	s_nop 0
	global_load_lds_dwordx4 v[212:213], off
	v_lshl_add_u64 v[212:213], v[168:169], 0, s[12:13]
	s_add_i32 s44, s5, 0x800
	s_mov_b32 m0, s44
	s_nop 0
	global_load_lds_dwordx4 v[212:213], off
	s_addk_i32 s5, 0xc00
	v_lshl_add_u64 v[212:213], v[166:167], 0, s[12:13]
	s_mov_b32 m0, s5
	s_nop 0
	global_load_lds_dwordx4 v[212:213], off
.Lmy_rl_4:
	s_add_i32 s4, s43, 1
	s_cmp_lg_u32 s43, 2
	s_cselect_b32 s43, s4, 0
	s_add_u32 s12, s12, 64
	s_addc_u32 s13, s13, 0
	s_cmpk_eq_i32 s12, 0x780
	s_cbranch_scc0 .LBB0_167
	s_waitcnt vmcnt(6)
	v_mov_b32_e32 v162, v23
	v_mov_b32_e32 v163, v24
	v_mov_b32_e32 v23, v25
	v_mov_b32_e32 v164, v7
	v_mov_b32_e32 v165, v8
	v_pk_add_f32 v[22:23], v[162:163], v[22:23]
	v_mov_b32_e32 v7, v9
	v_pk_add_f32 v[6:7], v[164:165], v[6:7]
	v_add_f32_e32 v0, v22, v23
	v_add_f32_e32 v0, v0, v6
	v_add_f32_e32 v0, v0, v7
	v_fmamk_f32 v0, v0, 0x3a800000, v250
	s_mov_b32 s4, 0x800000
	s_waitcnt vmcnt(4)
	v_mov_b32_e32 v166, v19
	v_mov_b32_e32 v167, v20
	v_mov_b32_e32 v168, v3
	v_mul_f32_e32 v3, 0x4b800000, v0
	v_cmp_gt_f32_e32 vcc, s4, v0
	v_mov_b32_e32 v19, v21
	v_mov_b32_e32 v169, v4
	v_cndmask_b32_e32 v0, v0, v3, vcc
	v_pk_add_f32 v[6:7], v[166:167], v[18:19]
	v_mov_b32_e32 v3, v5
	v_pk_add_f32 v[2:3], v[168:169], v[2:3]
	v_add_f32_e32 v4, v6, v7
	v_add_f32_e32 v2, v4, v2
	v_add_f32_e32 v2, v2, v3
	v_fmamk_f32 v2, v2, 0x3a800000, v250
	v_mul_f32_e32 v3, 0x4b800000, v2
	v_cmp_gt_f32_e64 s[40:41], s4, v2
	s_waitcnt vmcnt(2)
	v_mov_b32_e32 v170, v27
	v_mov_b32_e32 v171, v28
	v_cndmask_b32_e64 v2, v2, v3, s[40:41]
	v_mov_b32_e32 v27, v29
	v_mov_b32_e32 v172, v11
	v_mov_b32_e32 v173, v12
	v_rsq_f32_e32 v182, v2
	v_pk_add_f32 v[2:3], v[170:171], v[26:27]
	v_mov_b32_e32 v11, v13
	v_pk_add_f32 v[4:5], v[172:173], v[10:11]
	v_add_f32_e32 v2, v2, v3
	v_add_f32_e32 v2, v2, v4
	v_add_f32_e32 v2, v2, v5
	v_fmamk_f32 v2, v2, 0x3a800000, v250
	v_mul_f32_e32 v3, 0x4b800000, v2
	v_cmp_gt_f32_e64 s[42:43], s4, v2
	s_waitcnt vmcnt(0)
	v_mov_b32_e32 v174, v31
	v_mov_b32_e32 v175, v32
	v_cndmask_b32_e64 v2, v2, v3, s[42:43]
	v_mov_b32_e32 v31, v33
	v_mov_b32_e32 v180, v15
	v_mov_b32_e32 v181, v16
	v_rsq_f32_e32 v183, v2
	v_pk_add_f32 v[2:3], v[174:175], v[30:31]
	v_mov_b32_e32 v15, v17
	v_pk_add_f32 v[4:5], v[180:181], v[14:15]
	v_add_f32_e32 v2, v2, v3
	v_add_f32_e32 v2, v2, v4
	v_add_f32_e32 v2, v2, v5
	v_fmamk_f32 v2, v2, 0x3a800000, v250
	v_mul_f32_e32 v3, 0x4b800000, v2
	v_cmp_gt_f32_e64 s[44:45], s4, v2
	s_waitcnt vmcnt(6)
	v_add_u32_e32 v185, v178, v176
	s_waitcnt lgkmcnt(0)
	s_barrier
	v_cndmask_b32_e64 v2, v2, v3, s[44:45]
	v_rsq_f32_e32 v184, v2
	ds_read_b128 v[2:5], v185 offset:15360
	ds_read_b128 v[6:9], v185 offset:14336
	ds_read_b128 v[10:13], v185 offset:13312
	ds_read_b128 v[14:17], v185 offset:12288
	ds_read_b128 v[18:21], v185 offset:11264
	ds_read_b128 v[22:25], v185 offset:10240
	ds_read_b128 v[26:29], v185 offset:9216
	ds_read_b128 v[30:33], v185 offset:8192
	v_add3_u32 v186, s47, v177, v176
	ds_read_b128 v[162:165], v186 offset:3072
	ds_read_b128 v[166:169], v186 offset:2048
	ds_read_b128 v[170:173], v186 offset:1024
	ds_read_b128 v[174:177], v186
	v_rsq_f32_e32 v0, v0
	v_mul_f32_e32 v188, 0x45800000, v182
	v_mul_f32_e32 v189, 0x45800000, v183
	v_mul_f32_e32 v190, 0x45800000, v184
	v_mul_f32_e32 v187, 0x45800000, v0
	s_waitcnt lgkmcnt(0)
	v_mfma_f32_16x16x32_bf16 v[34:37], v[30:33], v[174:177], v[34:37]
	v_mfma_f32_16x16x32_bf16 v[38:41], v[30:33], v[170:173], v[38:41]
	v_mfma_f32_16x16x32_bf16 v[178:181], v[30:33], v[166:169], v[42:45]
	v_mfma_f32_16x16x32_bf16 v[30:33], v[30:33], v[162:165], v[46:49]
	v_mfma_f32_16x16x32_bf16 v[48:51], v[26:29], v[174:177], v[50:53]
	v_mfma_f32_16x16x32_bf16 v[52:55], v[26:29], v[170:173], v[54:57]
	v_mfma_f32_16x16x32_bf16 v[56:59], v[26:29], v[166:169], v[58:61]
	v_mfma_f32_16x16x32_bf16 v[26:29], v[26:29], v[162:165], v[62:65]
	v_mfma_f32_16x16x32_bf16 v[60:63], v[22:25], v[174:177], v[66:69]
	v_mfma_f32_16x16x32_bf16 v[64:67], v[22:25], v[170:173], v[70:73]
	v_mfma_f32_16x16x32_bf16 v[68:71], v[22:25], v[166:169], v[74:77]
	v_mfma_f32_16x16x32_bf16 v[22:25], v[22:25], v[162:165], v[78:81]
	v_mfma_f32_16x16x32_bf16 v[72:75], v[18:21], v[174:177], v[82:85]
	v_mfma_f32_16x16x32_bf16 v[76:79], v[18:21], v[170:173], v[86:89]
	v_mfma_f32_16x16x32_bf16 v[80:83], v[18:21], v[166:169], v[90:93]
	v_mfma_f32_16x16x32_bf16 v[18:21], v[18:21], v[162:165], v[94:97]
	v_mfma_f32_16x16x32_bf16 v[84:87], v[14:17], v[174:177], v[98:101]
	v_mfma_f32_16x16x32_bf16 v[88:91], v[14:17], v[170:173], v[102:105]
	v_mfma_f32_16x16x32_bf16 v[92:95], v[14:17], v[166:169], v[106:109]
	v_mfma_f32_16x16x32_bf16 v[14:17], v[14:17], v[162:165], v[110:113]
	v_mfma_f32_16x16x32_bf16 v[96:99], v[10:13], v[174:177], v[114:117]
	v_mfma_f32_16x16x32_bf16 v[100:103], v[10:13], v[170:173], v[118:121]
	v_mfma_f32_16x16x32_bf16 v[104:107], v[10:13], v[166:169], v[122:125]
	v_mfma_f32_16x16x32_bf16 v[10:13], v[10:13], v[162:165], v[126:129]
	v_mfma_f32_16x16x32_bf16 v[108:111], v[6:9], v[174:177], v[130:133]
	v_mfma_f32_16x16x32_bf16 v[112:115], v[6:9], v[170:173], v[134:137]
	v_mfma_f32_16x16x32_bf16 v[116:119], v[6:9], v[166:169], v[138:141]
	v_mfma_f32_16x16x32_bf16 v[120:123], v[2:5], v[174:177], v[146:149]
	v_mfma_f32_16x16x32_bf16 v[124:127], v[2:5], v[170:173], v[150:153]
	v_mfma_f32_16x16x32_bf16 v[128:131], v[2:5], v[166:169], v[154:157]
	v_mfma_f32_16x16x32_bf16 v[6:9], v[6:9], v[162:165], v[142:145]
	v_mfma_f32_16x16x32_bf16 v[2:5], v[2:5], v[162:165], v[158:161]
	s_waitcnt vmcnt(0)
	v_cndmask_b32_e32 v46, v0, v187, vcc
	v_cndmask_b32_e64 v44, v182, v188, s[40:41]
	v_cndmask_b32_e64 v42, v183, v189, s[42:43]
	v_cndmask_b32_e64 v0, v184, v190, s[44:45]
	s_waitcnt lgkmcnt(0)
	s_barrier
	ds_read_b128 v[132:135], v186 offset:24576
	ds_read_b128 v[136:139], v186 offset:25600
	ds_read_b128 v[140:143], v186 offset:26624
	ds_read_b128 v[144:147], v186 offset:27648
	ds_read_b128 v[148:151], v185 offset:32768
	ds_read_b128 v[152:155], v185 offset:33792
	ds_read_b128 v[156:159], v185 offset:34816
	ds_read_b128 v[160:163], v185 offset:35840
	ds_read_b128 v[164:167], v185 offset:36864
	ds_read_b128 v[168:171], v185 offset:37888
	ds_read_b128 v[172:175], v185 offset:38912
	ds_read_b128 v[182:185], v185 offset:39936
	s_waitcnt lgkmcnt(4)
	v_mfma_f32_16x16x32_bf16 v[242:245], v[160:163], v[140:143], v[80:83]
	v_mfma_f32_16x16x32_bf16 v[246:249], v[160:163], v[144:147], v[18:21]
	s_waitcnt lgkmcnt(3)
	v_mfma_f32_16x16x32_bf16 v[210:213], v[164:167], v[132:135], v[84:87]
	v_mfma_f32_16x16x32_bf16 v[194:197], v[164:167], v[136:139], v[88:91]
	v_mfma_f32_16x16x32_bf16 v[206:209], v[164:167], v[140:143], v[92:95]
	v_mfma_f32_16x16x32_bf16 v[164:167], v[164:167], v[144:147], v[14:17]
	v_mfma_f32_16x16x32_bf16 v[186:189], v[148:151], v[132:135], v[34:37]
	v_mfma_f32_16x16x32_bf16 v[190:193], v[148:151], v[136:139], v[38:41]
	v_mfma_f32_16x16x32_bf16 v[176:179], v[148:151], v[140:143], v[178:181]
	v_mfma_f32_16x16x32_bf16 v[198:201], v[148:151], v[144:147], v[30:33]
	v_mfma_f32_16x16x32_bf16 v[48:51], v[152:155], v[132:135], v[48:51]
	v_mfma_f32_16x16x32_bf16 v[52:55], v[152:155], v[136:139], v[52:55]
	v_mfma_f32_16x16x32_bf16 v[56:59], v[152:155], v[140:143], v[56:59]
	v_mfma_f32_16x16x32_bf16 v[202:205], v[152:155], v[144:147], v[26:29]
	v_mfma_f32_16x16x32_bf16 v[60:63], v[156:159], v[132:135], v[60:63]
	v_mfma_f32_16x16x32_bf16 v[216:219], v[156:159], v[136:139], v[64:67]
	v_mfma_f32_16x16x32_bf16 v[226:229], v[156:159], v[140:143], v[68:71]
	v_mfma_f32_16x16x32_bf16 v[230:233], v[156:159], v[144:147], v[22:25]
	v_mfma_f32_16x16x32_bf16 v[234:237], v[160:163], v[132:135], v[72:75]
	v_mfma_f32_16x16x32_bf16 v[238:241], v[160:163], v[136:139], v[76:79]
	s_waitcnt lgkmcnt(2)
	v_mfma_f32_16x16x32_bf16 v[150:153], v[168:171], v[132:135], v[96:99]
	v_mfma_f32_16x16x32_bf16 v[160:163], v[168:171], v[136:139], v[100:103]
	v_mfma_f32_16x16x32_bf16 v[38:41], v[168:171], v[140:143], v[104:107]
	v_mfma_f32_16x16x32_bf16 v[34:37], v[168:171], v[144:147], v[10:13]
	s_waitcnt lgkmcnt(1)
	v_mfma_f32_16x16x32_bf16 v[30:33], v[172:175], v[132:135], v[108:111]
	v_mfma_f32_16x16x32_bf16 v[26:29], v[172:175], v[136:139], v[112:115]
	v_mfma_f32_16x16x32_bf16 v[22:25], v[172:175], v[140:143], v[116:119]
	v_mfma_f32_16x16x32_bf16 v[18:21], v[172:175], v[144:147], v[6:9]
	s_waitcnt lgkmcnt(0)
	v_mfma_f32_16x16x32_bf16 v[14:17], v[182:185], v[132:135], v[120:123]
	v_mfma_f32_16x16x32_bf16 v[10:13], v[182:185], v[136:139], v[124:127]
	v_mfma_f32_16x16x32_bf16 v[6:9], v[182:185], v[140:143], v[128:131]
	v_mfma_f32_16x16x32_bf16 v[2:5], v[182:185], v[144:147], v[2:5]
	v_mov_b32_e32 v43, v224
	s_lshl_b32 s4, s46, 3
	v_lshrrev_b32_e32 v65, 1, v43
	v_lshlrev_b32_e32 v45, 3, v43
	v_and_b32_e32 v140, 24, v65
	v_ashrrev_i32_e32 v65, 4, v43
	v_and_b32_e32 v47, 56, v45
	v_add_u32_e32 v66, 0x7c, v65
	v_cmp_gt_i32_e32 vcc, 2, v65
	v_ashrrev_i32_e32 v142, 7, v43
	v_and_b32_e32 v64, 0x4f, v43
	v_cmp_gt_i32_e64 s[40:41], 64, v43
	v_cndmask_b32_e32 v66, v66, v65, vcc
	v_and_b32_e32 v67, 0x78, v45
	v_bfe_u32 v45, v45, 6, 1
	v_lshl_add_u32 v65, v65, 1, s4
	v_ashrrev_i32_e32 v43, 3, v43
	s_movk_i32 s4, 0xffe1
	v_pk_mul_f32 v[48:49], v[46:47], v[48:49] op_sel_hi:[0,1]
	v_or_b32_e32 v45, v65, v45
	v_cmp_lt_i32_e64 s[44:45], s4, v43
	s_movk_i32 s4, 0xffc1
	v_cvt_pk_bf16_f32 v74, v48, v49
	v_pk_mul_f32 v[48:49], v[46:47], v[50:51] op_sel_hi:[0,1]
	s_movk_i32 s5, 0x110
	v_add_u32_e32 v132, s15, v43
	v_cmp_lt_i32_e64 s[46:47], s4, v43
	s_movk_i32 s4, 0xffa1
	v_cvt_pk_bf16_f32 v75, v48, v49
	v_pk_mul_f32 v[48:49], v[44:45], v[52:53] op_sel_hi:[0,1]
	v_mul_u32_u24_e32 v141, 0x110, v64
	v_cmp_lt_i32_e64 s[42:43], 1, v43
	v_mul_lo_u32 v64, v43, s5
	v_cmp_lt_i32_e64 s[48:49], s4, v43
	v_add_u32_e32 v43, 0x60, v132
	v_cvt_pk_bf16_f32 v76, v48, v49
	v_pk_mul_f32 v[48:49], v[44:45], v[54:55] op_sel_hi:[0,1]
	v_cvt_pk_bf16_f32 v77, v48, v49
	v_pk_mul_f32 v[48:49], v[42:43], v[56:57] op_sel_hi:[0,1]
	v_cvt_pk_bf16_f32 v78, v48, v49
	v_pk_mul_f32 v[48:49], v[42:43], v[58:59] op_sel_hi:[0,1]
	v_cvt_pk_bf16_f32 v79, v48, v49
	v_pk_mul_f32 v[48:49], v[0:1], v[202:203] op_sel_hi:[0,1]
	v_cvt_pk_bf16_f32 v80, v48, v49
	v_pk_mul_f32 v[48:49], v[0:1], v[204:205] op_sel_hi:[0,1]
	v_cvt_pk_bf16_f32 v81, v48, v49
	v_pk_mul_f32 v[48:49], v[46:47], v[60:61] op_sel_hi:[0,1]
	v_cvt_pk_bf16_f32 v82, v48, v49
	v_pk_mul_f32 v[48:49], v[46:47], v[62:63] op_sel_hi:[0,1]
	v_cvt_pk_bf16_f32 v83, v48, v49
	v_pk_mul_f32 v[48:49], v[44:45], v[216:217] op_sel_hi:[0,1]
	v_cvt_pk_bf16_f32 v84, v48, v49
	v_pk_mul_f32 v[48:49], v[44:45], v[218:219] op_sel_hi:[0,1]
	v_cvt_pk_bf16_f32 v85, v48, v49
	v_pk_mul_f32 v[48:49], v[42:43], v[226:227] op_sel_hi:[0,1]
	v_cvt_pk_bf16_f32 v86, v48, v49
	v_pk_mul_f32 v[48:49], v[42:43], v[228:229] op_sel_hi:[0,1]
	v_cvt_pk_bf16_f32 v87, v48, v49
	v_pk_mul_f32 v[48:49], v[0:1], v[230:231] op_sel_hi:[0,1]
	v_cvt_pk_bf16_f32 v88, v48, v49
	v_pk_mul_f32 v[48:49], v[0:1], v[232:233] op_sel_hi:[0,1]
	v_cvt_pk_bf16_f32 v89, v48, v49
	v_pk_mul_f32 v[48:49], v[46:47], v[234:235] op_sel_hi:[0,1]
	v_cvt_pk_bf16_f32 v90, v48, v49
	v_pk_mul_f32 v[48:49], v[46:47], v[236:237] op_sel_hi:[0,1]
	v_cvt_pk_bf16_f32 v91, v48, v49
	v_pk_mul_f32 v[48:49], v[44:45], v[238:239] op_sel_hi:[0,1]
	v_cvt_pk_bf16_f32 v92, v48, v49
	v_pk_mul_f32 v[48:49], v[44:45], v[240:241] op_sel_hi:[0,1]
	v_cvt_pk_bf16_f32 v93, v48, v49
	v_pk_mul_f32 v[48:49], v[42:43], v[242:243] op_sel_hi:[0,1]
	v_cvt_pk_bf16_f32 v94, v48, v49
	v_pk_mul_f32 v[48:49], v[42:43], v[244:245] op_sel_hi:[0,1]
	v_cvt_pk_bf16_f32 v95, v48, v49
	v_pk_mul_f32 v[48:49], v[0:1], v[246:247] op_sel_hi:[0,1]
	v_cvt_pk_bf16_f32 v96, v48, v49
	v_pk_mul_f32 v[48:49], v[0:1], v[248:249] op_sel_hi:[0,1]
	v_cvt_pk_bf16_f32 v97, v48, v49
	v_pk_mul_f32 v[48:49], v[46:47], v[210:211] op_sel_hi:[0,1]
	v_cvt_pk_bf16_f32 v98, v48, v49
	v_pk_mul_f32 v[48:49], v[46:47], v[212:213] op_sel_hi:[0,1]
	v_cvt_pk_bf16_f32 v99, v48, v49
	v_pk_mul_f32 v[48:49], v[44:45], v[194:195] op_sel_hi:[0,1]
	v_cvt_pk_bf16_f32 v100, v48, v49
	v_pk_mul_f32 v[48:49], v[44:45], v[196:197] op_sel_hi:[0,1]
	v_mul_lo_u32 v66, v66, s5
	v_lshl_add_u32 v144, v47, 1, v64
	v_pk_mul_f32 v[64:65], v[46:47], v[186:187] op_sel_hi:[0,1]
	v_cvt_pk_bf16_f32 v101, v48, v49
	v_pk_mul_f32 v[48:49], v[42:43], v[206:207] op_sel_hi:[0,1]
	v_lshl_add_u32 v143, v67, 1, v66
	v_cvt_pk_bf16_f32 v66, v64, v65
	v_pk_mul_f32 v[64:65], v[46:47], v[188:189] op_sel_hi:[0,1]
	v_cvt_pk_bf16_f32 v102, v48, v49
	v_pk_mul_f32 v[48:49], v[42:43], v[208:209] op_sel_hi:[0,1]
	v_cvt_pk_bf16_f32 v67, v64, v65
	v_pk_mul_f32 v[64:65], v[44:45], v[190:191] op_sel_hi:[0,1]
	v_cvt_pk_bf16_f32 v103, v48, v49
	v_pk_mul_f32 v[48:49], v[0:1], v[164:165] op_sel_hi:[0,1]
	v_cvt_pk_bf16_f32 v68, v64, v65
	v_pk_mul_f32 v[64:65], v[44:45], v[192:193] op_sel_hi:[0,1]
	v_cvt_pk_bf16_f32 v104, v48, v49
	v_pk_mul_f32 v[48:49], v[0:1], v[166:167] op_sel_hi:[0,1]
	v_pk_mul_f32 v[2:3], v[0:1], v[2:3] op_sel_hi:[0,1]
	v_cvt_pk_bf16_f32 v69, v64, v65
	v_pk_mul_f32 v[64:65], v[42:43], v[176:177] op_sel_hi:[0,1]
	v_cvt_pk_bf16_f32 v105, v48, v49
	v_pk_mul_f32 v[48:49], v[46:47], v[150:151] op_sel_hi:[0,1]
	v_cvt_pk_bf16_f32 v128, v2, v3
	v_pk_mul_f32 v[2:3], v[0:1], v[4:5] op_sel_hi:[0,1]
	v_cvt_pk_bf16_f32 v70, v64, v65
	v_pk_mul_f32 v[64:65], v[42:43], v[178:179] op_sel_hi:[0,1]
	v_cvt_pk_bf16_f32 v106, v48, v49
	v_pk_mul_f32 v[48:49], v[46:47], v[152:153] op_sel_hi:[0,1]
	v_cvt_pk_bf16_f32 v129, v2, v3
	v_mov_b64_e32 v[2:3], s[54:55]
	v_add_u32_e32 v134, 32, v132
	v_add_u32_e32 v136, 64, v132
	v_cvt_pk_bf16_f32 v71, v64, v65
	v_pk_mul_f32 v[64:65], v[0:1], v[198:199] op_sel_hi:[0,1]
	v_cvt_pk_bf16_f32 v107, v48, v49
	v_pk_mul_f32 v[48:49], v[44:45], v[160:161] op_sel_hi:[0,1]
	v_pk_mul_f32 v[38:39], v[42:43], v[38:39] op_sel_hi:[0,1]
	v_pk_mul_f32 v[34:35], v[0:1], v[34:35] op_sel_hi:[0,1]
	v_pk_mul_f32 v[30:31], v[46:47], v[30:31] op_sel_hi:[0,1]
	v_pk_mul_f32 v[26:27], v[44:45], v[26:27] op_sel_hi:[0,1]
	v_pk_mul_f32 v[22:23], v[42:43], v[22:23] op_sel_hi:[0,1]
	v_pk_mul_f32 v[18:19], v[0:1], v[18:19] op_sel_hi:[0,1]
	v_pk_mul_f32 v[14:15], v[46:47], v[14:15] op_sel_hi:[0,1]
	v_pk_mul_f32 v[10:11], v[44:45], v[10:11] op_sel_hi:[0,1]
	v_pk_mul_f32 v[6:7], v[42:43], v[6:7] op_sel_hi:[0,1]
	v_mad_i64_i32 v[130:131], s[4:5], v45, s19, v[2:3]
	v_mov_b64_e32 v[2:3], s[52:53]
	v_cvt_pk_bf16_f32 v72, v64, v65
	v_pk_mul_f32 v[64:65], v[0:1], v[200:201] op_sel_hi:[0,1]
	v_cvt_pk_bf16_f32 v108, v48, v49
	v_pk_mul_f32 v[48:49], v[44:45], v[162:163] op_sel_hi:[0,1]
	v_cvt_pk_bf16_f32 v110, v38, v39
	v_pk_mul_f32 v[38:39], v[42:43], v[40:41] op_sel_hi:[0,1]
	v_cvt_pk_bf16_f32 v112, v34, v35
	v_pk_mul_f32 v[34:35], v[0:1], v[36:37] op_sel_hi:[0,1]
	v_cvt_pk_bf16_f32 v114, v30, v31
	v_pk_mul_f32 v[30:31], v[46:47], v[32:33] op_sel_hi:[0,1]
	v_cvt_pk_bf16_f32 v116, v26, v27
	v_pk_mul_f32 v[26:27], v[44:45], v[28:29] op_sel_hi:[0,1]
	v_cvt_pk_bf16_f32 v118, v22, v23
	v_pk_mul_f32 v[22:23], v[42:43], v[24:25] op_sel_hi:[0,1]
	v_cvt_pk_bf16_f32 v120, v18, v19
	v_pk_mul_f32 v[18:19], v[0:1], v[20:21] op_sel_hi:[0,1]
	v_cvt_pk_bf16_f32 v122, v14, v15
	v_pk_mul_f32 v[14:15], v[46:47], v[16:17] op_sel_hi:[0,1]
	v_cvt_pk_bf16_f32 v124, v10, v11
	v_pk_mul_f32 v[10:11], v[44:45], v[12:13] op_sel_hi:[0,1]
	v_cvt_pk_bf16_f32 v126, v6, v7
	v_pk_mul_f32 v[6:7], v[42:43], v[8:9] op_sel_hi:[0,1]
	v_mad_i64_i32 v[132:133], s[4:5], v132, s19, v[2:3]
	v_mad_i64_i32 v[134:135], s[4:5], v134, s19, v[2:3]
	v_mad_i64_i32 v[136:137], s[4:5], v136, s19, v[2:3]
	v_mad_i64_i32 v[138:139], s[4:5], v43, s19, v[2:3]
	v_add_u32_e32 v145, 0xfffffef0, v144
	v_add_u32_e32 v146, 0xffffff70, v144
	v_add_u32_e32 v147, 0xfffffde0, v144
	v_add_u32_e32 v148, 0xfffffe60, v144
	v_add_u32_e32 v149, 0x2200, v144
	v_add_u32_e32 v168, 0x20f0, v144
	v_add_u32_e32 v169, 0x2170, v144
	v_add_u32_e32 v170, 0x1fe0, v144
	v_add_u32_e32 v171, 0x2060, v144
	v_add_u32_e32 v154, 0x4400, v144
	v_add_u32_e32 v155, 0x42f0, v144
	v_add_u32_e32 v156, 0x4370, v144
	v_add_u32_e32 v157, 0x41e0, v144
	v_add_u32_e32 v158, 0x4260, v144
	v_add_u32_e32 v159, 0x6600, v144
	v_add_u32_e32 v172, 0x64f0, v144
	v_add_u32_e32 v173, 0x6570, v144
	v_add_u32_e32 v174, 0x63e0, v144
	v_add_u32_e32 v175, 0x6460, v144
	v_cvt_pk_bf16_f32 v73, v64, v65
	v_cvt_pk_bf16_f32 v109, v48, v49
	v_cvt_pk_bf16_f32 v111, v38, v39
	v_cvt_pk_bf16_f32 v113, v34, v35
	v_cvt_pk_bf16_f32 v115, v30, v31
	v_cvt_pk_bf16_f32 v117, v26, v27
	v_cvt_pk_bf16_f32 v119, v22, v23
	v_cvt_pk_bf16_f32 v121, v18, v19
	v_cvt_pk_bf16_f32 v123, v14, v15
	v_cvt_pk_bf16_f32 v125, v10, v11
	v_cvt_pk_bf16_f32 v127, v6, v7
	v_lshl_or_b32 v0, s14, 7, v47
	s_mov_b32 s4, 0
	s_mov_b64 s[12:13], -1
	v_add_u32_e32 v164, v140, v141
	v_xor_b32_e32 v246, 32, v225
	v_xor_b32_e32 v247, 16, v225
	v_xor_b32_e32 v248, 8, v225
	v_xor_b32_e32 v249, 4, v225
	v_mov_b32_e32 v243, v221
	s_branch .LBB0_171

.LBB0_194:
	s_mul_i32 s48, s13, 0x6000
	s_add_i32 s49, s48, 0xffffa000
	s_cmp_gt_i32 s13, 0
	s_waitcnt vmcnt(6)
	s_cselect_b32 s49, s49, 0xc000
	s_waitcnt lgkmcnt(0)
	s_barrier
	s_setprio 2
	v_or_b32_e32 v0, s48, v146
	v_add_u32_e32 v0, v0, v144
	v_add3_u32 v212, s48, v145, v144
	ds_read_b128 v[164:167], v212 offset:8192
	ds_read_b128 v[148:151], v0
	ds_read_b128 v[152:155], v0 offset:1024
	ds_read_b128 v[156:159], v0 offset:2048
	ds_read_b128 v[160:163], v0 offset:3072
	ds_read_b128 v[168:171], v212 offset:9216
	ds_read_b128 v[172:175], v212 offset:10240
	ds_read_b128 v[176:179], v212 offset:11264
	ds_read_b128 v[180:183], v212 offset:12288
	ds_read_b128 v[184:187], v212 offset:13312
	ds_read_b128 v[188:191], v212 offset:14336
	ds_read_b128 v[198:201], v212 offset:15360
	s_cmp_eq_u32 s100, 0
	s_cbranch_scc0 .Lmy_re_5
	v_lshl_add_u64 v[212:213], v[142:143], 0, s[40:41]
	v_lshl_add_u64 v[212:213], v[130:131], 1, v[212:213]
	s_add_i32 s69, s49, s47
	s_mov_b32 m0, s69
	s_nop 0
	global_load_lds_dwordx4 v[212:213], off
	v_lshl_add_u64 v[212:213], v[142:143], 0, s[40:41]
	v_lshl_add_u64 v[212:213], v[132:133], 1, v[212:213]
	s_add_i32 s69, s49, s14
	s_mov_b32 m0, s69
	s_nop 0
	global_load_lds_dwordx4 v[212:213], off
	s_add_i32 s49, s15, s49
	v_lshl_add_u64 v[212:213], v[140:141], 0, s[40:41]
	s_mov_b32 m0, s49
	s_nop 0
	global_load_lds_dwordx4 v[212:213], off
	v_lshl_add_u64 v[212:213], v[138:139], 0, s[40:41]
	s_add_i32 s69, s49, 0x400
	s_mov_b32 m0, s69
	s_nop 0
	global_load_lds_dwordx4 v[212:213], off
	v_lshl_add_u64 v[212:213], v[136:137], 0, s[40:41]
	s_add_i32 s69, s49, 0x800
	s_mov_b32 m0, s69
	s_nop 0
	global_load_lds_dwordx4 v[212:213], off
	v_lshl_add_u64 v[212:213], v[134:135], 0, s[40:41]
	s_addk_i32 s49, 0xc00
	s_mov_b32 m0, s49
	s_nop 0
	global_load_lds_dwordx4 v[212:213], off
.Lmy_re_5:
	s_setprio 0
	s_waitcnt lgkmcnt(10)
	v_mfma_f32_16x16x32_bf16 v[126:129], v[164:167], v[148:151], v[126:129]
	s_waitcnt lgkmcnt(9)
	v_mfma_f32_16x16x32_bf16 v[122:125], v[164:167], v[152:155], v[122:125]
	s_waitcnt lgkmcnt(8)
	v_mfma_f32_16x16x32_bf16 v[118:121], v[164:167], v[156:159], v[118:121]
	s_waitcnt lgkmcnt(7)
	v_mfma_f32_16x16x32_bf16 v[114:117], v[164:167], v[160:163], v[114:117]
	s_waitcnt lgkmcnt(6)
	v_mfma_f32_16x16x32_bf16 v[110:113], v[168:171], v[148:151], v[110:113]
	v_mfma_f32_16x16x32_bf16 v[106:109], v[168:171], v[152:155], v[106:109]
	v_mfma_f32_16x16x32_bf16 v[102:105], v[168:171], v[156:159], v[102:105]
	v_mfma_f32_16x16x32_bf16 v[98:101], v[168:171], v[160:163], v[98:101]
	s_waitcnt lgkmcnt(5)
	v_mfma_f32_16x16x32_bf16 v[94:97], v[172:175], v[148:151], v[94:97]
	v_mfma_f32_16x16x32_bf16 v[90:93], v[172:175], v[152:155], v[90:93]
	v_mfma_f32_16x16x32_bf16 v[86:89], v[172:175], v[156:159], v[86:89]
	v_mfma_f32_16x16x32_bf16 v[82:85], v[172:175], v[160:163], v[82:85]
	s_waitcnt lgkmcnt(4)
	v_mfma_f32_16x16x32_bf16 v[78:81], v[176:179], v[148:151], v[78:81]
	v_mfma_f32_16x16x32_bf16 v[74:77], v[176:179], v[152:155], v[74:77]
	v_mfma_f32_16x16x32_bf16 v[70:73], v[176:179], v[156:159], v[70:73]
	v_mfma_f32_16x16x32_bf16 v[66:69], v[176:179], v[160:163], v[66:69]
	s_waitcnt lgkmcnt(3)
	v_mfma_f32_16x16x32_bf16 v[62:65], v[180:183], v[148:151], v[62:65]
	v_mfma_f32_16x16x32_bf16 v[58:61], v[180:183], v[152:155], v[58:61]
	v_mfma_f32_16x16x32_bf16 v[54:57], v[180:183], v[156:159], v[54:57]
	v_mfma_f32_16x16x32_bf16 v[50:53], v[180:183], v[160:163], v[50:53]
	s_waitcnt lgkmcnt(2)
	v_mfma_f32_16x16x32_bf16 v[46:49], v[184:187], v[148:151], v[46:49]
	v_mfma_f32_16x16x32_bf16 v[42:45], v[184:187], v[152:155], v[42:45]
	v_mfma_f32_16x16x32_bf16 v[38:41], v[184:187], v[156:159], v[38:41]
	v_mfma_f32_16x16x32_bf16 v[34:37], v[184:187], v[160:163], v[34:37]
	s_waitcnt lgkmcnt(1)
	v_mfma_f32_16x16x32_bf16 v[30:33], v[188:191], v[148:151], v[30:33]
	v_mfma_f32_16x16x32_bf16 v[26:29], v[188:191], v[152:155], v[26:29]
	v_mfma_f32_16x16x32_bf16 v[22:25], v[188:191], v[156:159], v[22:25]
	v_mfma_f32_16x16x32_bf16 v[18:21], v[188:191], v[160:163], v[18:21]
	s_waitcnt lgkmcnt(0)
	v_mfma_f32_16x16x32_bf16 v[14:17], v[198:201], v[148:151], v[14:17]
	v_mfma_f32_16x16x32_bf16 v[10:13], v[198:201], v[152:155], v[10:13]
	v_mfma_f32_16x16x32_bf16 v[6:9], v[198:201], v[156:159], v[6:9]
	v_mfma_f32_16x16x32_bf16 v[2:5], v[198:201], v[160:163], v[2:5]
	s_cmp_eq_u32 s100, 0
	s_cbranch_scc1 .Lmy_rl_5
	s_setprio 2
	v_lshl_add_u64 v[212:213], v[142:143], 0, s[40:41]
	v_lshl_add_u64 v[212:213], v[130:131], 1, v[212:213]
	s_add_i32 s69, s49, s47
	s_mov_b32 m0, s69
	s_nop 0
	global_load_lds_dwordx4 v[212:213], off
	v_lshl_add_u64 v[212:213], v[142:143], 0, s[40:41]
	v_lshl_add_u64 v[212:213], v[132:133], 1, v[212:213]
	s_add_i32 s69, s49, s14
	s_mov_b32 m0, s69
	s_nop 0
	global_load_lds_dwordx4 v[212:213], off
	s_add_i32 s49, s15, s49
	v_lshl_add_u64 v[212:213], v[140:141], 0, s[40:41]
	s_mov_b32 m0, s49
	s_nop 0
	global_load_lds_dwordx4 v[212:213], off
	v_lshl_add_u64 v[212:213], v[138:139], 0, s[40:41]
	s_add_i32 s69, s49, 0x400
	s_mov_b32 m0, s69
	s_nop 0
	global_load_lds_dwordx4 v[212:213], off
	v_lshl_add_u64 v[212:213], v[136:137], 0, s[40:41]
	s_add_i32 s69, s49, 0x800
	s_mov_b32 m0, s69
	s_nop 0
	global_load_lds_dwordx4 v[212:213], off
	v_lshl_add_u64 v[212:213], v[134:135], 0, s[40:41]
	s_addk_i32 s49, 0xc00
	s_mov_b32 m0, s49
	s_nop 0
	global_load_lds_dwordx4 v[212:213], off
.Lmy_rl_5:
	s_add_i32 s48, s13, 1
	s_cmp_lg_u32 s13, 2
	s_cselect_b32 s13, s48, 0
	s_add_u32 s40, s40, 64
	s_addc_u32 s41, s41, 0
	s_cmpk_eq_i32 s40, 0x780
	s_cbranch_scc0 .LBB0_194
	s_waitcnt vmcnt(6)
	v_add_u32_e32 v0, v146, v144
	v_add_u32_e32 v194, v145, v144
	s_waitcnt lgkmcnt(0)
	s_barrier
	ds_read_b128 v[130:133], v0
	ds_read_b128 v[134:137], v0 offset:1024
	ds_read_b128 v[138:141], v0 offset:2048
	ds_read_b128 v[146:149], v0 offset:3072
	ds_read_b128 v[142:145], v194 offset:8192
	ds_read_b128 v[150:153], v194 offset:9216
	ds_read_b128 v[154:157], v194 offset:10240
	ds_read_b128 v[158:161], v194 offset:11264
	ds_read_b128 v[162:165], v194 offset:12288
	ds_read_b128 v[166:169], v194 offset:13312
	ds_read_b128 v[170:173], v194 offset:14336
	ds_read_b128 v[174:177], v194 offset:15360
	s_waitcnt lgkmcnt(7)
	v_mfma_f32_16x16x32_bf16 v[126:129], v[142:145], v[130:133], v[126:129]
	v_mfma_f32_16x16x32_bf16 v[122:125], v[142:145], v[134:137], v[122:125]
	v_mfma_f32_16x16x32_bf16 v[118:121], v[142:145], v[138:141], v[118:121]
	v_mfma_f32_16x16x32_bf16 v[114:117], v[142:145], v[146:149], v[114:117]
	s_waitcnt lgkmcnt(6)
	v_mfma_f32_16x16x32_bf16 v[110:113], v[150:153], v[130:133], v[110:113]
	v_mfma_f32_16x16x32_bf16 v[106:109], v[150:153], v[134:137], v[106:109]
	v_mfma_f32_16x16x32_bf16 v[102:105], v[150:153], v[138:141], v[102:105]
	v_mfma_f32_16x16x32_bf16 v[98:101], v[150:153], v[146:149], v[98:101]
	s_waitcnt lgkmcnt(5)
	v_mfma_f32_16x16x32_bf16 v[94:97], v[154:157], v[130:133], v[94:97]
	v_mfma_f32_16x16x32_bf16 v[90:93], v[154:157], v[134:137], v[90:93]
	v_mfma_f32_16x16x32_bf16 v[86:89], v[154:157], v[138:141], v[86:89]
	v_mfma_f32_16x16x32_bf16 v[82:85], v[154:157], v[146:149], v[82:85]
	s_waitcnt lgkmcnt(4)
	v_mfma_f32_16x16x32_bf16 v[78:81], v[158:161], v[130:133], v[78:81]
	v_mfma_f32_16x16x32_bf16 v[74:77], v[158:161], v[134:137], v[74:77]
	v_mfma_f32_16x16x32_bf16 v[70:73], v[158:161], v[138:141], v[70:73]
	v_mfma_f32_16x16x32_bf16 v[66:69], v[158:161], v[146:149], v[66:69]
	s_waitcnt lgkmcnt(3)
	v_mfma_f32_16x16x32_bf16 v[142:145], v[162:165], v[130:133], v[62:65]
	v_mfma_f32_16x16x32_bf16 v[150:153], v[162:165], v[134:137], v[58:61]
	v_mfma_f32_16x16x32_bf16 v[154:157], v[162:165], v[138:141], v[54:57]
	v_mfma_f32_16x16x32_bf16 v[158:161], v[162:165], v[146:149], v[50:53]
	s_waitcnt lgkmcnt(2)
	v_mfma_f32_16x16x32_bf16 v[162:165], v[166:169], v[130:133], v[46:49]
	v_mfma_f32_16x16x32_bf16 v[178:181], v[166:169], v[134:137], v[42:45]
	v_mfma_f32_16x16x32_bf16 v[182:185], v[166:169], v[138:141], v[38:41]
	v_mfma_f32_16x16x32_bf16 v[166:169], v[166:169], v[146:149], v[34:37]
	s_waitcnt lgkmcnt(1)
	v_mfma_f32_16x16x32_bf16 v[186:189], v[170:173], v[130:133], v[30:33]
	v_mfma_f32_16x16x32_bf16 v[190:193], v[170:173], v[134:137], v[26:29]
	v_mfma_f32_16x16x32_bf16 v[198:201], v[170:173], v[138:141], v[22:25]
	v_mfma_f32_16x16x32_bf16 v[170:173], v[170:173], v[146:149], v[18:21]
	s_waitcnt lgkmcnt(0)
	v_mfma_f32_16x16x32_bf16 v[130:133], v[174:177], v[130:133], v[14:17]
	v_mfma_f32_16x16x32_bf16 v[134:137], v[174:177], v[134:137], v[10:13]
	v_mfma_f32_16x16x32_bf16 v[138:141], v[174:177], v[138:141], v[6:9]
	v_mfma_f32_16x16x32_bf16 v[146:149], v[174:177], v[146:149], v[2:5]
	s_waitcnt vmcnt(0)
	s_waitcnt lgkmcnt(0)
	s_barrier
	ds_read_b128 v[174:177], v0 offset:24576
	ds_read_b128 v[202:205], v0 offset:25600
	ds_read_b128 v[216:219], v0 offset:26624
	ds_read_b128 v[226:229], v0 offset:27648
	ds_read_b128 v[14:17], v194 offset:32768
	ds_read_b128 v[30:33], v194 offset:33792
	ds_read_b128 v[46:49], v194 offset:34816
	ds_read_b128 v[62:65], v194 offset:35840
	ds_read_b128 v[230:233], v194 offset:36864
	ds_read_b128 v[234:237], v194 offset:37888
	ds_read_b128 v[238:241], v194 offset:38912
	ds_read_b128 v[242:245], v194 offset:39936
	s_waitcnt lgkmcnt(7)
	v_mfma_f32_16x16x32_bf16 v[2:5], v[14:17], v[174:177], v[126:129]
	v_mfma_f32_16x16x32_bf16 v[6:9], v[14:17], v[202:205], v[122:125]
	v_mfma_f32_16x16x32_bf16 v[10:13], v[14:17], v[216:219], v[118:121]
	v_mfma_f32_16x16x32_bf16 v[14:17], v[14:17], v[226:229], v[114:117]
	s_waitcnt lgkmcnt(6)
	v_mfma_f32_16x16x32_bf16 v[18:21], v[30:33], v[174:177], v[110:113]
	v_mfma_f32_16x16x32_bf16 v[22:25], v[30:33], v[202:205], v[106:109]
	v_mfma_f32_16x16x32_bf16 v[26:29], v[30:33], v[216:219], v[102:105]
	v_mfma_f32_16x16x32_bf16 v[30:33], v[30:33], v[226:229], v[98:101]
	s_waitcnt lgkmcnt(5)
	v_mfma_f32_16x16x32_bf16 v[34:37], v[46:49], v[174:177], v[94:97]
	v_mfma_f32_16x16x32_bf16 v[38:41], v[46:49], v[202:205], v[90:93]
	v_mfma_f32_16x16x32_bf16 v[42:45], v[46:49], v[216:219], v[86:89]
	v_mfma_f32_16x16x32_bf16 v[46:49], v[46:49], v[226:229], v[82:85]
	s_waitcnt lgkmcnt(4)
	v_mfma_f32_16x16x32_bf16 v[50:53], v[62:65], v[174:177], v[78:81]
	v_mfma_f32_16x16x32_bf16 v[54:57], v[62:65], v[202:205], v[74:77]
	v_mfma_f32_16x16x32_bf16 v[58:61], v[62:65], v[216:219], v[70:73]
	v_mfma_f32_16x16x32_bf16 v[62:65], v[62:65], v[226:229], v[66:69]
	s_waitcnt lgkmcnt(3)
	v_mfma_f32_16x16x32_bf16 v[66:69], v[230:233], v[174:177], v[142:145]
	v_mfma_f32_16x16x32_bf16 v[70:73], v[230:233], v[202:205], v[150:153]
	v_mfma_f32_16x16x32_bf16 v[74:77], v[230:233], v[216:219], v[154:157]
	v_mfma_f32_16x16x32_bf16 v[78:81], v[230:233], v[226:229], v[158:161]
	s_waitcnt lgkmcnt(2)
	v_mfma_f32_16x16x32_bf16 v[82:85], v[234:237], v[174:177], v[162:165]
	v_mfma_f32_16x16x32_bf16 v[86:89], v[234:237], v[202:205], v[178:181]
	v_mfma_f32_16x16x32_bf16 v[90:93], v[234:237], v[216:219], v[182:185]
	v_mfma_f32_16x16x32_bf16 v[94:97], v[234:237], v[226:229], v[166:169]
	s_waitcnt lgkmcnt(1)
	v_mfma_f32_16x16x32_bf16 v[98:101], v[238:241], v[174:177], v[186:189]
	v_mfma_f32_16x16x32_bf16 v[102:105], v[238:241], v[202:205], v[190:193]
	v_mfma_f32_16x16x32_bf16 v[106:109], v[238:241], v[216:219], v[198:201]
	v_mfma_f32_16x16x32_bf16 v[110:113], v[238:241], v[226:229], v[170:173]
	s_waitcnt lgkmcnt(0)
	v_mfma_f32_16x16x32_bf16 v[114:117], v[242:245], v[174:177], v[130:133]
	v_mfma_f32_16x16x32_bf16 v[118:121], v[242:245], v[202:205], v[134:137]
	v_mfma_f32_16x16x32_bf16 v[122:125], v[242:245], v[216:219], v[138:141]
	v_mfma_f32_16x16x32_bf16 v[126:129], v[242:245], v[226:229], v[146:149]
	v_mov_b32_e32 v130, v224
	s_ashr_i32 s13, s12, 31
	v_and_b32_e32 v131, 31, v130
	v_ashrrev_i32_e32 v197, 7, v130
	v_ashrrev_i32_e32 v132, 5, v130
	v_lshlrev_b32_e32 v0, 2, v131
	s_lshl_b64 s[48:49], s[12:13], 11
	v_lshlrev_b32_e32 v164, 4, v131
	v_cmp_eq_u32_e64 s[40:41], 0, v131
	v_and_b32_e32 v131, 0x4f, v130
	v_and_b32_e32 v130, 48, v130
	s_movk_i32 s13, 0x210
	v_cmp_lt_i32_e32 vcc, v247, v214
	v_mad_u32_u24 v202, v131, s13, v130
	s_ashr_i32 s47, s46, 31
	v_cndmask_b32_e32 v130, v225, v247, vcc
	v_cmp_lt_i32_e32 vcc, v248, v214
	v_lshlrev_b32_e32 v203, 2, v130
	s_lshl_b32 s69, s57, 1
	v_cndmask_b32_e32 v130, v225, v248, vcc
	v_cmp_lt_i32_e32 vcc, v249, v214
	v_lshlrev_b32_e32 v204, 2, v130
	s_add_u32 s15, s53, s48
	v_cndmask_b32_e32 v130, v225, v249, vcc
	v_cmp_lt_i32_e32 vcc, v223, v214
	v_lshlrev_b32_e32 v205, 2, v130
	v_lshl_or_b32 v0, v132, 10, v0
	v_cndmask_b32_e32 v130, v225, v223, vcc
	v_cmp_lt_i32_e32 vcc, v252, v214
	v_lshlrev_b32_e32 v206, 2, v130
	v_mul_lo_u32 v165, v132, s13
	v_cndmask_b32_e32 v130, v225, v252, vcc
	v_lshlrev_b32_e32 v207, 2, v130
	v_add_u32_e32 v130, s12, v132
	v_ashrrev_i32_e32 v131, 31, v130
	v_lshlrev_b64 v[132:133], 5, v[130:131]
	v_add_u32_e32 v134, 8, v130
	v_add_u32_e32 v136, 16, v130
	v_add_u32_e32 v138, 24, v130
	v_add_u32_e32 v140, 32, v130
	v_add_u32_e32 v142, 40, v130
	v_add_u32_e32 v144, 48, v130
	v_add_u32_e32 v146, 56, v130
	v_add_u32_e32 v148, 64, v130
	v_add_u32_e32 v150, 0x48, v130
	v_add_u32_e32 v152, 0x50, v130
	v_add_u32_e32 v154, 0x58, v130
	v_add_u32_e32 v156, 0x60, v130
	v_add_u32_e32 v158, 0x68, v130
	v_add_u32_e32 v160, 0x70, v130
	v_add_u32_e32 v130, 0x78, v130
	s_addc_u32 s48, s54, s49
	s_lshl_b64 s[12:13], s[46:47], 1
	v_ashrrev_i32_e32 v135, 31, v134
	v_ashrrev_i32_e32 v137, 31, v136
	v_ashrrev_i32_e32 v139, 31, v138
	v_ashrrev_i32_e32 v141, 31, v140
	v_ashrrev_i32_e32 v143, 31, v142
	v_ashrrev_i32_e32 v145, 31, v144
	v_ashrrev_i32_e32 v147, 31, v146
	v_ashrrev_i32_e32 v149, 31, v148
	v_ashrrev_i32_e32 v151, 31, v150
	v_ashrrev_i32_e32 v153, 31, v152
	v_ashrrev_i32_e32 v155, 31, v154
	v_ashrrev_i32_e32 v157, 31, v156
	v_ashrrev_i32_e32 v159, 31, v158
	v_ashrrev_i32_e32 v161, 31, v160
	v_ashrrev_i32_e32 v131, 31, v130
	s_add_u32 s12, s15, s12
	v_lshlrev_b64 v[134:135], 5, v[134:135]
	v_lshlrev_b64 v[136:137], 5, v[136:137]
	v_lshlrev_b64 v[138:139], 5, v[138:139]
	v_lshlrev_b64 v[140:141], 5, v[140:141]
	v_lshlrev_b64 v[142:143], 5, v[142:143]
	v_lshlrev_b64 v[144:145], 5, v[144:145]
	v_lshlrev_b64 v[146:147], 5, v[146:147]
	v_lshlrev_b64 v[148:149], 5, v[148:149]
	v_lshlrev_b64 v[150:151], 5, v[150:151]
	v_lshlrev_b64 v[152:153], 5, v[152:153]
	v_lshlrev_b64 v[154:155], 5, v[154:155]
	v_lshlrev_b64 v[156:157], 5, v[156:157]
	v_lshlrev_b64 v[158:159], 5, v[158:159]
	v_lshlrev_b64 v[160:161], 5, v[160:161]
	v_lshlrev_b64 v[162:163], 5, v[130:131]
	s_addc_u32 s13, s48, s13
	s_mov_b32 s14, 0
	v_lshl_add_u64 v[130:131], v[0:1], 1, s[12:13]
	v_lshl_add_u64 v[132:133], s[42:43], 0, v[132:133]
	v_lshl_add_u64 v[134:135], s[42:43], 0, v[134:135]
	v_lshl_add_u64 v[136:137], s[42:43], 0, v[136:137]
	v_lshl_add_u64 v[138:139], s[42:43], 0, v[138:139]
	v_lshl_add_u64 v[140:141], s[42:43], 0, v[140:141]
	v_lshl_add_u64 v[142:143], s[42:43], 0, v[142:143]
	v_lshl_add_u64 v[144:145], s[42:43], 0, v[144:145]
	v_lshl_add_u64 v[146:147], s[42:43], 0, v[146:147]
	v_lshl_add_u64 v[148:149], s[42:43], 0, v[148:149]
	v_lshl_add_u64 v[150:151], s[42:43], 0, v[150:151]
	v_lshl_add_u64 v[152:153], s[42:43], 0, v[152:153]
	v_lshl_add_u64 v[154:155], s[42:43], 0, v[154:155]
	v_lshl_add_u64 v[156:157], s[42:43], 0, v[156:157]
	v_lshl_add_u64 v[158:159], s[42:43], 0, v[158:159]
	v_lshl_add_u64 v[160:161], s[42:43], 0, v[160:161]
	v_lshl_add_u64 v[162:163], s[42:43], 0, v[162:163]
	s_mov_b64 s[46:47], -1
	v_add_u32_e32 v0, v164, v165
	v_mov_b32_e32 v243, 0x7f800000
	s_branch .LBB0_197

.LBB0_643:
	s_mul_i32 s44, s43, 0x6000
	s_add_i32 s45, s44, 0xffffa000
	s_cmp_gt_i32 s43, 0
	s_waitcnt vmcnt(6)
	s_cselect_b32 s45, s45, 0xc000
	s_waitcnt lgkmcnt(0)
	s_barrier
	s_setprio 2
	v_add3_u32 v0, s44, v177, v176
	v_add_u32_e32 v0, s55, v0
	v_add3_u32 v212, s44, v178, v176
	ds_read_b128 v[202:205], v212 offset:8192
	ds_read_b128 v[180:183], v0
	ds_read_b128 v[184:187], v0 offset:1024
	ds_read_b128 v[188:191], v0 offset:2048
	ds_read_b128 v[198:201], v0 offset:3072
	ds_read_b128 v[234:237], v212 offset:9216
	ds_read_b128 v[238:241], v212 offset:10240
	ds_read_b128 v[242:245], v212 offset:11264
	ds_read_b128 v[246:249], v212 offset:12288
	ds_read_b128 v[226:229], v212 offset:13312
	ds_read_b128 v[216:219], v212 offset:14336
	ds_read_b128 v[230:233], v212 offset:15360
	s_cmp_eq_u32 s100, 0
	s_cbranch_scc0 .Lmy_re_6
	v_lshl_add_u64 v[212:213], v[174:175], 0, s[12:13]
	v_lshl_add_u64 v[212:213], v[162:163], 1, v[212:213]
	s_add_i32 s68, s45, s42
	s_mov_b32 m0, s68
	s_nop 0
	global_load_lds_dwordx4 v[212:213], off
	v_lshl_add_u64 v[212:213], v[174:175], 0, s[12:13]
	v_lshl_add_u64 v[212:213], v[164:165], 1, v[212:213]
	s_add_i32 s68, s45, s40
	s_mov_b32 m0, s68
	s_nop 0
	global_load_lds_dwordx4 v[212:213], off
	s_add_i32 s45, s41, s45
	v_lshl_add_u64 v[212:213], v[172:173], 0, s[12:13]
	s_mov_b32 m0, s45
	s_nop 0
	global_load_lds_dwordx4 v[212:213], off
	v_lshl_add_u64 v[212:213], v[170:171], 0, s[12:13]
	s_add_i32 s68, s45, 0x400
	s_mov_b32 m0, s68
	s_nop 0
	global_load_lds_dwordx4 v[212:213], off
	v_lshl_add_u64 v[212:213], v[168:169], 0, s[12:13]
	s_add_i32 s68, s45, 0x800
	s_mov_b32 m0, s68
	s_nop 0
	global_load_lds_dwordx4 v[212:213], off
	s_addk_i32 s45, 0xc00
	v_lshl_add_u64 v[212:213], v[166:167], 0, s[12:13]
	s_mov_b32 m0, s45
	s_nop 0
	global_load_lds_dwordx4 v[212:213], off
.Lmy_re_6:
	s_setprio 0
	s_waitcnt lgkmcnt(10)
	v_mfma_f32_16x16x32_bf16 v[34:37], v[202:205], v[180:183], v[34:37]
	s_waitcnt lgkmcnt(9)
	v_mfma_f32_16x16x32_bf16 v[38:41], v[202:205], v[184:187], v[38:41]
	s_waitcnt lgkmcnt(8)
	v_mfma_f32_16x16x32_bf16 v[42:45], v[202:205], v[188:191], v[42:45]
	s_waitcnt lgkmcnt(7)
	v_mfma_f32_16x16x32_bf16 v[46:49], v[202:205], v[198:201], v[46:49]
	s_waitcnt lgkmcnt(6)
	v_mfma_f32_16x16x32_bf16 v[50:53], v[234:237], v[180:183], v[50:53]
	v_mfma_f32_16x16x32_bf16 v[54:57], v[234:237], v[184:187], v[54:57]
	v_mfma_f32_16x16x32_bf16 v[58:61], v[234:237], v[188:191], v[58:61]
	v_mfma_f32_16x16x32_bf16 v[62:65], v[234:237], v[198:201], v[62:65]
	s_waitcnt lgkmcnt(5)
	v_mfma_f32_16x16x32_bf16 v[66:69], v[238:241], v[180:183], v[66:69]
	v_mfma_f32_16x16x32_bf16 v[70:73], v[238:241], v[184:187], v[70:73]
	v_mfma_f32_16x16x32_bf16 v[74:77], v[238:241], v[188:191], v[74:77]
	v_mfma_f32_16x16x32_bf16 v[78:81], v[238:241], v[198:201], v[78:81]
	s_waitcnt lgkmcnt(4)
	v_mfma_f32_16x16x32_bf16 v[82:85], v[242:245], v[180:183], v[82:85]
	v_mfma_f32_16x16x32_bf16 v[86:89], v[242:245], v[184:187], v[86:89]
	v_mfma_f32_16x16x32_bf16 v[90:93], v[242:245], v[188:191], v[90:93]
	v_mfma_f32_16x16x32_bf16 v[94:97], v[242:245], v[198:201], v[94:97]
	s_waitcnt lgkmcnt(3)
	v_mfma_f32_16x16x32_bf16 v[98:101], v[246:249], v[180:183], v[98:101]
	v_mfma_f32_16x16x32_bf16 v[102:105], v[246:249], v[184:187], v[102:105]
	v_mfma_f32_16x16x32_bf16 v[106:109], v[246:249], v[188:191], v[106:109]
	v_mfma_f32_16x16x32_bf16 v[110:113], v[246:249], v[198:201], v[110:113]
	s_waitcnt lgkmcnt(2)
	v_mfma_f32_16x16x32_bf16 v[114:117], v[226:229], v[180:183], v[114:117]
	v_mfma_f32_16x16x32_bf16 v[118:121], v[226:229], v[184:187], v[118:121]
	v_mfma_f32_16x16x32_bf16 v[122:125], v[226:229], v[188:191], v[122:125]
	v_mfma_f32_16x16x32_bf16 v[126:129], v[226:229], v[198:201], v[126:129]
	s_waitcnt lgkmcnt(1)
	v_mfma_f32_16x16x32_bf16 v[130:133], v[216:219], v[180:183], v[130:133]
	v_mfma_f32_16x16x32_bf16 v[134:137], v[216:219], v[184:187], v[134:137]
	v_mfma_f32_16x16x32_bf16 v[138:141], v[216:219], v[188:191], v[138:141]
	v_mfma_f32_16x16x32_bf16 v[142:145], v[216:219], v[198:201], v[142:145]
	s_waitcnt lgkmcnt(0)
	v_mfma_f32_16x16x32_bf16 v[146:149], v[230:233], v[180:183], v[146:149]
	v_mfma_f32_16x16x32_bf16 v[150:153], v[230:233], v[184:187], v[150:153]
	v_mfma_f32_16x16x32_bf16 v[154:157], v[230:233], v[188:191], v[154:157]
	v_mfma_f32_16x16x32_bf16 v[158:161], v[230:233], v[198:201], v[158:161]
	s_cmp_eq_u32 s100, 0
	s_cbranch_scc1 .Lmy_rl_6
	s_setprio 2
	v_lshl_add_u64 v[212:213], v[174:175], 0, s[12:13]
	v_lshl_add_u64 v[212:213], v[162:163], 1, v[212:213]
	s_add_i32 s68, s45, s42
	s_mov_b32 m0, s68
	s_nop 0
	global_load_lds_dwordx4 v[212:213], off
	v_lshl_add_u64 v[212:213], v[174:175], 0, s[12:13]
	v_lshl_add_u64 v[212:213], v[164:165], 1, v[212:213]
	s_add_i32 s68, s45, s40
	s_mov_b32 m0, s68
	s_nop 0
	global_load_lds_dwordx4 v[212:213], off
	s_add_i32 s45, s41, s45
	v_lshl_add_u64 v[212:213], v[172:173], 0, s[12:13]
	s_mov_b32 m0, s45
	s_nop 0
	global_load_lds_dwordx4 v[212:213], off
	v_lshl_add_u64 v[212:213], v[170:171], 0, s[12:13]
	s_add_i32 s68, s45, 0x400
	s_mov_b32 m0, s68
	s_nop 0
	global_load_lds_dwordx4 v[212:213], off
	v_lshl_add_u64 v[212:213], v[168:169], 0, s[12:13]
	s_add_i32 s68, s45, 0x800
	s_mov_b32 m0, s68
	s_nop 0
	global_load_lds_dwordx4 v[212:213], off
	s_addk_i32 s45, 0xc00
	v_lshl_add_u64 v[212:213], v[166:167], 0, s[12:13]
	s_mov_b32 m0, s45
	s_nop 0
	global_load_lds_dwordx4 v[212:213], off
.Lmy_rl_6:
	s_add_i32 s44, s43, 1
	s_cmp_lg_u32 s43, 2
	s_cselect_b32 s43, s44, 0
	s_add_u32 s12, s12, 64
	s_addc_u32 s13, s13, 0
	s_cmpk_eq_i32 s12, 0x780
	s_cbranch_scc0 .LBB0_643
	s_waitcnt vmcnt(6)
	v_mov_b32_e32 v162, v19
	v_mov_b32_e32 v163, v20
	v_mov_b32_e32 v19, v21
	v_mov_b32_e32 v164, v3
	v_mov_b32_e32 v165, v4
	v_pk_add_f32 v[18:19], v[162:163], v[18:19]
	v_mov_b32_e32 v3, v5
	v_pk_add_f32 v[2:3], v[164:165], v[2:3]
	v_add_f32_e32 v0, v18, v19
	v_add_f32_e32 v0, v0, v2
	v_add_f32_e32 v0, v0, v3
	v_fmamk_f32 v0, v0, 0x3a800000, v250
	s_waitcnt vmcnt(4)
	v_mov_b32_e32 v166, v23
	v_mov_b32_e32 v167, v24
	v_mul_f32_e32 v2, 0x4b800000, v0
	v_cmp_gt_f32_e32 vcc, s80, v0
	v_mov_b32_e32 v23, v25
	v_mov_b32_e32 v168, v7
	v_mov_b32_e32 v169, v8
	v_cndmask_b32_e32 v0, v0, v2, vcc
	v_pk_add_f32 v[2:3], v[166:167], v[22:23]
	v_mov_b32_e32 v7, v9
	v_pk_add_f32 v[4:5], v[168:169], v[6:7]
	v_add_f32_e32 v2, v2, v3
	v_add_f32_e32 v2, v2, v4
	v_add_f32_e32 v2, v2, v5
	v_fmamk_f32 v2, v2, 0x3a800000, v250
	v_mul_f32_e32 v3, 0x4b800000, v2
	v_cmp_gt_f32_e64 s[40:41], s80, v2
	s_waitcnt vmcnt(2)
	v_mov_b32_e32 v170, v27
	v_mov_b32_e32 v171, v28
	v_cndmask_b32_e64 v2, v2, v3, s[40:41]
	v_mov_b32_e32 v27, v29
	v_mov_b32_e32 v172, v11
	v_mov_b32_e32 v173, v12
	v_rsq_f32_e32 v179, v2
	v_pk_add_f32 v[2:3], v[170:171], v[26:27]
	v_mov_b32_e32 v11, v13
	v_pk_add_f32 v[4:5], v[172:173], v[10:11]
	v_add_f32_e32 v2, v2, v3
	v_add_f32_e32 v2, v2, v4
	v_add_f32_e32 v2, v2, v5
	v_fmamk_f32 v2, v2, 0x3a800000, v250
	v_mul_f32_e32 v3, 0x4b800000, v2
	v_cmp_gt_f32_e64 s[42:43], s80, v2
	s_waitcnt vmcnt(0)
	v_mov_b32_e32 v174, v31
	v_mov_b32_e32 v175, v32
	v_cndmask_b32_e64 v2, v2, v3, s[42:43]
	v_mov_b32_e32 v31, v33
	v_mov_b32_e32 v180, v15
	v_mov_b32_e32 v181, v16
	v_rsq_f32_e32 v182, v2
	v_pk_add_f32 v[2:3], v[174:175], v[30:31]
	v_mov_b32_e32 v15, v17
	v_pk_add_f32 v[4:5], v[180:181], v[14:15]
	v_add_f32_e32 v2, v2, v3
	v_add_f32_e32 v2, v2, v4
	v_add_f32_e32 v2, v2, v5
	v_fmamk_f32 v2, v2, 0x3a800000, v250
	v_mul_f32_e32 v3, 0x4b800000, v2
	v_cmp_gt_f32_e64 s[44:45], s80, v2
	s_waitcnt vmcnt(6)
	v_add_u32_e32 v183, v178, v176
	s_waitcnt lgkmcnt(0)
	s_barrier
	v_cndmask_b32_e64 v2, v2, v3, s[44:45]
	v_rsq_f32_e32 v180, v2
	ds_read_b128 v[2:5], v183 offset:15360
	ds_read_b128 v[6:9], v183 offset:14336
	ds_read_b128 v[10:13], v183 offset:13312
	ds_read_b128 v[14:17], v183 offset:12288
	ds_read_b128 v[18:21], v183 offset:11264
	ds_read_b128 v[22:25], v183 offset:10240
	ds_read_b128 v[26:29], v183 offset:9216
	ds_read_b128 v[30:33], v183 offset:8192
	v_add3_u32 v178, s55, v177, v176
	ds_read_b128 v[162:165], v178 offset:3072
	ds_read_b128 v[166:169], v178 offset:2048
	ds_read_b128 v[170:173], v178 offset:1024
	ds_read_b128 v[174:177], v178
	v_rsq_f32_e32 v0, v0
	v_mul_f32_e32 v184, 0x45800000, v179
	v_mul_f32_e32 v185, 0x45800000, v182
	v_mul_f32_e32 v186, 0x45800000, v180
	v_mul_f32_e32 v181, 0x45800000, v0
	s_waitcnt lgkmcnt(0)
	v_mfma_f32_16x16x32_bf16 v[34:37], v[30:33], v[174:177], v[34:37]
	v_mfma_f32_16x16x32_bf16 v[38:41], v[30:33], v[170:173], v[38:41]
	v_mfma_f32_16x16x32_bf16 v[42:45], v[30:33], v[166:169], v[42:45]
	v_mfma_f32_16x16x32_bf16 v[30:33], v[30:33], v[162:165], v[46:49]
	v_mfma_f32_16x16x32_bf16 v[46:49], v[26:29], v[174:177], v[50:53]
	v_mfma_f32_16x16x32_bf16 v[50:53], v[26:29], v[170:173], v[54:57]
	v_mfma_f32_16x16x32_bf16 v[54:57], v[26:29], v[166:169], v[58:61]
	v_mfma_f32_16x16x32_bf16 v[58:61], v[26:29], v[162:165], v[62:65]
	v_mfma_f32_16x16x32_bf16 v[62:65], v[22:25], v[174:177], v[66:69]
	v_mfma_f32_16x16x32_bf16 v[66:69], v[22:25], v[170:173], v[70:73]
	v_mfma_f32_16x16x32_bf16 v[70:73], v[22:25], v[166:169], v[74:77]
	v_mfma_f32_16x16x32_bf16 v[74:77], v[22:25], v[162:165], v[78:81]
	v_mfma_f32_16x16x32_bf16 v[78:81], v[18:21], v[174:177], v[82:85]
	v_mfma_f32_16x16x32_bf16 v[82:85], v[18:21], v[170:173], v[86:89]
	v_mfma_f32_16x16x32_bf16 v[86:89], v[18:21], v[166:169], v[90:93]
	v_mfma_f32_16x16x32_bf16 v[18:21], v[18:21], v[162:165], v[94:97]
	v_mfma_f32_16x16x32_bf16 v[90:93], v[14:17], v[174:177], v[98:101]
	v_mfma_f32_16x16x32_bf16 v[94:97], v[14:17], v[170:173], v[102:105]
	v_mfma_f32_16x16x32_bf16 v[98:101], v[14:17], v[166:169], v[106:109]
	v_mfma_f32_16x16x32_bf16 v[14:17], v[14:17], v[162:165], v[110:113]
	v_mfma_f32_16x16x32_bf16 v[102:105], v[10:13], v[174:177], v[114:117]
	v_mfma_f32_16x16x32_bf16 v[106:109], v[10:13], v[170:173], v[118:121]
	v_mfma_f32_16x16x32_bf16 v[110:113], v[10:13], v[166:169], v[122:125]
	v_mfma_f32_16x16x32_bf16 v[10:13], v[10:13], v[162:165], v[126:129]
	v_mfma_f32_16x16x32_bf16 v[114:117], v[6:9], v[174:177], v[130:133]
	v_mfma_f32_16x16x32_bf16 v[118:121], v[6:9], v[170:173], v[134:137]
	v_mfma_f32_16x16x32_bf16 v[122:125], v[6:9], v[166:169], v[138:141]
	v_mfma_f32_16x16x32_bf16 v[6:9], v[6:9], v[162:165], v[142:145]
	v_mfma_f32_16x16x32_bf16 v[126:129], v[2:5], v[174:177], v[146:149]
	v_mfma_f32_16x16x32_bf16 v[130:133], v[2:5], v[170:173], v[150:153]
	v_mfma_f32_16x16x32_bf16 v[134:137], v[2:5], v[166:169], v[154:157]
	v_mfma_f32_16x16x32_bf16 v[2:5], v[2:5], v[162:165], v[158:161]
	s_waitcnt vmcnt(0)
	v_cndmask_b32_e32 v26, v0, v181, vcc
	v_cndmask_b32_e64 v24, v179, v184, s[40:41]
	v_cndmask_b32_e64 v22, v182, v185, s[42:43]
	v_cndmask_b32_e64 v0, v180, v186, s[44:45]
	s_waitcnt lgkmcnt(0)
	s_barrier
	ds_read_b128 v[138:141], v178 offset:24576
	ds_read_b128 v[142:145], v178 offset:25600
	ds_read_b128 v[146:149], v178 offset:26624
	ds_read_b128 v[150:153], v178 offset:27648
	ds_read_b128 v[154:157], v183 offset:32768
	ds_read_b128 v[158:161], v183 offset:33792
	ds_read_b128 v[162:165], v183 offset:34816
	ds_read_b128 v[166:169], v183 offset:35840
	ds_read_b128 v[170:173], v183 offset:36864
	ds_read_b128 v[174:177], v183 offset:37888
	ds_read_b128 v[178:181], v183 offset:38912
	ds_read_b128 v[182:185], v183 offset:39936
	s_waitcnt lgkmcnt(7)
	v_mfma_f32_16x16x32_bf16 v[34:37], v[154:157], v[138:141], v[34:37]
	v_mfma_f32_16x16x32_bf16 v[38:41], v[154:157], v[142:145], v[38:41]
	v_mfma_f32_16x16x32_bf16 v[42:45], v[154:157], v[146:149], v[42:45]
	v_mfma_f32_16x16x32_bf16 v[28:31], v[154:157], v[150:153], v[30:33]
	s_waitcnt lgkmcnt(6)
	v_mfma_f32_16x16x32_bf16 v[46:49], v[158:161], v[138:141], v[46:49]
	v_mfma_f32_16x16x32_bf16 v[50:53], v[158:161], v[142:145], v[50:53]
	v_mfma_f32_16x16x32_bf16 v[54:57], v[158:161], v[146:149], v[54:57]
	v_mfma_f32_16x16x32_bf16 v[58:61], v[158:161], v[150:153], v[58:61]
	s_waitcnt lgkmcnt(5)
	v_mfma_f32_16x16x32_bf16 v[62:65], v[162:165], v[138:141], v[62:65]
	v_mfma_f32_16x16x32_bf16 v[66:69], v[162:165], v[142:145], v[66:69]
	v_mfma_f32_16x16x32_bf16 v[70:73], v[162:165], v[146:149], v[70:73]
	v_mfma_f32_16x16x32_bf16 v[74:77], v[162:165], v[150:153], v[74:77]
	s_waitcnt lgkmcnt(4)
	v_mfma_f32_16x16x32_bf16 v[78:81], v[166:169], v[138:141], v[78:81]
	v_mfma_f32_16x16x32_bf16 v[82:85], v[166:169], v[142:145], v[82:85]
	v_mfma_f32_16x16x32_bf16 v[86:89], v[166:169], v[146:149], v[86:89]
	v_mfma_f32_16x16x32_bf16 v[154:157], v[166:169], v[150:153], v[18:21]
	s_waitcnt lgkmcnt(3)
	v_mfma_f32_16x16x32_bf16 v[90:93], v[170:173], v[138:141], v[90:93]
	v_mfma_f32_16x16x32_bf16 v[94:97], v[170:173], v[142:145], v[94:97]
	v_mfma_f32_16x16x32_bf16 v[98:101], v[170:173], v[146:149], v[98:101]
	v_mfma_f32_16x16x32_bf16 v[158:161], v[170:173], v[150:153], v[14:17]
	s_waitcnt lgkmcnt(2)
	v_mfma_f32_16x16x32_bf16 v[102:105], v[174:177], v[138:141], v[102:105]
	v_mfma_f32_16x16x32_bf16 v[106:109], v[174:177], v[142:145], v[106:109]
	v_mfma_f32_16x16x32_bf16 v[110:113], v[174:177], v[146:149], v[110:113]
	v_mfma_f32_16x16x32_bf16 v[162:165], v[174:177], v[150:153], v[10:13]
	s_waitcnt lgkmcnt(1)
	v_mfma_f32_16x16x32_bf16 v[114:117], v[178:181], v[138:141], v[114:117]
	v_mfma_f32_16x16x32_bf16 v[118:121], v[178:181], v[142:145], v[118:121]
	v_mfma_f32_16x16x32_bf16 v[122:125], v[178:181], v[146:149], v[122:125]
	v_mfma_f32_16x16x32_bf16 v[18:21], v[178:181], v[150:153], v[6:9]
	s_waitcnt lgkmcnt(0)
	v_mfma_f32_16x16x32_bf16 v[14:17], v[182:185], v[138:141], v[126:129]
	v_mfma_f32_16x16x32_bf16 v[10:13], v[182:185], v[142:145], v[130:133]
	v_mfma_f32_16x16x32_bf16 v[6:9], v[182:185], v[146:149], v[134:137]
	v_mfma_f32_16x16x32_bf16 v[2:5], v[182:185], v[150:153], v[2:5]
	v_mov_b32_e32 v23, v224
	s_movk_i32 s12, 0x210
	v_lshrrev_b32_e32 v32, 1, v23
	v_and_b32_e32 v27, 0x7fffff80, v23
	v_and_b32_e32 v32, 24, v32
	v_and_b32_e32 v25, 0x4f, v23
	v_lshl_or_b32 v27, v27, 1, v32
	v_pk_mul_f32 v[32:33], v[26:27], v[34:35] op_sel_hi:[0,1]
	v_pk_mul_f32 v[34:35], v[26:27], v[36:37] op_sel_hi:[0,1]
	v_mad_u32_u24 v25, v25, s12, v27
	v_cvt_pk_bf16_f32 v32, v32, v33
	v_cvt_pk_bf16_f32 v33, v34, v35
	v_pk_mul_f32 v[34:35], v[24:25], v[38:39] op_sel_hi:[0,1]
	v_pk_mul_f32 v[36:37], v[24:25], v[40:41] op_sel_hi:[0,1]
	v_cvt_pk_bf16_f32 v34, v34, v35
	v_cvt_pk_bf16_f32 v35, v36, v37
	v_pk_mul_f32 v[36:37], v[22:23], v[42:43] op_sel_hi:[0,1]
	v_pk_mul_f32 v[38:39], v[22:23], v[44:45] op_sel_hi:[0,1]
	v_pk_mul_f32 v[28:29], v[0:1], v[28:29] op_sel_hi:[0,1]
	v_pk_mul_f32 v[30:31], v[0:1], v[30:31] op_sel_hi:[0,1]
	v_cvt_pk_bf16_f32 v36, v36, v37
	v_cvt_pk_bf16_f32 v37, v38, v39
	v_cvt_pk_bf16_f32 v28, v28, v29
	v_cvt_pk_bf16_f32 v29, v30, v31
	v_pk_mul_f32 v[30:31], v[26:27], v[46:47] op_sel_hi:[0,1]
	v_pk_mul_f32 v[38:39], v[26:27], v[48:49] op_sel_hi:[0,1]
	v_cvt_pk_bf16_f32 v30, v30, v31
	v_cvt_pk_bf16_f32 v31, v38, v39
	s_barrier
	ds_write2_b64 v25, v[32:33], v[30:31] offset1:4
	v_pk_mul_f32 v[30:31], v[24:25], v[50:51] op_sel_hi:[0,1]
	v_pk_mul_f32 v[32:33], v[24:25], v[52:53] op_sel_hi:[0,1]
	v_cvt_pk_bf16_f32 v30, v30, v31
	v_cvt_pk_bf16_f32 v31, v32, v33
	v_add_u32_e32 v27, 0x2000, v25
	ds_write2_b64 v27, v[34:35], v[30:31] offset0:32 offset1:36
	v_pk_mul_f32 v[30:31], v[22:23], v[54:55] op_sel_hi:[0,1]
	v_pk_mul_f32 v[32:33], v[22:23], v[56:57] op_sel_hi:[0,1]
	v_cvt_pk_bf16_f32 v30, v30, v31
	v_cvt_pk_bf16_f32 v31, v32, v33
	v_add_u32_e32 v40, 0x4000, v25
	ds_write2_b64 v40, v[36:37], v[30:31] offset0:64 offset1:68
	v_pk_mul_f32 v[30:31], v[0:1], v[58:59] op_sel_hi:[0,1]
	v_pk_mul_f32 v[32:33], v[0:1], v[60:61] op_sel_hi:[0,1]
	v_cvt_pk_bf16_f32 v30, v30, v31
	v_cvt_pk_bf16_f32 v31, v32, v33
	v_add_u32_e32 v41, 0x6000, v25
	ds_write2_b64 v41, v[28:29], v[30:31] offset0:96 offset1:100
	v_pk_mul_f32 v[28:29], v[26:27], v[62:63] op_sel_hi:[0,1]
	v_pk_mul_f32 v[30:31], v[26:27], v[64:65] op_sel_hi:[0,1]
	v_cvt_pk_bf16_f32 v28, v28, v29
	v_cvt_pk_bf16_f32 v29, v30, v31
	v_pk_mul_f32 v[30:31], v[24:25], v[66:67] op_sel_hi:[0,1]
	v_pk_mul_f32 v[32:33], v[24:25], v[68:69] op_sel_hi:[0,1]
	v_cvt_pk_bf16_f32 v30, v30, v31
	v_cvt_pk_bf16_f32 v31, v32, v33
	v_pk_mul_f32 v[32:33], v[22:23], v[70:71] op_sel_hi:[0,1]
	v_pk_mul_f32 v[34:35], v[22:23], v[72:73] op_sel_hi:[0,1]
	v_cvt_pk_bf16_f32 v32, v32, v33
	v_cvt_pk_bf16_f32 v33, v34, v35
	v_pk_mul_f32 v[34:35], v[0:1], v[74:75] op_sel_hi:[0,1]
	v_pk_mul_f32 v[36:37], v[0:1], v[76:77] op_sel_hi:[0,1]
	v_cvt_pk_bf16_f32 v34, v34, v35
	v_cvt_pk_bf16_f32 v35, v36, v37
	v_pk_mul_f32 v[36:37], v[26:27], v[78:79] op_sel_hi:[0,1]
	v_pk_mul_f32 v[38:39], v[26:27], v[80:81] op_sel_hi:[0,1]
	v_cvt_pk_bf16_f32 v36, v36, v37
	v_cvt_pk_bf16_f32 v37, v38, v39
	ds_write2_b64 v25, v[28:29], v[36:37] offset0:8 offset1:12
	v_pk_mul_f32 v[28:29], v[24:25], v[82:83] op_sel_hi:[0,1]
	v_pk_mul_f32 v[36:37], v[24:25], v[84:85] op_sel_hi:[0,1]
	v_cvt_pk_bf16_f32 v28, v28, v29
	v_cvt_pk_bf16_f32 v29, v36, v37
	ds_write2_b64 v27, v[30:31], v[28:29] offset0:40 offset1:44
	v_pk_mul_f32 v[28:29], v[22:23], v[86:87] op_sel_hi:[0,1]
	v_pk_mul_f32 v[30:31], v[22:23], v[88:89] op_sel_hi:[0,1]
	v_cvt_pk_bf16_f32 v28, v28, v29
	v_cvt_pk_bf16_f32 v29, v30, v31
	ds_write2_b64 v40, v[32:33], v[28:29] offset0:72 offset1:76
	v_pk_mul_f32 v[28:29], v[0:1], v[154:155] op_sel_hi:[0,1]
	v_pk_mul_f32 v[30:31], v[0:1], v[156:157] op_sel_hi:[0,1]
	v_cvt_pk_bf16_f32 v28, v28, v29
	v_cvt_pk_bf16_f32 v29, v30, v31
	ds_write2_b64 v41, v[34:35], v[28:29] offset0:104 offset1:108
	v_pk_mul_f32 v[28:29], v[26:27], v[90:91] op_sel_hi:[0,1]
	v_pk_mul_f32 v[30:31], v[26:27], v[92:93] op_sel_hi:[0,1]
	v_cvt_pk_bf16_f32 v28, v28, v29
	v_cvt_pk_bf16_f32 v29, v30, v31
	v_pk_mul_f32 v[30:31], v[24:25], v[94:95] op_sel_hi:[0,1]
	v_pk_mul_f32 v[32:33], v[24:25], v[96:97] op_sel_hi:[0,1]
	v_cvt_pk_bf16_f32 v30, v30, v31
	v_cvt_pk_bf16_f32 v31, v32, v33
	v_pk_mul_f32 v[32:33], v[22:23], v[98:99] op_sel_hi:[0,1]
	v_pk_mul_f32 v[34:35], v[22:23], v[100:101] op_sel_hi:[0,1]
	v_cvt_pk_bf16_f32 v32, v32, v33
	v_cvt_pk_bf16_f32 v33, v34, v35
	v_pk_mul_f32 v[34:35], v[0:1], v[158:159] op_sel_hi:[0,1]
	v_pk_mul_f32 v[36:37], v[0:1], v[160:161] op_sel_hi:[0,1]
	v_cvt_pk_bf16_f32 v34, v34, v35
	v_cvt_pk_bf16_f32 v35, v36, v37
	v_pk_mul_f32 v[36:37], v[26:27], v[102:103] op_sel_hi:[0,1]
	v_pk_mul_f32 v[38:39], v[26:27], v[104:105] op_sel_hi:[0,1]
	v_cvt_pk_bf16_f32 v36, v36, v37
	v_cvt_pk_bf16_f32 v37, v38, v39
	ds_write2_b64 v25, v[28:29], v[36:37] offset0:16 offset1:20
	v_pk_mul_f32 v[28:29], v[24:25], v[106:107] op_sel_hi:[0,1]
	v_pk_mul_f32 v[36:37], v[24:25], v[108:109] op_sel_hi:[0,1]
	v_cvt_pk_bf16_f32 v28, v28, v29
	v_cvt_pk_bf16_f32 v29, v36, v37
	ds_write2_b64 v27, v[30:31], v[28:29] offset0:48 offset1:52
	v_pk_mul_f32 v[28:29], v[22:23], v[110:111] op_sel_hi:[0,1]
	v_pk_mul_f32 v[30:31], v[22:23], v[112:113] op_sel_hi:[0,1]
	v_cvt_pk_bf16_f32 v28, v28, v29
	v_cvt_pk_bf16_f32 v29, v30, v31
	ds_write2_b64 v40, v[32:33], v[28:29] offset0:80 offset1:84
	v_pk_mul_f32 v[28:29], v[0:1], v[162:163] op_sel_hi:[0,1]
	v_pk_mul_f32 v[30:31], v[0:1], v[164:165] op_sel_hi:[0,1]
	v_cvt_pk_bf16_f32 v28, v28, v29
	v_cvt_pk_bf16_f32 v29, v30, v31
	ds_write2_b64 v41, v[34:35], v[28:29] offset0:112 offset1:116
	v_pk_mul_f32 v[28:29], v[26:27], v[114:115] op_sel_hi:[0,1]
	v_pk_mul_f32 v[30:31], v[26:27], v[116:117] op_sel_hi:[0,1]
	v_pk_mul_f32 v[18:19], v[0:1], v[18:19] op_sel_hi:[0,1]
	v_pk_mul_f32 v[20:21], v[0:1], v[20:21] op_sel_hi:[0,1]
	v_pk_mul_f32 v[2:3], v[0:1], v[2:3] op_sel_hi:[0,1]
	v_pk_mul_f32 v[4:5], v[0:1], v[4:5] op_sel_hi:[0,1]
	v_lshlrev_b32_e32 v0, 3, v23
	v_cvt_pk_bf16_f32 v28, v28, v29
	v_cvt_pk_bf16_f32 v29, v30, v31
	v_pk_mul_f32 v[30:31], v[24:25], v[118:119] op_sel_hi:[0,1]
	v_pk_mul_f32 v[32:33], v[24:25], v[120:121] op_sel_hi:[0,1]
	v_cvt_pk_bf16_f32 v18, v18, v19
	v_cvt_pk_bf16_f32 v19, v20, v21
	v_cvt_pk_bf16_f32 v2, v2, v3
	v_cvt_pk_bf16_f32 v3, v4, v5
	v_and_b32_e32 v0, 0xf8, v0
	v_cvt_pk_bf16_f32 v30, v30, v31
	v_cvt_pk_bf16_f32 v31, v32, v33
	v_pk_mul_f32 v[32:33], v[22:23], v[122:123] op_sel_hi:[0,1]
	v_pk_mul_f32 v[34:35], v[22:23], v[124:125] op_sel_hi:[0,1]
	v_pk_mul_f32 v[14:15], v[26:27], v[14:15] op_sel_hi:[0,1]
	v_pk_mul_f32 v[16:17], v[26:27], v[16:17] op_sel_hi:[0,1]
	v_pk_mul_f32 v[10:11], v[24:25], v[10:11] op_sel_hi:[0,1]
	v_pk_mul_f32 v[12:13], v[24:25], v[12:13] op_sel_hi:[0,1]
	v_pk_mul_f32 v[6:7], v[22:23], v[6:7] op_sel_hi:[0,1]
	v_pk_mul_f32 v[8:9], v[22:23], v[8:9] op_sel_hi:[0,1]
	ds_write2_b64 v41, v[18:19], v[2:3] offset0:120 offset1:124
	v_or_b32_e32 v2, s54, v0
	s_movk_i32 s12, 0xa30
	v_cvt_pk_bf16_f32 v32, v32, v33
	v_cvt_pk_bf16_f32 v33, v34, v35
	v_cvt_pk_bf16_f32 v14, v14, v15
	v_cvt_pk_bf16_f32 v15, v16, v17
	v_cvt_pk_bf16_f32 v10, v10, v11
	v_cvt_pk_bf16_f32 v11, v12, v13
	v_cvt_pk_bf16_f32 v6, v6, v7
	v_cvt_pk_bf16_f32 v7, v8, v9
	v_cmp_gt_i32_e32 vcc, s12, v2
	ds_write2_b64 v25, v[28:29], v[14:15] offset0:24 offset1:28
	ds_write2_b64 v27, v[30:31], v[10:11] offset0:56 offset1:60
	ds_write2_b64 v40, v[32:33], v[6:7] offset0:88 offset1:92
	s_waitcnt lgkmcnt(0)
	s_barrier
	s_and_saveexec_b64 s[12:13], vcc
	s_cbranch_execz .LBB0_641
	v_ashrrev_i32_e32 v8, 5, v23
	v_lshlrev_b32_e32 v0, 1, v0
	s_movk_i32 s40, 0x210
	v_mad_u64_u32 v[6:7], s[40:41], v8, s40, v[0:1]
	ds_read_b128 v[2:5], v6
	v_add_u32_e32 v7, s57, v8
	v_mov_b64_e32 v[8:9], s[4:5]
	s_ashr_i32 s55, s54, 31
	v_mad_i64_i32 v[10:11], s[40:41], v7, s16, v[8:9]
	s_lshl_b64 s[40:41], s[54:55], 1
	s_nop 0
	v_lshl_add_u64 v[10:11], v[10:11], 0, s[40:41]
	v_lshl_add_u64 v[10:11], v[10:11], 0, v[0:1]
	s_waitcnt lgkmcnt(0)
	global_store_dwordx4 v[10:11], v[2:5], off
	ds_read_b128 v[2:5], v6 offset:4224
	v_add_u32_e32 v10, 8, v7
	v_mad_i64_i32 v[10:11], s[42:43], v10, s16, v[8:9]
	v_lshl_add_u64 v[10:11], v[10:11], 0, s[40:41]
	v_lshl_add_u64 v[10:11], v[10:11], 0, v[0:1]
	s_waitcnt lgkmcnt(0)
	global_store_dwordx4 v[10:11], v[2:5], off
	ds_read_b128 v[2:5], v6 offset:8448
	v_add_u32_e32 v10, 16, v7
	v_mad_i64_i32 v[10:11], s[42:43], v10, s16, v[8:9]
	v_lshl_add_u64 v[10:11], v[10:11], 0, s[40:41]
	v_lshl_add_u64 v[10:11], v[10:11], 0, v[0:1]
	s_waitcnt lgkmcnt(0)
	global_store_dwordx4 v[10:11], v[2:5], off
	ds_read_b128 v[2:5], v6 offset:12672
	v_add_u32_e32 v10, 24, v7
	v_mad_i64_i32 v[10:11], s[42:43], v10, s16, v[8:9]
	v_lshl_add_u64 v[10:11], v[10:11], 0, s[40:41]
	v_lshl_add_u64 v[10:11], v[10:11], 0, v[0:1]
	s_waitcnt lgkmcnt(0)
	global_store_dwordx4 v[10:11], v[2:5], off
	ds_read_b128 v[2:5], v6 offset:16896
	v_add_u32_e32 v10, 32, v7
	v_mad_i64_i32 v[10:11], s[42:43], v10, s16, v[8:9]
	v_lshl_add_u64 v[10:11], v[10:11], 0, s[40:41]
	v_lshl_add_u64 v[10:11], v[10:11], 0, v[0:1]
	s_waitcnt lgkmcnt(0)
	global_store_dwordx4 v[10:11], v[2:5], off
	ds_read_b128 v[2:5], v6 offset:21120
	v_add_u32_e32 v10, 40, v7
	v_mad_i64_i32 v[10:11], s[42:43], v10, s16, v[8:9]
	v_lshl_add_u64 v[10:11], v[10:11], 0, s[40:41]
	v_lshl_add_u64 v[10:11], v[10:11], 0, v[0:1]
	s_waitcnt lgkmcnt(0)
	global_store_dwordx4 v[10:11], v[2:5], off
	ds_read_b128 v[2:5], v6 offset:25344
	v_add_u32_e32 v10, 48, v7
	v_mad_i64_i32 v[10:11], s[42:43], v10, s16, v[8:9]
	v_lshl_add_u64 v[10:11], v[10:11], 0, s[40:41]
	v_lshl_add_u64 v[10:11], v[10:11], 0, v[0:1]
	s_waitcnt lgkmcnt(0)
	global_store_dwordx4 v[10:11], v[2:5], off
	ds_read_b128 v[2:5], v6 offset:29568
	v_add_u32_e32 v10, 56, v7
	v_mad_i64_i32 v[10:11], s[42:43], v10, s16, v[8:9]
	v_lshl_add_u64 v[10:11], v[10:11], 0, s[40:41]
	v_lshl_add_u64 v[10:11], v[10:11], 0, v[0:1]
	s_waitcnt lgkmcnt(0)
	global_store_dwordx4 v[10:11], v[2:5], off
	ds_read_b128 v[2:5], v6 offset:33792
	v_add_u32_e32 v10, 64, v7
	v_mad_i64_i32 v[10:11], s[42:43], v10, s16, v[8:9]
	v_lshl_add_u64 v[10:11], v[10:11], 0, s[40:41]
	v_lshl_add_u64 v[10:11], v[10:11], 0, v[0:1]
	s_waitcnt lgkmcnt(0)
	global_store_dwordx4 v[10:11], v[2:5], off
	ds_read_b128 v[2:5], v6 offset:38016
	v_add_u32_e32 v10, 0x48, v7
	v_mad_i64_i32 v[10:11], s[42:43], v10, s16, v[8:9]
	v_lshl_add_u64 v[10:11], v[10:11], 0, s[40:41]
	v_lshl_add_u64 v[10:11], v[10:11], 0, v[0:1]
	s_waitcnt lgkmcnt(0)
	global_store_dwordx4 v[10:11], v[2:5], off
	ds_read_b128 v[2:5], v6 offset:42240
	v_add_u32_e32 v10, 0x50, v7
	v_mad_i64_i32 v[10:11], s[42:43], v10, s16, v[8:9]
	v_lshl_add_u64 v[10:11], v[10:11], 0, s[40:41]
	v_lshl_add_u64 v[10:11], v[10:11], 0, v[0:1]
	s_waitcnt lgkmcnt(0)
	global_store_dwordx4 v[10:11], v[2:5], off
	ds_read_b128 v[2:5], v6 offset:46464
	v_add_u32_e32 v10, 0x58, v7
	v_mad_i64_i32 v[10:11], s[42:43], v10, s16, v[8:9]
	v_lshl_add_u64 v[10:11], v[10:11], 0, s[40:41]
	v_lshl_add_u64 v[10:11], v[10:11], 0, v[0:1]
	s_waitcnt lgkmcnt(0)
	global_store_dwordx4 v[10:11], v[2:5], off
	ds_read_b128 v[2:5], v6 offset:50688
	v_add_u32_e32 v10, 0x60, v7
	v_mad_i64_i32 v[10:11], s[42:43], v10, s16, v[8:9]
	v_lshl_add_u64 v[10:11], v[10:11], 0, s[40:41]
	v_lshl_add_u64 v[10:11], v[10:11], 0, v[0:1]
	s_waitcnt lgkmcnt(0)
	global_store_dwordx4 v[10:11], v[2:5], off
	ds_read_b128 v[2:5], v6 offset:54912
	v_add_u32_e32 v10, 0x68, v7
	v_mad_i64_i32 v[10:11], s[42:43], v10, s16, v[8:9]
	v_lshl_add_u64 v[10:11], v[10:11], 0, s[40:41]
	v_lshl_add_u64 v[10:11], v[10:11], 0, v[0:1]
	s_waitcnt lgkmcnt(0)
	global_store_dwordx4 v[10:11], v[2:5], off
	ds_read_b128 v[2:5], v6 offset:59136
	v_add_u32_e32 v10, 0x70, v7
	v_mad_i64_i32 v[10:11], s[42:43], v10, s16, v[8:9]
	v_lshl_add_u64 v[10:11], v[10:11], 0, s[40:41]
	v_lshl_add_u64 v[10:11], v[10:11], 0, v[0:1]
	s_waitcnt lgkmcnt(0)
	global_store_dwordx4 v[10:11], v[2:5], off
	ds_read_b128 v[2:5], v6 offset:63360
	v_add_u32_e32 v6, 0x78, v7
	v_mad_i64_i32 v[6:7], s[42:43], v6, s16, v[8:9]
	v_lshl_add_u64 v[6:7], v[6:7], 0, s[40:41]
	v_lshl_add_u64 v[6:7], v[6:7], 0, v[0:1]
	s_waitcnt lgkmcnt(0)
	global_store_dwordx4 v[6:7], v[2:5], off
	s_branch .LBB0_641

	.amdhsa_kernel _Z4mega6Paramsii
		.amdhsa_group_segment_fixed_size 73744
		.amdhsa_private_segment_fixed_size 0
		.amdhsa_kernarg_size 440
		.amdhsa_user_sgpr_count 2
		.amdhsa_user_sgpr_dispatch_ptr 0
		.amdhsa_user_sgpr_queue_ptr 0
		.amdhsa_user_sgpr_kernarg_segment_ptr 1
		.amdhsa_user_sgpr_dispatch_id 0
		.amdhsa_user_sgpr_kernarg_preload_length 0
		.amdhsa_user_sgpr_kernarg_preload_offset 0
		.amdhsa_user_sgpr_private_segment_size 0
		.amdhsa_uses_dynamic_stack 0
		.amdhsa_enable_private_segment 0
		.amdhsa_system_sgpr_workgroup_id_x 1
		.amdhsa_system_sgpr_workgroup_id_y 0
		.amdhsa_system_sgpr_workgroup_id_z 0
		.amdhsa_system_sgpr_workgroup_info 0
		.amdhsa_system_vgpr_workitem_id 2
		.amdhsa_next_free_vgpr 256
		.amdhsa_next_free_sgpr 102
		.amdhsa_accum_offset 256
		.amdhsa_reserve_vcc 1
		.amdhsa_float_round_mode_32 0
		.amdhsa_float_round_mode_16_64 0
		.amdhsa_float_denorm_mode_32 3
		.amdhsa_float_denorm_mode_16_64 3
		.amdhsa_dx10_clamp 1
		.amdhsa_ieee_mode 1
		.amdhsa_fp16_overflow 0
		.amdhsa_tg_split 0
		.amdhsa_exception_fp_ieee_invalid_op 0
		.amdhsa_exception_fp_denorm_src 0
		.amdhsa_exception_fp_ieee_div_zero 0
		.amdhsa_exception_fp_ieee_overflow 0
		.amdhsa_exception_fp_ieee_underflow 0
		.amdhsa_exception_fp_ieee_inexact 0
		.amdhsa_exception_int_div_zero 0
	.end_amdhsa_kernel

amdhsa.kernels:
  - .agpr_count:     0
    .args:
      - .offset:         0
        .size:           176
        .value_kind:     by_value
      - .offset:         176
        .size:           4
        .value_kind:     by_value
      - .offset:         180
        .size:           4
        .value_kind:     by_value
      - .offset:         184
        .size:           4
        .value_kind:     hidden_block_count_x
      - .offset:         188
        .size:           4
        .value_kind:     hidden_block_count_y
      - .offset:         192
        .size:           4
        .value_kind:     hidden_block_count_z
      - .offset:         196
        .size:           2
        .value_kind:     hidden_group_size_x
      - .offset:         198
        .size:           2
        .value_kind:     hidden_group_size_y
      - .offset:         200
        .size:           2
        .value_kind:     hidden_group_size_z
      - .offset:         202
        .size:           2
        .value_kind:     hidden_remainder_x
      - .offset:         204
        .size:           2
        .value_kind:     hidden_remainder_y
      - .offset:         206
        .size:           2
        .value_kind:     hidden_remainder_z
      - .offset:         224
        .size:           8
        .value_kind:     hidden_global_offset_x
      - .offset:         232
        .size:           8
        .value_kind:     hidden_global_offset_y
      - .offset:         240
        .size:           8
        .value_kind:     hidden_global_offset_z
      - .offset:         248
        .size:           2
        .value_kind:     hidden_grid_dims
      - .offset:         272
        .size:           8
        .value_kind:     hidden_multigrid_sync_arg
    .group_segment_fixed_size: 73744
    .kernarg_segment_align: 8
    .kernarg_segment_size: 440
    .language:       OpenCL C
    .language_version:
      - 2
      - 0
    .max_flat_workgroup_size: 256
    .name:           _Z4mega6Paramsii
    .private_segment_fixed_size: 0
    .sgpr_count:     108
    .sgpr_spill_count: 137
    .symbol:         _Z4mega6Paramsii.kd
    .uniform_work_group_size: 1
    .uses_dynamic_stack: false
    .vgpr_count:     256
    .vgpr_spill_count: 0
    .wavefront_size: 64
